# v16 + Hyena: hy_filter<1> tap staging with 32 loads in flight and hyconv16 edge loads de-serialised (patches p03 + p02 from the first round)
# speedup vs baseline: 1.0139x; 1.0069x over previous
.LBB0_418:
	s_or_b64 exec, exec, s[0:1]
	v_mov_b32_e32 v39, v32
	s_waitcnt lgkmcnt(0)
	s_barrier
	s_add_i32 s26, 0, 0x11000
	v_and_b32_e32 v86, 31, v39
	v_cvt_f32_ubyte0_e32 v24, v86
	v_mul_f32_e32 v80, 0x3b000000, v24
	v_sin_f32_e32 v24, v80
	v_ashrrev_i32_e32 v0, 4, v39
	v_lshlrev_b32_e32 v0, 3, v0
	v_lshlrev_b32_e32 v1, 3, v39
	v_cos_f32_e32 v80, v80
	v_add3_u32 v25, s26, v0, v1
	ds_read_b64 v[0:1], v25
	ds_read_b64 v[2:3], v25 offset:4352
	ds_read_b64 v[4:5], v25 offset:8704
	ds_read_b64 v[6:7], v25 offset:13056
	ds_read_b64 v[8:9], v25 offset:17408
	ds_read_b64 v[10:11], v25 offset:21760
	ds_read_b64 v[12:13], v25 offset:26112
	ds_read_b64 v[14:15], v25 offset:30464
	ds_read_b64 v[16:17], v25 offset:34816
	ds_read_b64 v[18:19], v25 offset:39168
	ds_read_b64 v[20:21], v25 offset:43520
	ds_read_b64 v[22:23], v25 offset:47872
	v_xor_b32_e32 v81, 0x80000000, v24
	s_waitcnt lgkmcnt(10)
	v_pk_mul_f32 v[82:83], v[2:3], v[24:25] op_sel:[1,0] op_sel_hi:[0,0] neg_hi:[0,1]
	v_pk_fma_f32 v[2:3], v[2:3], v[80:81], v[82:83] op_sel_hi:[1,0,1]
	v_pk_mul_f32 v[82:83], v[24:25], v[80:81] op_sel:[0,1] op_sel_hi:[0,0] neg_hi:[1,0]
	v_pk_fma_f32 v[82:83], v[80:81], v[80:81], v[82:83] op_sel_hi:[0,1,1]
	ds_read_b64 v[26:27], v25 offset:52224
	ds_read_b64 v[28:29], v25 offset:56576
	ds_read_b64 v[30:31], v25 offset:60928
	ds_read_b64 v[78:79], v25 offset:65280
	s_waitcnt lgkmcnt(13)
	v_pk_mul_f32 v[84:85], v[4:5], v[82:83] op_sel:[1,1] op_sel_hi:[0,1] neg_lo:[0,1]
	v_pk_fma_f32 v[4:5], v[4:5], v[82:83], v[84:85] op_sel_hi:[1,0,1]
	v_pk_mul_f32 v[84:85], v[24:25], v[82:83] op_sel:[0,1] op_sel_hi:[0,0] neg_hi:[1,0]
	v_pk_fma_f32 v[82:83], v[80:81], v[82:83], v[84:85] op_sel_hi:[0,1,1]
	s_mov_b32 s11, s14
	s_waitcnt lgkmcnt(12)
	v_pk_mul_f32 v[84:85], v[6:7], v[82:83] op_sel:[1,1] op_sel_hi:[0,1] neg_lo:[0,1]
	v_pk_fma_f32 v[6:7], v[6:7], v[82:83], v[84:85] op_sel_hi:[1,0,1]
	v_pk_mul_f32 v[84:85], v[24:25], v[82:83] op_sel:[0,1] op_sel_hi:[0,0] neg_hi:[1,0]
	v_pk_fma_f32 v[82:83], v[80:81], v[82:83], v[84:85] op_sel_hi:[0,1,1]
	s_mov_b32 s35, s30
	s_waitcnt lgkmcnt(11)
	v_pk_mul_f32 v[84:85], v[8:9], v[82:83] op_sel:[1,1] op_sel_hi:[0,1] neg_lo:[0,1]
	v_pk_fma_f32 v[8:9], v[8:9], v[82:83], v[84:85] op_sel_hi:[1,0,1]
	v_pk_mul_f32 v[84:85], v[24:25], v[82:83] op_sel:[0,1] op_sel_hi:[0,0] neg_hi:[1,0]
	v_pk_fma_f32 v[82:83], v[80:81], v[82:83], v[84:85] op_sel_hi:[0,1,1]
	s_mov_b32 s0, s19
	s_waitcnt lgkmcnt(10)
	v_pk_mul_f32 v[84:85], v[10:11], v[82:83] op_sel:[1,1] op_sel_hi:[0,1] neg_lo:[0,1]
	v_pk_fma_f32 v[10:11], v[10:11], v[82:83], v[84:85] op_sel_hi:[1,0,1]
	v_pk_mul_f32 v[84:85], v[24:25], v[82:83] op_sel:[0,1] op_sel_hi:[0,0] neg_hi:[1,0]
	v_pk_fma_f32 v[82:83], v[80:81], v[82:83], v[84:85] op_sel_hi:[0,1,1]
	s_waitcnt lgkmcnt(0)
	v_pk_mul_f32 v[84:85], v[12:13], v[82:83] op_sel:[1,1] op_sel_hi:[0,1] neg_lo:[0,1]
	v_pk_fma_f32 v[12:13], v[12:13], v[82:83], v[84:85] op_sel_hi:[1,0,1]
	v_pk_mul_f32 v[84:85], v[24:25], v[82:83] op_sel:[0,1] op_sel_hi:[0,0] neg_hi:[1,0]
	v_pk_fma_f32 v[82:83], v[80:81], v[82:83], v[84:85] op_sel_hi:[0,1,1]
	s_barrier
	v_pk_mul_f32 v[84:85], v[14:15], v[82:83] op_sel:[1,1] op_sel_hi:[0,1] neg_lo:[0,1]
	v_pk_fma_f32 v[14:15], v[14:15], v[82:83], v[84:85] op_sel_hi:[1,0,1]
	v_pk_mul_f32 v[84:85], v[24:25], v[82:83] op_sel:[0,1] op_sel_hi:[0,0] neg_hi:[1,0]
	v_pk_fma_f32 v[82:83], v[80:81], v[82:83], v[84:85] op_sel_hi:[0,1,1]
	s_nop 0
	v_pk_mul_f32 v[84:85], v[16:17], v[82:83] op_sel:[1,1] op_sel_hi:[0,1] neg_lo:[0,1]
	v_pk_fma_f32 v[16:17], v[16:17], v[82:83], v[84:85] op_sel_hi:[1,0,1]
	v_pk_mul_f32 v[84:85], v[24:25], v[82:83] op_sel:[0,1] op_sel_hi:[0,0] neg_hi:[1,0]
	v_pk_fma_f32 v[82:83], v[80:81], v[82:83], v[84:85] op_sel_hi:[0,1,1]
	s_nop 0
	v_pk_mul_f32 v[84:85], v[18:19], v[82:83] op_sel:[1,1] op_sel_hi:[0,1] neg_lo:[0,1]
	v_pk_fma_f32 v[18:19], v[18:19], v[82:83], v[84:85] op_sel_hi:[1,0,1]
	v_pk_mul_f32 v[84:85], v[24:25], v[82:83] op_sel:[0,1] op_sel_hi:[0,0] neg_hi:[1,0]
	v_pk_fma_f32 v[82:83], v[80:81], v[82:83], v[84:85] op_sel_hi:[0,1,1]
	s_nop 0
	v_pk_mul_f32 v[84:85], v[20:21], v[82:83] op_sel:[1,1] op_sel_hi:[0,1] neg_lo:[0,1]
	v_pk_fma_f32 v[20:21], v[20:21], v[82:83], v[84:85] op_sel_hi:[1,0,1]
	v_pk_mul_f32 v[84:85], v[24:25], v[82:83] op_sel:[0,1] op_sel_hi:[0,0] neg_hi:[1,0]
	v_pk_fma_f32 v[82:83], v[80:81], v[82:83], v[84:85] op_sel_hi:[0,1,1]
	s_nop 0
	v_pk_mul_f32 v[84:85], v[22:23], v[82:83] op_sel:[1,1] op_sel_hi:[0,1] neg_lo:[0,1]
	v_pk_fma_f32 v[22:23], v[22:23], v[82:83], v[84:85] op_sel_hi:[1,0,1]
	v_pk_mul_f32 v[84:85], v[24:25], v[82:83] op_sel:[0,1] op_sel_hi:[0,0] neg_hi:[1,0]
	v_pk_fma_f32 v[82:83], v[80:81], v[82:83], v[84:85] op_sel_hi:[0,1,1]
	s_nop 0
	v_pk_mul_f32 v[84:85], v[26:27], v[82:83] op_sel:[1,1] op_sel_hi:[0,1] neg_lo:[0,1]
	v_pk_fma_f32 v[26:27], v[26:27], v[82:83], v[84:85] op_sel_hi:[1,0,1]
	v_pk_mul_f32 v[84:85], v[24:25], v[82:83] op_sel:[0,1] op_sel_hi:[0,0] neg_hi:[1,0]
	v_pk_fma_f32 v[82:83], v[80:81], v[82:83], v[84:85] op_sel_hi:[0,1,1]
	s_nop 0
	v_pk_mul_f32 v[84:85], v[28:29], v[82:83] op_sel:[1,1] op_sel_hi:[0,1] neg_lo:[0,1]
	v_pk_fma_f32 v[28:29], v[28:29], v[82:83], v[84:85] op_sel_hi:[1,0,1]
	v_pk_mul_f32 v[84:85], v[24:25], v[82:83] op_sel:[0,1] op_sel_hi:[0,0] neg_hi:[1,0]
	v_pk_fma_f32 v[82:83], v[80:81], v[82:83], v[84:85] op_sel_hi:[0,1,1]
	v_pk_mul_f32 v[24:25], v[24:25], v[82:83] op_sel:[0,1] op_sel_hi:[0,0] neg_hi:[1,0]
	v_pk_fma_f32 v[24:25], v[80:81], v[82:83], v[24:25] op_sel_hi:[0,1,1]
	v_pk_mul_f32 v[80:81], v[78:79], v[24:25] op_sel:[1,1] op_sel_hi:[0,1] neg_lo:[0,1]
	v_pk_fma_f32 v[24:25], v[78:79], v[24:25], v[80:81] op_sel_hi:[1,0,1]
	v_pk_add_f32 v[78:79], v[0:1], v[16:17]
	v_pk_add_f32 v[0:1], v[0:1], v[16:17] neg_lo:[0,1] neg_hi:[0,1]
	v_pk_add_f32 v[16:17], v[2:3], v[18:19]
	v_pk_add_f32 v[2:3], v[2:3], v[18:19] neg_lo:[0,1] neg_hi:[0,1]
	v_pk_mul_f32 v[84:85], v[30:31], v[82:83] op_sel:[1,1] op_sel_hi:[0,1] neg_lo:[0,1]
	v_pk_mul_f32 v[18:19], v[2:3], s[18:19]
	v_pk_fma_f32 v[30:31], v[30:31], v[82:83], v[84:85] op_sel_hi:[1,0,1]
	v_pk_fma_f32 v[2:3], v[2:3], s[30:31], v[18:19] op_sel:[0,0,1] op_sel_hi:[1,0,0]
	v_pk_add_f32 v[18:19], v[4:5], v[20:21]
	v_pk_add_f32 v[4:5], v[4:5], v[20:21] neg_lo:[0,1] neg_hi:[0,1]
	s_nop 0
	v_pk_mul_f32 v[20:21], v[4:5], s[10:11]
	s_nop 0
	v_pk_fma_f32 v[4:5], v[4:5], s[14:15], v[20:21] op_sel:[0,0,1] op_sel_hi:[1,0,0]
	v_pk_add_f32 v[20:21], v[6:7], v[22:23]
	v_pk_add_f32 v[6:7], v[6:7], v[22:23] neg_lo:[0,1] neg_hi:[0,1]
	s_nop 0
	v_pk_mul_f32 v[22:23], v[6:7], s[34:35]
	s_nop 0
	v_pk_fma_f32 v[6:7], v[6:7], s[0:1], v[22:23] op_sel:[0,0,1] op_sel_hi:[1,0,0]
	v_pk_add_f32 v[22:23], v[8:9], v[26:27]
	v_pk_add_f32 v[8:9], v[8:9], v[26:27] neg_lo:[0,1] neg_hi:[0,1]
	v_pk_add_f32 v[26:27], v[10:11], v[28:29]
	v_pk_add_f32 v[10:11], v[10:11], v[28:29] neg_lo:[0,1] neg_hi:[0,1]
	s_nop 0
	v_pk_mul_f32 v[28:29], v[10:11], s[34:35]
	s_nop 0
	v_pk_fma_f32 v[10:11], v[10:11], s[0:1], v[28:29] op_sel:[0,0,1] op_sel_hi:[1,0,0] neg_lo:[1,0,0] neg_hi:[1,0,0]
	v_pk_add_f32 v[28:29], v[12:13], v[30:31]
	v_pk_add_f32 v[12:13], v[12:13], v[30:31] neg_lo:[0,1] neg_hi:[0,1]
	s_nop 0
	v_pk_mul_f32 v[30:31], v[12:13], s[10:11]
	s_nop 0
	v_pk_fma_f32 v[12:13], v[12:13], s[14:15], v[30:31] op_sel:[0,0,1] op_sel_hi:[1,0,0] neg_lo:[1,0,0] neg_hi:[1,0,0]
	v_pk_add_f32 v[30:31], v[14:15], v[24:25]
	v_pk_add_f32 v[14:15], v[14:15], v[24:25] neg_lo:[0,1] neg_hi:[0,1]
	s_nop 0
	v_pk_mul_f32 v[24:25], v[14:15], s[18:19]
	s_nop 0
	v_pk_fma_f32 v[14:15], v[14:15], s[30:31], v[24:25] op_sel:[0,0,1] op_sel_hi:[1,0,0] neg_lo:[1,0,0] neg_hi:[1,0,0]
	v_pk_add_f32 v[24:25], v[78:79], v[22:23]
	v_pk_add_f32 v[22:23], v[78:79], v[22:23] neg_lo:[0,1] neg_hi:[0,1]
	v_pk_add_f32 v[78:79], v[16:17], v[26:27]
	v_pk_add_f32 v[16:17], v[16:17], v[26:27] neg_lo:[0,1] neg_hi:[0,1]
	s_nop 0
	v_pk_mul_f32 v[26:27], v[16:17], s[10:11]
	s_nop 0
	v_pk_fma_f32 v[16:17], v[16:17], s[14:15], v[26:27] op_sel:[0,0,1] op_sel_hi:[1,0,0]
	v_pk_add_f32 v[26:27], v[18:19], v[28:29]
	v_pk_add_f32 v[18:19], v[18:19], v[28:29] neg_lo:[0,1] neg_hi:[0,1]
	v_pk_add_f32 v[28:29], v[20:21], v[30:31]
	v_pk_add_f32 v[20:21], v[20:21], v[30:31] neg_lo:[0,1] neg_hi:[0,1]
	s_nop 0
	v_pk_mul_f32 v[30:31], v[20:21], s[10:11]
	s_nop 0
	v_pk_fma_f32 v[20:21], v[20:21], s[14:15], v[30:31] op_sel:[0,0,1] op_sel_hi:[1,0,0] neg_lo:[1,0,0] neg_hi:[1,0,0]
	v_pk_add_f32 v[30:31], v[0:1], v[8:9] op_sel:[0,1] op_sel_hi:[1,0] neg_hi:[0,1]
	v_pk_add_f32 v[0:1], v[0:1], v[8:9] op_sel:[0,1] op_sel_hi:[1,0] neg_lo:[0,1]
	v_pk_add_f32 v[8:9], v[2:3], v[10:11]
	v_pk_add_f32 v[2:3], v[2:3], v[10:11] neg_lo:[0,1] neg_hi:[0,1]
	s_nop 0
	v_pk_mul_f32 v[10:11], v[2:3], s[10:11]
	s_nop 0
	v_pk_fma_f32 v[2:3], v[2:3], s[14:15], v[10:11] op_sel:[0,0,1] op_sel_hi:[1,0,0]
	v_pk_add_f32 v[10:11], v[4:5], v[12:13]
	v_pk_add_f32 v[4:5], v[4:5], v[12:13] neg_lo:[0,1] neg_hi:[0,1]
	v_pk_add_f32 v[12:13], v[6:7], v[14:15]
	v_pk_add_f32 v[6:7], v[6:7], v[14:15] neg_lo:[0,1] neg_hi:[0,1]
	s_nop 0
	v_pk_mul_f32 v[14:15], v[6:7], s[10:11]
	s_nop 0
	v_pk_fma_f32 v[6:7], v[6:7], s[14:15], v[14:15] op_sel:[0,0,1] op_sel_hi:[1,0,0] neg_lo:[1,0,0] neg_hi:[1,0,0]
	v_pk_add_f32 v[14:15], v[24:25], v[26:27]
	v_pk_add_f32 v[24:25], v[24:25], v[26:27] neg_lo:[0,1] neg_hi:[0,1]
	v_pk_add_f32 v[26:27], v[78:79], v[28:29]
	v_pk_add_f32 v[28:29], v[78:79], v[28:29] neg_lo:[0,1] neg_hi:[0,1]
	v_pk_add_f32 v[78:79], v[22:23], v[18:19] op_sel:[0,1] op_sel_hi:[1,0] neg_hi:[0,1]
	v_pk_add_f32 v[18:19], v[22:23], v[18:19] op_sel:[0,1] op_sel_hi:[1,0] neg_lo:[0,1]
	v_pk_add_f32 v[22:23], v[16:17], v[20:21]
	v_pk_add_f32 v[16:17], v[16:17], v[20:21] neg_lo:[0,1] neg_hi:[0,1]
	v_pk_add_f32 v[20:21], v[30:31], v[10:11]
	v_pk_add_f32 v[10:11], v[30:31], v[10:11] neg_lo:[0,1] neg_hi:[0,1]
	v_pk_add_f32 v[30:31], v[8:9], v[12:13]
	v_pk_add_f32 v[8:9], v[8:9], v[12:13] neg_lo:[0,1] neg_hi:[0,1]
	v_pk_add_f32 v[12:13], v[0:1], v[4:5] op_sel:[0,1] op_sel_hi:[1,0] neg_hi:[0,1]
	v_pk_add_f32 v[0:1], v[0:1], v[4:5] op_sel:[0,1] op_sel_hi:[1,0] neg_lo:[0,1]
	v_pk_add_f32 v[4:5], v[2:3], v[6:7]
	v_pk_add_f32 v[2:3], v[2:3], v[6:7] neg_lo:[0,1] neg_hi:[0,1]
	s_nop 0
	v_pk_mul_f32 v[2:3], v[2:3], s[22:23]
	v_pk_add_f32 v[6:7], v[14:15], v[26:27]
	v_pk_add_f32 v[14:15], v[14:15], v[26:27] neg_lo:[0,1] neg_hi:[0,1]
	v_pk_add_f32 v[26:27], v[24:25], v[28:29] op_sel:[0,1] op_sel_hi:[1,0] neg_hi:[0,1]
	v_pk_add_f32 v[24:25], v[24:25], v[28:29] op_sel:[0,1] op_sel_hi:[1,0] neg_lo:[0,1]
	v_pk_add_f32 v[28:29], v[78:79], v[22:23]
	v_pk_add_f32 v[22:23], v[78:79], v[22:23] neg_lo:[0,1] neg_hi:[0,1]
	v_pk_add_f32 v[78:79], v[18:19], v[16:17] op_sel:[0,1] op_sel_hi:[1,0] neg_hi:[0,1]
	v_pk_add_f32 v[16:17], v[18:19], v[16:17] op_sel:[0,1] op_sel_hi:[1,0] neg_lo:[0,1]
	v_pk_add_f32 v[18:19], v[20:21], v[30:31]
	v_pk_add_f32 v[20:21], v[20:21], v[30:31] neg_lo:[0,1] neg_hi:[0,1]
	v_pk_add_f32 v[30:31], v[10:11], v[8:9] op_sel:[0,1] op_sel_hi:[1,0] neg_hi:[0,1]
	v_pk_add_f32 v[8:9], v[10:11], v[8:9] op_sel:[0,1] op_sel_hi:[1,0] neg_lo:[0,1]
	v_pk_add_f32 v[10:11], v[12:13], v[4:5]
	v_pk_add_f32 v[4:5], v[12:13], v[4:5] neg_lo:[0,1] neg_hi:[0,1]
	v_pk_add_f32 v[12:13], v[0:1], v[2:3] op_sel:[0,1] op_sel_hi:[1,0]
	v_pk_add_f32 v[0:1], v[0:1], v[2:3] op_sel:[0,1] op_sel_hi:[1,0] neg_lo:[0,1] neg_hi:[0,1]
	v_lshlrev_b32_e32 v2, 4, v39
	v_and_or_b32 v2, v2, s7, v86
	v_ashrrev_i32_e32 v3, 4, v2
	v_lshlrev_b32_e32 v3, 3, v3
	v_lshlrev_b32_e32 v2, 3, v2
	v_add3_u32 v2, s26, v3, v2
	v_add_u32_e32 v3, 0x800, v2
	v_mov_b32_e32 v39, v32
	ds_write2_b64 v2, v[6:7], v[18:19] offset1:34
	ds_write2_b64 v3, v[14:15], v[20:21] offset0:16 offset1:50
	ds_write2_b64 v2, v[26:27], v[30:31] offset0:136 offset1:170
	ds_write2_b64 v3, v[24:25], v[8:9] offset0:152 offset1:186
	ds_write2_b64 v2, v[28:29], v[10:11] offset0:68 offset1:102
	ds_write2_b64 v3, v[22:23], v[4:5] offset0:84 offset1:118
	ds_write2_b64 v2, v[78:79], v[12:13] offset0:204 offset1:238
	ds_write2_b64 v3, v[16:17], v[0:1] offset0:220 offset1:254
	s_waitcnt lgkmcnt(0)
	s_barrier
	s_nop 0
	v_and_b32_e32 v86, 0x1ff, v39
	v_cvt_f32_u32_e32 v24, v86
	v_ashrrev_i32_e32 v0, 4, v39
	v_lshlrev_b32_e32 v0, 3, v0
	v_lshlrev_b32_e32 v1, 3, v39
	v_mul_f32_e32 v80, 0x39000000, v24
	v_sin_f32_e32 v24, v80
	v_cos_f32_e32 v80, v80
	v_add3_u32 v25, s26, v0, v1
	ds_read_b64 v[0:1], v25
	ds_read_b64 v[2:3], v25 offset:4352
	ds_read_b64 v[4:5], v25 offset:8704
	ds_read_b64 v[6:7], v25 offset:13056
	ds_read_b64 v[8:9], v25 offset:17408
	ds_read_b64 v[10:11], v25 offset:21760
	ds_read_b64 v[12:13], v25 offset:26112
	ds_read_b64 v[14:15], v25 offset:30464
	v_xor_b32_e32 v81, 0x80000000, v24
	s_waitcnt lgkmcnt(6)
	v_pk_mul_f32 v[82:83], v[2:3], v[24:25] op_sel:[1,0] op_sel_hi:[0,0] neg_hi:[0,1]
	v_pk_fma_f32 v[2:3], v[2:3], v[80:81], v[82:83] op_sel_hi:[1,0,1]
	v_pk_mul_f32 v[82:83], v[24:25], v[80:81] op_sel:[0,1] op_sel_hi:[0,0] neg_hi:[1,0]
	v_pk_fma_f32 v[82:83], v[80:81], v[80:81], v[82:83] op_sel_hi:[0,1,1]
	ds_read_b64 v[16:17], v25 offset:34816
	ds_read_b64 v[18:19], v25 offset:39168
	ds_read_b64 v[20:21], v25 offset:43520
	ds_read_b64 v[22:23], v25 offset:47872
	s_waitcnt lgkmcnt(9)
	v_pk_mul_f32 v[84:85], v[4:5], v[82:83] op_sel:[1,1] op_sel_hi:[0,1] neg_lo:[0,1]
	v_pk_fma_f32 v[4:5], v[4:5], v[82:83], v[84:85] op_sel_hi:[1,0,1]
	v_pk_mul_f32 v[84:85], v[24:25], v[82:83] op_sel:[0,1] op_sel_hi:[0,0] neg_hi:[1,0]
	v_pk_fma_f32 v[82:83], v[80:81], v[82:83], v[84:85] op_sel_hi:[0,1,1]
	ds_read_b64 v[26:27], v25 offset:52224
	ds_read_b64 v[28:29], v25 offset:56576
	ds_read_b64 v[30:31], v25 offset:60928
	ds_read_b64 v[78:79], v25 offset:65280
	s_waitcnt lgkmcnt(12)
	v_pk_mul_f32 v[84:85], v[6:7], v[82:83] op_sel:[1,1] op_sel_hi:[0,1] neg_lo:[0,1]
	v_pk_fma_f32 v[6:7], v[6:7], v[82:83], v[84:85] op_sel_hi:[1,0,1]
	v_pk_mul_f32 v[84:85], v[24:25], v[82:83] op_sel:[0,1] op_sel_hi:[0,0] neg_hi:[1,0]
	v_pk_fma_f32 v[82:83], v[80:81], v[82:83], v[84:85] op_sel_hi:[0,1,1]
	s_waitcnt lgkmcnt(0)
	v_pk_mul_f32 v[84:85], v[8:9], v[82:83] op_sel:[1,1] op_sel_hi:[0,1] neg_lo:[0,1]
	v_pk_fma_f32 v[8:9], v[8:9], v[82:83], v[84:85] op_sel_hi:[1,0,1]
	v_pk_mul_f32 v[84:85], v[24:25], v[82:83] op_sel:[0,1] op_sel_hi:[0,0] neg_hi:[1,0]
	v_pk_fma_f32 v[82:83], v[80:81], v[82:83], v[84:85] op_sel_hi:[0,1,1]
	s_barrier
	v_pk_mul_f32 v[84:85], v[10:11], v[82:83] op_sel:[1,1] op_sel_hi:[0,1] neg_lo:[0,1]
	v_pk_fma_f32 v[10:11], v[10:11], v[82:83], v[84:85] op_sel_hi:[1,0,1]
	v_pk_mul_f32 v[84:85], v[24:25], v[82:83] op_sel:[0,1] op_sel_hi:[0,0] neg_hi:[1,0]
	v_pk_fma_f32 v[82:83], v[80:81], v[82:83], v[84:85] op_sel_hi:[0,1,1]
	s_nop 0
	v_pk_mul_f32 v[84:85], v[12:13], v[82:83] op_sel:[1,1] op_sel_hi:[0,1] neg_lo:[0,1]
	v_pk_fma_f32 v[12:13], v[12:13], v[82:83], v[84:85] op_sel_hi:[1,0,1]
	v_pk_mul_f32 v[84:85], v[24:25], v[82:83] op_sel:[0,1] op_sel_hi:[0,0] neg_hi:[1,0]
	v_pk_fma_f32 v[82:83], v[80:81], v[82:83], v[84:85] op_sel_hi:[0,1,1]
	s_nop 0
	v_pk_mul_f32 v[84:85], v[14:15], v[82:83] op_sel:[1,1] op_sel_hi:[0,1] neg_lo:[0,1]
	v_pk_fma_f32 v[14:15], v[14:15], v[82:83], v[84:85] op_sel_hi:[1,0,1]
	v_pk_mul_f32 v[84:85], v[24:25], v[82:83] op_sel:[0,1] op_sel_hi:[0,0] neg_hi:[1,0]
	v_pk_fma_f32 v[82:83], v[80:81], v[82:83], v[84:85] op_sel_hi:[0,1,1]
	s_nop 0
	v_pk_mul_f32 v[84:85], v[16:17], v[82:83] op_sel:[1,1] op_sel_hi:[0,1] neg_lo:[0,1]
	v_pk_fma_f32 v[16:17], v[16:17], v[82:83], v[84:85] op_sel_hi:[1,0,1]
	v_pk_mul_f32 v[84:85], v[24:25], v[82:83] op_sel:[0,1] op_sel_hi:[0,0] neg_hi:[1,0]
	v_pk_fma_f32 v[82:83], v[80:81], v[82:83], v[84:85] op_sel_hi:[0,1,1]
	s_nop 0
	v_pk_mul_f32 v[84:85], v[18:19], v[82:83] op_sel:[1,1] op_sel_hi:[0,1] neg_lo:[0,1]
	v_pk_fma_f32 v[18:19], v[18:19], v[82:83], v[84:85] op_sel_hi:[1,0,1]
	v_pk_mul_f32 v[84:85], v[24:25], v[82:83] op_sel:[0,1] op_sel_hi:[0,0] neg_hi:[1,0]
	v_pk_fma_f32 v[82:83], v[80:81], v[82:83], v[84:85] op_sel_hi:[0,1,1]
	s_nop 0
	v_pk_mul_f32 v[84:85], v[20:21], v[82:83] op_sel:[1,1] op_sel_hi:[0,1] neg_lo:[0,1]
	v_pk_fma_f32 v[20:21], v[20:21], v[82:83], v[84:85] op_sel_hi:[1,0,1]
	v_pk_mul_f32 v[84:85], v[24:25], v[82:83] op_sel:[0,1] op_sel_hi:[0,0] neg_hi:[1,0]
	v_pk_fma_f32 v[82:83], v[80:81], v[82:83], v[84:85] op_sel_hi:[0,1,1]
	s_nop 0
	v_pk_mul_f32 v[84:85], v[22:23], v[82:83] op_sel:[1,1] op_sel_hi:[0,1] neg_lo:[0,1]
	v_pk_fma_f32 v[22:23], v[22:23], v[82:83], v[84:85] op_sel_hi:[1,0,1]
	v_pk_mul_f32 v[84:85], v[24:25], v[82:83] op_sel:[0,1] op_sel_hi:[0,0] neg_hi:[1,0]
	v_pk_fma_f32 v[82:83], v[80:81], v[82:83], v[84:85] op_sel_hi:[0,1,1]
	s_nop 0
	v_pk_mul_f32 v[84:85], v[26:27], v[82:83] op_sel:[1,1] op_sel_hi:[0,1] neg_lo:[0,1]
	v_pk_fma_f32 v[26:27], v[26:27], v[82:83], v[84:85] op_sel_hi:[1,0,1]
	v_pk_mul_f32 v[84:85], v[24:25], v[82:83] op_sel:[0,1] op_sel_hi:[0,0] neg_hi:[1,0]
	v_pk_fma_f32 v[82:83], v[80:81], v[82:83], v[84:85] op_sel_hi:[0,1,1]
	s_nop 0
	v_pk_mul_f32 v[84:85], v[28:29], v[82:83] op_sel:[1,1] op_sel_hi:[0,1] neg_lo:[0,1]
	v_pk_fma_f32 v[28:29], v[28:29], v[82:83], v[84:85] op_sel_hi:[1,0,1]
	v_pk_mul_f32 v[84:85], v[24:25], v[82:83] op_sel:[0,1] op_sel_hi:[0,0] neg_hi:[1,0]
	v_pk_fma_f32 v[82:83], v[80:81], v[82:83], v[84:85] op_sel_hi:[0,1,1]
	v_pk_mul_f32 v[24:25], v[24:25], v[82:83] op_sel:[0,1] op_sel_hi:[0,0] neg_hi:[1,0]
	v_pk_fma_f32 v[24:25], v[80:81], v[82:83], v[24:25] op_sel_hi:[0,1,1]
	v_pk_mul_f32 v[80:81], v[78:79], v[24:25] op_sel:[1,1] op_sel_hi:[0,1] neg_lo:[0,1]
	v_pk_fma_f32 v[24:25], v[78:79], v[24:25], v[80:81] op_sel_hi:[1,0,1]
	v_pk_add_f32 v[78:79], v[0:1], v[16:17]
	v_pk_add_f32 v[0:1], v[0:1], v[16:17] neg_lo:[0,1] neg_hi:[0,1]
	v_pk_add_f32 v[16:17], v[2:3], v[18:19]
	v_pk_add_f32 v[2:3], v[2:3], v[18:19] neg_lo:[0,1] neg_hi:[0,1]
	v_pk_mul_f32 v[84:85], v[30:31], v[82:83] op_sel:[1,1] op_sel_hi:[0,1] neg_lo:[0,1]
	v_pk_mul_f32 v[18:19], v[2:3], s[18:19]
	v_pk_fma_f32 v[30:31], v[30:31], v[82:83], v[84:85] op_sel_hi:[1,0,1]
	v_pk_fma_f32 v[2:3], v[2:3], s[30:31], v[18:19] op_sel:[0,0,1] op_sel_hi:[1,0,0]
	v_pk_add_f32 v[18:19], v[4:5], v[20:21]
	v_pk_add_f32 v[4:5], v[4:5], v[20:21] neg_lo:[0,1] neg_hi:[0,1]
	v_mov_b32_e32 v81, 0
	v_pk_mul_f32 v[20:21], v[4:5], s[10:11]
	v_mov_b32_e32 v80, 0
	v_pk_fma_f32 v[4:5], v[4:5], s[14:15], v[20:21] op_sel:[0,0,1] op_sel_hi:[1,0,0]
	v_pk_add_f32 v[20:21], v[6:7], v[22:23]
	v_pk_add_f32 v[6:7], v[6:7], v[22:23] neg_lo:[0,1] neg_hi:[0,1]
	s_nop 0
	v_pk_mul_f32 v[22:23], v[6:7], s[34:35]
	s_nop 0
	v_pk_fma_f32 v[6:7], v[6:7], s[0:1], v[22:23] op_sel:[0,0,1] op_sel_hi:[1,0,0]
	v_pk_add_f32 v[22:23], v[8:9], v[26:27]
	v_pk_add_f32 v[8:9], v[8:9], v[26:27] neg_lo:[0,1] neg_hi:[0,1]
	v_pk_add_f32 v[26:27], v[10:11], v[28:29]
	v_pk_add_f32 v[10:11], v[10:11], v[28:29] neg_lo:[0,1] neg_hi:[0,1]
	s_nop 0
	v_pk_mul_f32 v[28:29], v[10:11], s[34:35]
	s_nop 0
	v_pk_fma_f32 v[10:11], v[10:11], s[0:1], v[28:29] op_sel:[0,0,1] op_sel_hi:[1,0,0] neg_lo:[1,0,0] neg_hi:[1,0,0]
	v_pk_add_f32 v[28:29], v[12:13], v[30:31]
	v_pk_add_f32 v[12:13], v[12:13], v[30:31] neg_lo:[0,1] neg_hi:[0,1]
	s_lshl_b32 s0, s57, 9
	v_pk_mul_f32 v[30:31], v[12:13], s[10:11]
	s_add_u32 s0, s60, s0
	v_pk_fma_f32 v[12:13], v[12:13], s[14:15], v[30:31] op_sel:[0,0,1] op_sel_hi:[1,0,0] neg_lo:[1,0,0] neg_hi:[1,0,0]
	v_pk_add_f32 v[30:31], v[14:15], v[24:25]
	v_pk_add_f32 v[14:15], v[14:15], v[24:25] neg_lo:[0,1] neg_hi:[0,1]
	s_addc_u32 s1, s61, 0
	v_pk_mul_f32 v[24:25], v[14:15], s[18:19]
	s_add_u32 s0, s0, 0x81b2000
	v_pk_fma_f32 v[14:15], v[14:15], s[30:31], v[24:25] op_sel:[0,0,1] op_sel_hi:[1,0,0] neg_lo:[1,0,0] neg_hi:[1,0,0]
	v_pk_add_f32 v[24:25], v[78:79], v[22:23]
	v_pk_add_f32 v[22:23], v[78:79], v[22:23] neg_lo:[0,1] neg_hi:[0,1]
	v_pk_add_f32 v[78:79], v[16:17], v[26:27]
	v_pk_add_f32 v[16:17], v[16:17], v[26:27] neg_lo:[0,1] neg_hi:[0,1]
	s_addc_u32 s1, s1, 0
	v_pk_mul_f32 v[26:27], v[16:17], s[10:11]
	s_nop 0
	v_pk_fma_f32 v[16:17], v[16:17], s[14:15], v[26:27] op_sel:[0,0,1] op_sel_hi:[1,0,0]
	v_pk_add_f32 v[26:27], v[18:19], v[28:29]
	v_pk_add_f32 v[18:19], v[18:19], v[28:29] neg_lo:[0,1] neg_hi:[0,1]
	v_pk_add_f32 v[28:29], v[20:21], v[30:31]
	v_pk_add_f32 v[20:21], v[20:21], v[30:31] neg_lo:[0,1] neg_hi:[0,1]
	s_nop 0
	v_pk_mul_f32 v[30:31], v[20:21], s[10:11]
	s_nop 0
	v_pk_fma_f32 v[20:21], v[20:21], s[14:15], v[30:31] op_sel:[0,0,1] op_sel_hi:[1,0,0] neg_lo:[1,0,0] neg_hi:[1,0,0]
	v_pk_add_f32 v[30:31], v[0:1], v[8:9] op_sel:[0,1] op_sel_hi:[1,0] neg_hi:[0,1]
	v_pk_add_f32 v[0:1], v[0:1], v[8:9] op_sel:[0,1] op_sel_hi:[1,0] neg_lo:[0,1]
	v_pk_add_f32 v[8:9], v[2:3], v[10:11]
	v_pk_add_f32 v[2:3], v[2:3], v[10:11] neg_lo:[0,1] neg_hi:[0,1]
	s_nop 0
	v_pk_mul_f32 v[10:11], v[2:3], s[10:11]
	s_nop 0
	v_pk_fma_f32 v[2:3], v[2:3], s[14:15], v[10:11] op_sel:[0,0,1] op_sel_hi:[1,0,0]
	v_pk_add_f32 v[10:11], v[4:5], v[12:13]
	v_pk_add_f32 v[4:5], v[4:5], v[12:13] neg_lo:[0,1] neg_hi:[0,1]
	v_pk_add_f32 v[12:13], v[6:7], v[14:15]
	v_pk_add_f32 v[6:7], v[6:7], v[14:15] neg_lo:[0,1] neg_hi:[0,1]
	s_nop 0
	v_pk_mul_f32 v[14:15], v[6:7], s[10:11]
	s_nop 0
	v_pk_fma_f32 v[6:7], v[6:7], s[14:15], v[14:15] op_sel:[0,0,1] op_sel_hi:[1,0,0] neg_lo:[1,0,0] neg_hi:[1,0,0]
	v_pk_add_f32 v[14:15], v[24:25], v[26:27]
	v_pk_add_f32 v[24:25], v[24:25], v[26:27] neg_lo:[0,1] neg_hi:[0,1]
	v_pk_add_f32 v[26:27], v[78:79], v[28:29]
	v_pk_add_f32 v[28:29], v[78:79], v[28:29] neg_lo:[0,1] neg_hi:[0,1]
	v_pk_add_f32 v[78:79], v[22:23], v[18:19] op_sel:[0,1] op_sel_hi:[1,0] neg_hi:[0,1]
	v_pk_add_f32 v[18:19], v[22:23], v[18:19] op_sel:[0,1] op_sel_hi:[1,0] neg_lo:[0,1]
	v_pk_add_f32 v[22:23], v[16:17], v[20:21]
	v_pk_add_f32 v[16:17], v[16:17], v[20:21] neg_lo:[0,1] neg_hi:[0,1]
	v_pk_add_f32 v[20:21], v[30:31], v[10:11]
	v_pk_add_f32 v[10:11], v[30:31], v[10:11] neg_lo:[0,1] neg_hi:[0,1]
	v_pk_add_f32 v[30:31], v[8:9], v[12:13]
	v_pk_add_f32 v[8:9], v[8:9], v[12:13] neg_lo:[0,1] neg_hi:[0,1]
	v_pk_add_f32 v[12:13], v[0:1], v[4:5] op_sel:[0,1] op_sel_hi:[1,0] neg_hi:[0,1]
	v_pk_add_f32 v[0:1], v[0:1], v[4:5] op_sel:[0,1] op_sel_hi:[1,0] neg_lo:[0,1]
	v_pk_add_f32 v[4:5], v[2:3], v[6:7]
	v_pk_add_f32 v[2:3], v[2:3], v[6:7] neg_lo:[0,1] neg_hi:[0,1]
	s_nop 0
	v_pk_mul_f32 v[2:3], v[2:3], s[22:23]
	v_pk_add_f32 v[6:7], v[14:15], v[26:27]
	v_pk_add_f32 v[14:15], v[14:15], v[26:27] neg_lo:[0,1] neg_hi:[0,1]
	v_pk_add_f32 v[26:27], v[24:25], v[28:29] op_sel:[0,1] op_sel_hi:[1,0] neg_hi:[0,1]
	v_pk_add_f32 v[24:25], v[24:25], v[28:29] op_sel:[0,1] op_sel_hi:[1,0] neg_lo:[0,1]
	v_pk_add_f32 v[28:29], v[78:79], v[22:23]
	v_pk_add_f32 v[22:23], v[78:79], v[22:23] neg_lo:[0,1] neg_hi:[0,1]
	v_pk_add_f32 v[78:79], v[18:19], v[16:17] op_sel:[0,1] op_sel_hi:[1,0] neg_hi:[0,1]
	v_pk_add_f32 v[16:17], v[18:19], v[16:17] op_sel:[0,1] op_sel_hi:[1,0] neg_lo:[0,1]
	v_pk_add_f32 v[18:19], v[20:21], v[30:31]
	v_pk_add_f32 v[20:21], v[20:21], v[30:31] neg_lo:[0,1] neg_hi:[0,1]
	v_pk_add_f32 v[30:31], v[10:11], v[8:9] op_sel:[0,1] op_sel_hi:[1,0] neg_hi:[0,1]
	v_pk_add_f32 v[8:9], v[10:11], v[8:9] op_sel:[0,1] op_sel_hi:[1,0] neg_lo:[0,1]
	v_pk_add_f32 v[10:11], v[12:13], v[4:5]
	v_pk_add_f32 v[4:5], v[12:13], v[4:5] neg_lo:[0,1] neg_hi:[0,1]
	v_pk_add_f32 v[12:13], v[0:1], v[2:3] op_sel:[0,1] op_sel_hi:[1,0]
	v_pk_add_f32 v[0:1], v[0:1], v[2:3] op_sel:[0,1] op_sel_hi:[1,0] neg_lo:[0,1] neg_hi:[0,1]
	v_lshlrev_b32_e32 v2, 4, v39
	v_and_or_b32 v2, v2, s15, v86
	v_ashrrev_i32_e32 v3, 4, v2
	v_lshlrev_b32_e32 v3, 3, v3
	v_lshlrev_b32_e32 v2, 3, v2
	v_add3_u32 v2, s26, v3, v2
	v_and_b32_e32 v39, 31, v32
	ds_write_b64 v2, v[6:7]
	ds_write_b64 v2, v[14:15] offset:34816
	ds_write_b64 v2, v[26:27] offset:17408
	ds_write_b64 v2, v[24:25] offset:52224
	ds_write_b64 v2, v[28:29] offset:8704
	ds_write_b64 v2, v[22:23] offset:43520
	ds_write_b64 v2, v[78:79] offset:26112
	ds_write_b64 v2, v[16:17] offset:60928
	ds_write_b64 v2, v[18:19] offset:4352
	ds_write_b64 v2, v[20:21] offset:39168
	ds_write_b64 v2, v[30:31] offset:21760
	ds_write_b64 v2, v[8:9] offset:56576
	ds_write_b64 v2, v[10:11] offset:13056
	ds_write_b64 v2, v[4:5] offset:47872
	ds_write_b64 v2, v[12:13] offset:30464
	ds_write_b64 v2, v[0:1] offset:65280
	v_lshlrev_b32_e32 v2, 4, v39
	v_ashrrev_i32_e32 v3, 5, v32
	v_mov_b64_e32 v[0:1], s[0:1]
	s_mov_b32 s0, 0x180000
	v_cmp_gt_u32_e64 s[42:43], 16, v39
	v_mad_i64_i32 v[78:79], s[0:1], v3, s0, v[0:1]
	v_mov_b32_e32 v9, 0
	v_lshlrev_b32_e32 v172, 1, v2
	v_mov_b32_e32 v8, 0
	v_mov_b32_e32 v11, 0
	v_mov_b32_e32 v10, 0
	v_mov_b32_e32 v13, 0
	v_mov_b32_e32 v12, 0
	v_mov_b32_e32 v15, 0
	v_mov_b32_e32 v14, 0
	v_mov_b32_e32 v17, 0
	v_mov_b32_e32 v16, 0
	v_mov_b32_e32 v21, 0
	v_mov_b32_e32 v20, 0
	v_mov_b32_e32 v23, 0
	v_mov_b32_e32 v22, 0
	v_mov_b32_e32 v25, 0
	v_mov_b32_e32 v24, 0
	v_mov_b32_e32 v1, 0
	v_mov_b32_e32 v0, 0
	v_mov_b32_e32 v3, 0
	v_mov_b32_e32 v2, 0
	v_mov_b32_e32 v5, 0
	v_mov_b32_e32 v4, 0
	v_mov_b32_e32 v7, 0
	v_mov_b32_e32 v6, 0
	v_mov_b32_e32 v27, 0
	v_mov_b32_e32 v26, 0
	v_mov_b32_e32 v29, 0
	v_mov_b32_e32 v28, 0
	v_mov_b32_e32 v31, 0
	v_mov_b32_e32 v30, 0
	s_waitcnt lgkmcnt(0)
	s_barrier
	s_and_saveexec_b64 s[0:1], s[42:43]
	s_cbranch_execz .LBB0_428
	v_lshl_add_u64 v[0:1], v[78:79], 0, v[172:173]
	global_load_dwordx4 v[8:11], v[0:1], off offset:16
	global_load_dwordx4 v[12:15], v[0:1], off
	v_cmp_ne_u32_e64 s[44:45], 0, v39
	v_mov_b32_e32 v27, 0
	v_mov_b32_e32 v16, 0
	v_mov_b32_e32 v33, 0
	s_and_saveexec_b64 s[4:5], s[44:45]
	s_cbranch_execz .LBB0_421
	global_load_ushort v33, v[0:1], off offset:-2
.LBB0_421:
	s_or_b64 exec, exec, s[4:5]
	v_cmp_ne_u32_e64 s[46:47], 15, v39
	v_mov_b32_e32 v82, 0
	s_and_saveexec_b64 s[4:5], s[46:47]
	s_cbranch_execz .LBB0_423
	global_load_ushort v82, v[0:1], off offset:32
.LBB0_423:
	s_or_b64 exec, exec, s[4:5]
	v_lshl_add_u64 v[0:1], v[78:79], 0, v[172:173]
	s_mov_b64 s[4:5], 0xc0000
	v_lshl_add_u64 v[20:21], v[0:1], 0, s[4:5]
	v_add_co_u32_e32 v0, vcc, 0xc0000, v0
	v_mov_b32_e32 v19, 0
	s_nop 0
	v_addc_co_u32_e32 v1, vcc, 0, v1, vcc
	global_load_dwordx4 v[4:7], v[0:1], off
	s_nop 0
	global_load_dwordx4 v[0:3], v[20:21], off offset:16
	v_mov_b32_e32 v28, 0
	v_mov_b32_e32 v83, 0
	s_and_saveexec_b64 s[4:5], s[44:45]
	s_cbranch_execz .LBB0_425
	global_load_ushort v83, v[20:21], off offset:-2
.LBB0_425:
	s_or_b64 exec, exec, s[4:5]
	v_mov_b32_e32 v84, 0
	s_and_saveexec_b64 s[4:5], s[46:47]
	s_cbranch_execz .LBB0_427
	global_load_ushort v84, v[20:21], off offset:32
.LBB0_427:
	s_or_b64 exec, exec, s[4:5]
	s_waitcnt vmcnt(0)
	v_lshlrev_b32_e32 v16, 16, v33
	v_lshlrev_b32_e32 v27, 16, v82
	v_lshlrev_b32_e32 v28, 16, v83
	v_lshlrev_b32_e32 v19, 16, v84
	v_lshlrev_b32_e32 v25, 16, v13
	v_and_b32_e32 v31, 16, v14
	v_and_b32_e32 v30, 0xffff0000, v13
	v_lshlrev_b32_e32 v13, 16, v14
	v_and_b32_e32 v83, 16, v15
	v_and_b32_e32 v82, 0xffff0000, v14
	v_lshlrev_b32_e32 v85, 16, v15
	v_pk_mov_b32 v[14:15], v[14:15], v[8:9] op_sel:[1,0]
	v_lshlrev_b32_e32 v20, 16, v12
	v_and_b32_e32 v14, 0xffff0000, v14
	v_and_b32_e32 v92, 0xffff0000, v8
	v_and_b32_e32 v98, 0xffff0000, v9
	v_and_b32_e32 v24, 0xffff0000, v12
	v_mov_b32_e32 v17, v20
	v_mov_b32_e32 v12, v30
	v_mov_b32_e32 v84, v82
	v_and_b32_e32 v15, 16, v15
	v_lshlrev_b32_e32 v89, 16, v8
	v_mov_b32_e32 v88, v14
	v_and_b32_e32 v93, 16, v9
	v_lshlrev_b32_e32 v95, 16, v9
	v_mov_b32_e32 v94, v92
	v_and_b32_e32 v99, 16, v10
	v_lshlrev_b32_e32 v9, 16, v10
	v_mov_b32_e32 v8, v98
	v_and_b32_e32 v103, 16, v11
	v_and_b32_e32 v102, 0xffff0000, v10
	v_and_b32_e32 v23, 0xffff0000, v11
	v_mov_b32_e32 v21, v24
	v_pk_fma_f32 v[16:17], v[34:35], v[16:17], v[36:37] op_sel_hi:[0,1,0]
	v_pk_fma_f32 v[80:81], v[34:35], v[24:25], v[36:37] op_sel_hi:[0,1,0]
	v_pk_mov_b32 v[30:31], v[24:25], v[30:31] op_sel:[1,0]
	v_pk_fma_f32 v[86:87], v[34:35], v[12:13], v[36:37] op_sel_hi:[0,1,0]
	v_pk_mov_b32 v[82:83], v[12:13], v[82:83] op_sel:[1,0]
	v_pk_fma_f32 v[90:91], v[34:35], v[84:85], v[36:37] op_sel_hi:[0,1,0]
	v_pk_mov_b32 v[14:15], v[84:85], v[14:15] op_sel:[1,0]
	v_pk_fma_f32 v[96:97], v[34:35], v[88:89], v[36:37] op_sel_hi:[0,1,0]
	v_pk_mov_b32 v[92:93], v[88:89], v[92:93] op_sel:[1,0]
	v_pk_fma_f32 v[100:101], v[34:35], v[94:95], v[36:37] op_sel_hi:[0,1,0]
	v_pk_mov_b32 v[98:99], v[94:95], v[98:99] op_sel:[1,0]
	v_lshlrev_b32_e32 v11, 16, v11
	v_mov_b32_e32 v10, v102
	v_pk_fma_f32 v[104:105], v[34:35], v[8:9], v[36:37] op_sel_hi:[0,1,0]
	v_pk_mov_b32 v[102:103], v[8:9], v[102:103] op_sel:[1,0]
	v_pk_fma_f32 v[106:107], v[34:35], v[10:11], v[36:37] op_sel_hi:[0,1,0]
	v_mov_b32_e32 v22, v11
	v_pk_fma_f32 v[16:17], v[38:39], v[20:21], v[16:17] op_sel_hi:[0,1,1]
	v_pk_fma_f32 v[20:21], v[38:39], v[30:31], v[80:81] op_sel_hi:[0,1,1]
	v_pk_fma_f32 v[30:31], v[38:39], v[82:83], v[86:87] op_sel_hi:[0,1,1]
	v_pk_fma_f32 v[14:15], v[38:39], v[14:15], v[90:91] op_sel_hi:[0,1,1]
	v_pk_fma_f32 v[80:81], v[38:39], v[92:93], v[96:97] op_sel_hi:[0,1,1]
	v_pk_fma_f32 v[82:83], v[38:39], v[98:99], v[100:101] op_sel_hi:[0,1,1]
	v_pk_fma_f32 v[86:87], v[38:39], v[102:103], v[104:105] op_sel_hi:[0,1,1]
	v_mov_b32_e32 v26, v23
	v_pk_fma_f32 v[90:91], v[38:39], v[22:23], v[106:107] op_sel_hi:[0,1,1]
	v_pk_fma_f32 v[24:25], v[40:41], v[24:25], v[16:17] op_sel_hi:[0,1,1]
	v_pk_fma_f32 v[22:23], v[40:41], v[12:13], v[20:21] op_sel_hi:[0,1,1]
	v_pk_fma_f32 v[16:17], v[40:41], v[88:89], v[14:15] op_sel_hi:[0,1,1]
	v_pk_fma_f32 v[14:15], v[40:41], v[94:95], v[80:81] op_sel_hi:[0,1,1]
	v_pk_fma_f32 v[12:13], v[40:41], v[8:9], v[82:83] op_sel_hi:[0,1,1]
	v_pk_fma_f32 v[10:11], v[40:41], v[10:11], v[86:87] op_sel_hi:[0,1,1]
	s_waitcnt vmcnt(1)
	v_lshlrev_b32_e32 v81, 16, v5
	v_and_b32_e32 v83, 16, v6
	v_and_b32_e32 v82, 0xffff0000, v5
	v_lshlrev_b32_e32 v5, 16, v6
	v_and_b32_e32 v87, 16, v7
	v_and_b32_e32 v86, 0xffff0000, v6
	v_lshlrev_b32_e32 v89, 16, v7
	s_waitcnt vmcnt(0)
	v_pk_mov_b32 v[6:7], v[6:7], v[0:1] op_sel:[1,0]
	v_pk_fma_f32 v[8:9], v[40:41], v[26:27], v[90:91] op_sel_hi:[0,1,1]
	v_lshlrev_b32_e32 v26, 16, v4
	v_and_b32_e32 v6, 0xffff0000, v6
	v_and_b32_e32 v96, 0xffff0000, v0
	v_and_b32_e32 v102, 0xffff0000, v1
	v_and_b32_e32 v106, 0xffff0000, v2
	v_pk_fma_f32 v[20:21], v[40:41], v[84:85], v[30:31] op_sel_hi:[0,1,1]
	v_and_b32_e32 v31, 0xffff0000, v3
	v_and_b32_e32 v80, 0xffff0000, v4
	v_mov_b32_e32 v29, v26
	v_mov_b32_e32 v4, v82
	v_mov_b32_e32 v88, v86
	v_and_b32_e32 v7, 16, v7
	v_lshlrev_b32_e32 v93, 16, v0
	v_mov_b32_e32 v92, v6
	v_and_b32_e32 v97, 16, v1
	v_lshlrev_b32_e32 v99, 16, v1
	v_mov_b32_e32 v98, v96
	v_and_b32_e32 v103, 16, v2
	v_lshlrev_b32_e32 v1, 16, v2
	v_mov_b32_e32 v0, v102
	v_and_b32_e32 v107, 16, v3
	v_lshlrev_b32_e32 v3, 16, v3
	v_mov_b32_e32 v2, v106
	v_mov_b32_e32 v27, v80
	v_pk_fma_f32 v[28:29], v[34:35], v[28:29], v[36:37] op_sel_hi:[0,1,0]
	v_pk_fma_f32 v[84:85], v[34:35], v[80:81], v[36:37] op_sel_hi:[0,1,0]
	v_pk_mov_b32 v[82:83], v[80:81], v[82:83] op_sel:[1,0]
	v_pk_fma_f32 v[90:91], v[34:35], v[4:5], v[36:37] op_sel_hi:[0,1,0]
	v_pk_mov_b32 v[86:87], v[4:5], v[86:87] op_sel:[1,0]
	v_pk_fma_f32 v[94:95], v[34:35], v[88:89], v[36:37] op_sel_hi:[0,1,0]
	v_pk_mov_b32 v[6:7], v[88:89], v[6:7] op_sel:[1,0]
	v_pk_fma_f32 v[100:101], v[34:35], v[92:93], v[36:37] op_sel_hi:[0,1,0]
	v_pk_mov_b32 v[96:97], v[92:93], v[96:97] op_sel:[1,0]
	v_pk_fma_f32 v[104:105], v[34:35], v[98:99], v[36:37] op_sel_hi:[0,1,0]
	v_pk_mov_b32 v[102:103], v[98:99], v[102:103] op_sel:[1,0]
	v_pk_fma_f32 v[108:109], v[34:35], v[0:1], v[36:37] op_sel_hi:[0,1,0]
	v_pk_mov_b32 v[106:107], v[0:1], v[106:107] op_sel:[1,0]
	v_pk_fma_f32 v[110:111], v[34:35], v[2:3], v[36:37] op_sel_hi:[0,1,0]
	v_mov_b32_e32 v30, v3
	v_mov_b32_e32 v18, v31
	v_pk_fma_f32 v[26:27], v[38:39], v[26:27], v[28:29] op_sel_hi:[0,1,1]
	v_pk_fma_f32 v[28:29], v[38:39], v[82:83], v[84:85] op_sel_hi:[0,1,1]
	v_pk_fma_f32 v[82:83], v[38:39], v[86:87], v[90:91] op_sel_hi:[0,1,1]
	v_pk_fma_f32 v[6:7], v[38:39], v[6:7], v[94:95] op_sel_hi:[0,1,1]
	v_pk_fma_f32 v[84:85], v[38:39], v[96:97], v[100:101] op_sel_hi:[0,1,1]
	v_pk_fma_f32 v[86:87], v[38:39], v[102:103], v[104:105] op_sel_hi:[0,1,1]
	v_pk_fma_f32 v[90:91], v[38:39], v[106:107], v[108:109] op_sel_hi:[0,1,1]
	v_pk_fma_f32 v[94:95], v[38:39], v[30:31], v[110:111] op_sel_hi:[0,1,1]
	v_pk_fma_f32 v[80:81], v[40:41], v[80:81], v[26:27] op_sel_hi:[0,1,1]
	v_pk_fma_f32 v[30:31], v[40:41], v[4:5], v[28:29] op_sel_hi:[0,1,1]
	v_pk_fma_f32 v[28:29], v[40:41], v[88:89], v[82:83] op_sel_hi:[0,1,1]
	v_pk_fma_f32 v[26:27], v[40:41], v[92:93], v[6:7] op_sel_hi:[0,1,1]
	v_pk_fma_f32 v[6:7], v[40:41], v[98:99], v[84:85] op_sel_hi:[0,1,1]
	v_pk_fma_f32 v[4:5], v[40:41], v[0:1], v[86:87] op_sel_hi:[0,1,1]
	v_pk_fma_f32 v[2:3], v[40:41], v[2:3], v[90:91] op_sel_hi:[0,1,1]
	v_pk_fma_f32 v[0:1], v[40:41], v[18:19], v[94:95] op_sel_hi:[0,1,1]

.LBB0_438:
	s_or_b64 exec, exec, s[0:1]
	v_mov_b32_e32 v47, v32
	s_waitcnt lgkmcnt(0)
	s_barrier
	s_mov_b32 s11, s14
	v_and_b32_e32 v81, 31, v47
	v_cvt_f32_ubyte0_e32 v24, v81
	v_mul_f32_e32 v110, 0x3b000000, v24
	v_sin_f32_e32 v24, v110
	v_ashrrev_i32_e32 v0, 4, v47
	v_lshlrev_b32_e32 v0, 3, v0
	v_lshlrev_b32_e32 v1, 3, v47
	v_cos_f32_e32 v110, v110
	v_add3_u32 v25, 0, v0, v1
	ds_read_b64 v[0:1], v25
	ds_read_b64 v[2:3], v25 offset:4352
	ds_read_b64 v[4:5], v25 offset:8704
	ds_read_b64 v[6:7], v25 offset:13056
	ds_read_b64 v[8:9], v25 offset:17408
	ds_read_b64 v[10:11], v25 offset:21760
	ds_read_b64 v[12:13], v25 offset:26112
	ds_read_b64 v[14:15], v25 offset:30464
	ds_read_b64 v[16:17], v25 offset:34816
	ds_read_b64 v[18:19], v25 offset:39168
	ds_read_b64 v[20:21], v25 offset:43520
	ds_read_b64 v[22:23], v25 offset:47872
	v_xor_b32_e32 v111, 0x80000000, v24
	s_waitcnt lgkmcnt(10)
	v_pk_mul_f32 v[118:119], v[2:3], v[24:25] op_sel:[1,0] op_sel_hi:[0,0] neg_hi:[0,1]
	v_pk_fma_f32 v[2:3], v[2:3], v[110:111], v[118:119] op_sel_hi:[1,0,1]
	v_pk_mul_f32 v[118:119], v[24:25], v[110:111] op_sel:[0,1] op_sel_hi:[0,0] neg_hi:[1,0]
	v_pk_fma_f32 v[118:119], v[110:111], v[110:111], v[118:119] op_sel_hi:[0,1,1]
	ds_read_b64 v[26:27], v25 offset:52224
	ds_read_b64 v[28:29], v25 offset:56576
	ds_read_b64 v[30:31], v25 offset:60928
	ds_read_b64 v[102:103], v25 offset:65280
	s_waitcnt lgkmcnt(13)
	v_pk_mul_f32 v[120:121], v[4:5], v[118:119] op_sel:[1,1] op_sel_hi:[0,1] neg_lo:[0,1]
	v_pk_fma_f32 v[4:5], v[4:5], v[118:119], v[120:121] op_sel_hi:[1,0,1]
	v_pk_mul_f32 v[120:121], v[24:25], v[118:119] op_sel:[0,1] op_sel_hi:[0,0] neg_hi:[1,0]
	v_pk_fma_f32 v[118:119], v[110:111], v[118:119], v[120:121] op_sel_hi:[0,1,1]
	s_mov_b32 s35, s30
	s_waitcnt lgkmcnt(12)
	v_pk_mul_f32 v[120:121], v[6:7], v[118:119] op_sel:[1,1] op_sel_hi:[0,1] neg_lo:[0,1]
	v_pk_fma_f32 v[6:7], v[6:7], v[118:119], v[120:121] op_sel_hi:[1,0,1]
	v_pk_mul_f32 v[120:121], v[24:25], v[118:119] op_sel:[0,1] op_sel_hi:[0,0] neg_hi:[1,0]
	v_pk_fma_f32 v[118:119], v[110:111], v[118:119], v[120:121] op_sel_hi:[0,1,1]
	s_mov_b32 s0, s19
	s_waitcnt lgkmcnt(11)
	v_pk_mul_f32 v[120:121], v[8:9], v[118:119] op_sel:[1,1] op_sel_hi:[0,1] neg_lo:[0,1]
	v_pk_fma_f32 v[8:9], v[8:9], v[118:119], v[120:121] op_sel_hi:[1,0,1]
	v_pk_mul_f32 v[120:121], v[24:25], v[118:119] op_sel:[0,1] op_sel_hi:[0,0] neg_hi:[1,0]
	v_pk_fma_f32 v[118:119], v[110:111], v[118:119], v[120:121] op_sel_hi:[0,1,1]
	s_waitcnt lgkmcnt(0)
	v_pk_mul_f32 v[120:121], v[10:11], v[118:119] op_sel:[1,1] op_sel_hi:[0,1] neg_lo:[0,1]
	v_pk_fma_f32 v[10:11], v[10:11], v[118:119], v[120:121] op_sel_hi:[1,0,1]
	v_pk_mul_f32 v[120:121], v[24:25], v[118:119] op_sel:[0,1] op_sel_hi:[0,0] neg_hi:[1,0]
	v_pk_fma_f32 v[118:119], v[110:111], v[118:119], v[120:121] op_sel_hi:[0,1,1]
	s_barrier
	v_pk_mul_f32 v[120:121], v[12:13], v[118:119] op_sel:[1,1] op_sel_hi:[0,1] neg_lo:[0,1]
	v_pk_fma_f32 v[12:13], v[12:13], v[118:119], v[120:121] op_sel_hi:[1,0,1]
	v_pk_mul_f32 v[120:121], v[24:25], v[118:119] op_sel:[0,1] op_sel_hi:[0,0] neg_hi:[1,0]
	v_pk_fma_f32 v[118:119], v[110:111], v[118:119], v[120:121] op_sel_hi:[0,1,1]
	s_nop 0
	v_pk_mul_f32 v[120:121], v[14:15], v[118:119] op_sel:[1,1] op_sel_hi:[0,1] neg_lo:[0,1]
	v_pk_fma_f32 v[14:15], v[14:15], v[118:119], v[120:121] op_sel_hi:[1,0,1]
	v_pk_mul_f32 v[120:121], v[24:25], v[118:119] op_sel:[0,1] op_sel_hi:[0,0] neg_hi:[1,0]
	v_pk_fma_f32 v[118:119], v[110:111], v[118:119], v[120:121] op_sel_hi:[0,1,1]
	s_nop 0
	v_pk_mul_f32 v[120:121], v[16:17], v[118:119] op_sel:[1,1] op_sel_hi:[0,1] neg_lo:[0,1]
	v_pk_fma_f32 v[16:17], v[16:17], v[118:119], v[120:121] op_sel_hi:[1,0,1]
	v_pk_mul_f32 v[120:121], v[24:25], v[118:119] op_sel:[0,1] op_sel_hi:[0,0] neg_hi:[1,0]
	v_pk_fma_f32 v[118:119], v[110:111], v[118:119], v[120:121] op_sel_hi:[0,1,1]
	s_nop 0
	v_pk_mul_f32 v[120:121], v[18:19], v[118:119] op_sel:[1,1] op_sel_hi:[0,1] neg_lo:[0,1]
	v_pk_fma_f32 v[18:19], v[18:19], v[118:119], v[120:121] op_sel_hi:[1,0,1]
	v_pk_mul_f32 v[120:121], v[24:25], v[118:119] op_sel:[0,1] op_sel_hi:[0,0] neg_hi:[1,0]
	v_pk_fma_f32 v[118:119], v[110:111], v[118:119], v[120:121] op_sel_hi:[0,1,1]
	s_nop 0
	v_pk_mul_f32 v[120:121], v[20:21], v[118:119] op_sel:[1,1] op_sel_hi:[0,1] neg_lo:[0,1]
	v_pk_fma_f32 v[20:21], v[20:21], v[118:119], v[120:121] op_sel_hi:[1,0,1]
	v_pk_mul_f32 v[120:121], v[24:25], v[118:119] op_sel:[0,1] op_sel_hi:[0,0] neg_hi:[1,0]
	v_pk_fma_f32 v[118:119], v[110:111], v[118:119], v[120:121] op_sel_hi:[0,1,1]
	s_nop 0
	v_pk_mul_f32 v[120:121], v[22:23], v[118:119] op_sel:[1,1] op_sel_hi:[0,1] neg_lo:[0,1]
	v_pk_fma_f32 v[22:23], v[22:23], v[118:119], v[120:121] op_sel_hi:[1,0,1]
	v_pk_mul_f32 v[120:121], v[24:25], v[118:119] op_sel:[0,1] op_sel_hi:[0,0] neg_hi:[1,0]
	v_pk_fma_f32 v[118:119], v[110:111], v[118:119], v[120:121] op_sel_hi:[0,1,1]
	s_nop 0
	v_pk_mul_f32 v[120:121], v[26:27], v[118:119] op_sel:[1,1] op_sel_hi:[0,1] neg_lo:[0,1]
	v_pk_fma_f32 v[26:27], v[26:27], v[118:119], v[120:121] op_sel_hi:[1,0,1]
	v_pk_mul_f32 v[120:121], v[24:25], v[118:119] op_sel:[0,1] op_sel_hi:[0,0] neg_hi:[1,0]
	v_pk_fma_f32 v[118:119], v[110:111], v[118:119], v[120:121] op_sel_hi:[0,1,1]
	s_nop 0
	v_pk_mul_f32 v[120:121], v[28:29], v[118:119] op_sel:[1,1] op_sel_hi:[0,1] neg_lo:[0,1]
	v_pk_fma_f32 v[28:29], v[28:29], v[118:119], v[120:121] op_sel_hi:[1,0,1]
	v_pk_mul_f32 v[120:121], v[24:25], v[118:119] op_sel:[0,1] op_sel_hi:[0,0] neg_hi:[1,0]
	v_pk_fma_f32 v[118:119], v[110:111], v[118:119], v[120:121] op_sel_hi:[0,1,1]
	v_pk_mul_f32 v[24:25], v[24:25], v[118:119] op_sel:[0,1] op_sel_hi:[0,0] neg_hi:[1,0]
	v_pk_fma_f32 v[24:25], v[110:111], v[118:119], v[24:25] op_sel_hi:[0,1,1]
	v_pk_mul_f32 v[110:111], v[102:103], v[24:25] op_sel:[1,1] op_sel_hi:[0,1] neg_lo:[0,1]
	v_pk_fma_f32 v[24:25], v[102:103], v[24:25], v[110:111] op_sel_hi:[1,0,1]
	v_pk_add_f32 v[102:103], v[0:1], v[16:17]
	v_pk_add_f32 v[0:1], v[0:1], v[16:17] neg_lo:[0,1] neg_hi:[0,1]
	v_pk_add_f32 v[16:17], v[2:3], v[18:19]
	v_pk_add_f32 v[2:3], v[2:3], v[18:19] neg_lo:[0,1] neg_hi:[0,1]
	v_pk_mul_f32 v[120:121], v[30:31], v[118:119] op_sel:[1,1] op_sel_hi:[0,1] neg_lo:[0,1]
	v_pk_mul_f32 v[18:19], v[2:3], s[18:19]
	v_pk_fma_f32 v[30:31], v[30:31], v[118:119], v[120:121] op_sel_hi:[1,0,1]
	v_pk_fma_f32 v[2:3], v[2:3], s[30:31], v[18:19] op_sel:[0,0,1] op_sel_hi:[1,0,0]
	v_pk_add_f32 v[18:19], v[4:5], v[20:21]
	v_pk_add_f32 v[4:5], v[4:5], v[20:21] neg_lo:[0,1] neg_hi:[0,1]
	s_nop 0
	v_pk_mul_f32 v[20:21], v[4:5], s[10:11]
	s_nop 0
	v_pk_fma_f32 v[4:5], v[4:5], s[14:15], v[20:21] op_sel:[0,0,1] op_sel_hi:[1,0,0]
	v_pk_add_f32 v[20:21], v[6:7], v[22:23]
	v_pk_add_f32 v[6:7], v[6:7], v[22:23] neg_lo:[0,1] neg_hi:[0,1]
	s_nop 0
	v_pk_mul_f32 v[22:23], v[6:7], s[34:35]
	s_nop 0
	v_pk_fma_f32 v[6:7], v[6:7], s[0:1], v[22:23] op_sel:[0,0,1] op_sel_hi:[1,0,0]
	v_pk_add_f32 v[22:23], v[8:9], v[26:27]
	v_pk_add_f32 v[8:9], v[8:9], v[26:27] neg_lo:[0,1] neg_hi:[0,1]
	v_pk_add_f32 v[26:27], v[10:11], v[28:29]
	v_pk_add_f32 v[10:11], v[10:11], v[28:29] neg_lo:[0,1] neg_hi:[0,1]
	s_nop 0
	v_pk_mul_f32 v[28:29], v[10:11], s[34:35]
	s_nop 0
	v_pk_fma_f32 v[10:11], v[10:11], s[0:1], v[28:29] op_sel:[0,0,1] op_sel_hi:[1,0,0] neg_lo:[1,0,0] neg_hi:[1,0,0]
	v_pk_add_f32 v[28:29], v[12:13], v[30:31]
	v_pk_add_f32 v[12:13], v[12:13], v[30:31] neg_lo:[0,1] neg_hi:[0,1]
	s_nop 0
	v_pk_mul_f32 v[30:31], v[12:13], s[10:11]
	s_nop 0
	v_pk_fma_f32 v[12:13], v[12:13], s[14:15], v[30:31] op_sel:[0,0,1] op_sel_hi:[1,0,0] neg_lo:[1,0,0] neg_hi:[1,0,0]
	v_pk_add_f32 v[30:31], v[14:15], v[24:25]
	v_pk_add_f32 v[14:15], v[14:15], v[24:25] neg_lo:[0,1] neg_hi:[0,1]
	s_nop 0
	v_pk_mul_f32 v[24:25], v[14:15], s[18:19]
	s_nop 0
	v_pk_fma_f32 v[14:15], v[14:15], s[30:31], v[24:25] op_sel:[0,0,1] op_sel_hi:[1,0,0] neg_lo:[1,0,0] neg_hi:[1,0,0]
	v_pk_add_f32 v[24:25], v[102:103], v[22:23]
	v_pk_add_f32 v[22:23], v[102:103], v[22:23] neg_lo:[0,1] neg_hi:[0,1]
	v_pk_add_f32 v[102:103], v[16:17], v[26:27]
	v_pk_add_f32 v[16:17], v[16:17], v[26:27] neg_lo:[0,1] neg_hi:[0,1]
	s_nop 0
	v_pk_mul_f32 v[26:27], v[16:17], s[10:11]
	s_nop 0
	v_pk_fma_f32 v[16:17], v[16:17], s[14:15], v[26:27] op_sel:[0,0,1] op_sel_hi:[1,0,0]
	v_pk_add_f32 v[26:27], v[18:19], v[28:29]
	v_pk_add_f32 v[18:19], v[18:19], v[28:29] neg_lo:[0,1] neg_hi:[0,1]
	v_pk_add_f32 v[28:29], v[20:21], v[30:31]
	v_pk_add_f32 v[20:21], v[20:21], v[30:31] neg_lo:[0,1] neg_hi:[0,1]
	s_nop 0
	v_pk_mul_f32 v[30:31], v[20:21], s[10:11]
	s_nop 0
	v_pk_fma_f32 v[20:21], v[20:21], s[14:15], v[30:31] op_sel:[0,0,1] op_sel_hi:[1,0,0] neg_lo:[1,0,0] neg_hi:[1,0,0]
	v_pk_add_f32 v[30:31], v[0:1], v[8:9] op_sel:[0,1] op_sel_hi:[1,0] neg_hi:[0,1]
	v_pk_add_f32 v[0:1], v[0:1], v[8:9] op_sel:[0,1] op_sel_hi:[1,0] neg_lo:[0,1]
	v_pk_add_f32 v[8:9], v[2:3], v[10:11]
	v_pk_add_f32 v[2:3], v[2:3], v[10:11] neg_lo:[0,1] neg_hi:[0,1]
	s_nop 0
	v_pk_mul_f32 v[10:11], v[2:3], s[10:11]
	s_nop 0
	v_pk_fma_f32 v[2:3], v[2:3], s[14:15], v[10:11] op_sel:[0,0,1] op_sel_hi:[1,0,0]
	v_pk_add_f32 v[10:11], v[4:5], v[12:13]
	v_pk_add_f32 v[4:5], v[4:5], v[12:13] neg_lo:[0,1] neg_hi:[0,1]
	v_pk_add_f32 v[12:13], v[6:7], v[14:15]
	v_pk_add_f32 v[6:7], v[6:7], v[14:15] neg_lo:[0,1] neg_hi:[0,1]
	s_nop 0
	v_pk_mul_f32 v[14:15], v[6:7], s[10:11]
	s_nop 0
	v_pk_fma_f32 v[6:7], v[6:7], s[14:15], v[14:15] op_sel:[0,0,1] op_sel_hi:[1,0,0] neg_lo:[1,0,0] neg_hi:[1,0,0]
	v_pk_add_f32 v[14:15], v[24:25], v[26:27]
	v_pk_add_f32 v[24:25], v[24:25], v[26:27] neg_lo:[0,1] neg_hi:[0,1]
	v_pk_add_f32 v[26:27], v[102:103], v[28:29]
	v_pk_add_f32 v[28:29], v[102:103], v[28:29] neg_lo:[0,1] neg_hi:[0,1]
	v_pk_add_f32 v[102:103], v[22:23], v[18:19] op_sel:[0,1] op_sel_hi:[1,0] neg_hi:[0,1]
	v_pk_add_f32 v[18:19], v[22:23], v[18:19] op_sel:[0,1] op_sel_hi:[1,0] neg_lo:[0,1]
	v_pk_add_f32 v[22:23], v[16:17], v[20:21]
	v_pk_add_f32 v[16:17], v[16:17], v[20:21] neg_lo:[0,1] neg_hi:[0,1]
	v_pk_add_f32 v[20:21], v[30:31], v[10:11]
	v_pk_add_f32 v[10:11], v[30:31], v[10:11] neg_lo:[0,1] neg_hi:[0,1]
	v_pk_add_f32 v[30:31], v[8:9], v[12:13]
	v_pk_add_f32 v[8:9], v[8:9], v[12:13] neg_lo:[0,1] neg_hi:[0,1]
	v_pk_add_f32 v[12:13], v[0:1], v[4:5] op_sel:[0,1] op_sel_hi:[1,0] neg_hi:[0,1]
	v_pk_add_f32 v[0:1], v[0:1], v[4:5] op_sel:[0,1] op_sel_hi:[1,0] neg_lo:[0,1]
	v_pk_add_f32 v[4:5], v[2:3], v[6:7]
	v_pk_add_f32 v[2:3], v[2:3], v[6:7] neg_lo:[0,1] neg_hi:[0,1]
	s_nop 0
	v_pk_mul_f32 v[2:3], v[2:3], s[22:23]
	v_pk_add_f32 v[6:7], v[14:15], v[26:27]
	v_pk_add_f32 v[14:15], v[14:15], v[26:27] neg_lo:[0,1] neg_hi:[0,1]
	v_pk_add_f32 v[26:27], v[24:25], v[28:29] op_sel:[0,1] op_sel_hi:[1,0] neg_hi:[0,1]
	v_pk_add_f32 v[24:25], v[24:25], v[28:29] op_sel:[0,1] op_sel_hi:[1,0] neg_lo:[0,1]
	v_pk_add_f32 v[28:29], v[102:103], v[22:23]
	v_pk_add_f32 v[22:23], v[102:103], v[22:23] neg_lo:[0,1] neg_hi:[0,1]
	v_pk_add_f32 v[102:103], v[18:19], v[16:17] op_sel:[0,1] op_sel_hi:[1,0] neg_hi:[0,1]
	v_pk_add_f32 v[16:17], v[18:19], v[16:17] op_sel:[0,1] op_sel_hi:[1,0] neg_lo:[0,1]
	v_pk_add_f32 v[18:19], v[20:21], v[30:31]
	v_pk_add_f32 v[20:21], v[20:21], v[30:31] neg_lo:[0,1] neg_hi:[0,1]
	v_pk_add_f32 v[30:31], v[10:11], v[8:9] op_sel:[0,1] op_sel_hi:[1,0] neg_hi:[0,1]
	v_pk_add_f32 v[8:9], v[10:11], v[8:9] op_sel:[0,1] op_sel_hi:[1,0] neg_lo:[0,1]
	v_pk_add_f32 v[10:11], v[12:13], v[4:5]
	v_pk_add_f32 v[4:5], v[12:13], v[4:5] neg_lo:[0,1] neg_hi:[0,1]
	v_pk_add_f32 v[12:13], v[0:1], v[2:3] op_sel:[0,1] op_sel_hi:[1,0]
	v_pk_add_f32 v[0:1], v[0:1], v[2:3] op_sel:[0,1] op_sel_hi:[1,0] neg_lo:[0,1] neg_hi:[0,1]
	v_lshlrev_b32_e32 v2, 4, v47
	v_and_or_b32 v2, v2, s7, v81
	v_ashrrev_i32_e32 v3, 4, v2
	v_lshlrev_b32_e32 v3, 3, v3
	v_lshlrev_b32_e32 v2, 3, v2
	v_add3_u32 v2, 0, v3, v2
	v_add_u32_e32 v3, 0x800, v2
	v_mov_b32_e32 v47, v32
	ds_write2_b64 v2, v[6:7], v[18:19] offset1:34
	ds_write2_b64 v3, v[14:15], v[20:21] offset0:16 offset1:50
	ds_write2_b64 v2, v[26:27], v[30:31] offset0:136 offset1:170
	ds_write2_b64 v3, v[24:25], v[8:9] offset0:152 offset1:186
	ds_write2_b64 v2, v[28:29], v[10:11] offset0:68 offset1:102
	ds_write2_b64 v3, v[22:23], v[4:5] offset0:84 offset1:118
	ds_write2_b64 v2, v[102:103], v[12:13] offset0:204 offset1:238
	ds_write2_b64 v3, v[16:17], v[0:1] offset0:220 offset1:254
	s_waitcnt lgkmcnt(0)
	s_barrier
	s_nop 0
	v_and_b32_e32 v81, 0x1ff, v47
	v_cvt_f32_u32_e32 v24, v81
	v_ashrrev_i32_e32 v0, 4, v47
	v_lshlrev_b32_e32 v0, 3, v0
	v_lshlrev_b32_e32 v1, 3, v47
	v_mul_f32_e32 v110, 0x39000000, v24
	v_sin_f32_e32 v24, v110
	v_cos_f32_e32 v110, v110
	v_add3_u32 v25, 0, v0, v1
	ds_read_b64 v[0:1], v25
	ds_read_b64 v[2:3], v25 offset:4352
	ds_read_b64 v[4:5], v25 offset:8704
	ds_read_b64 v[6:7], v25 offset:13056
	ds_read_b64 v[8:9], v25 offset:17408
	ds_read_b64 v[10:11], v25 offset:21760
	ds_read_b64 v[12:13], v25 offset:26112
	ds_read_b64 v[14:15], v25 offset:30464
	v_xor_b32_e32 v111, 0x80000000, v24
	s_waitcnt lgkmcnt(6)
	v_pk_mul_f32 v[118:119], v[2:3], v[24:25] op_sel:[1,0] op_sel_hi:[0,0] neg_hi:[0,1]
	v_pk_fma_f32 v[2:3], v[2:3], v[110:111], v[118:119] op_sel_hi:[1,0,1]
	v_pk_mul_f32 v[118:119], v[24:25], v[110:111] op_sel:[0,1] op_sel_hi:[0,0] neg_hi:[1,0]
	v_pk_fma_f32 v[118:119], v[110:111], v[110:111], v[118:119] op_sel_hi:[0,1,1]
	ds_read_b64 v[16:17], v25 offset:34816
	ds_read_b64 v[18:19], v25 offset:39168
	ds_read_b64 v[20:21], v25 offset:43520
	ds_read_b64 v[22:23], v25 offset:47872
	s_waitcnt lgkmcnt(9)
	v_pk_mul_f32 v[120:121], v[4:5], v[118:119] op_sel:[1,1] op_sel_hi:[0,1] neg_lo:[0,1]
	v_pk_fma_f32 v[4:5], v[4:5], v[118:119], v[120:121] op_sel_hi:[1,0,1]
	v_pk_mul_f32 v[120:121], v[24:25], v[118:119] op_sel:[0,1] op_sel_hi:[0,0] neg_hi:[1,0]
	v_pk_fma_f32 v[118:119], v[110:111], v[118:119], v[120:121] op_sel_hi:[0,1,1]
	ds_read_b64 v[26:27], v25 offset:52224
	ds_read_b64 v[28:29], v25 offset:56576
	ds_read_b64 v[30:31], v25 offset:60928
	ds_read_b64 v[102:103], v25 offset:65280
	s_waitcnt lgkmcnt(12)
	v_pk_mul_f32 v[120:121], v[6:7], v[118:119] op_sel:[1,1] op_sel_hi:[0,1] neg_lo:[0,1]
	v_pk_fma_f32 v[6:7], v[6:7], v[118:119], v[120:121] op_sel_hi:[1,0,1]
	v_pk_mul_f32 v[120:121], v[24:25], v[118:119] op_sel:[0,1] op_sel_hi:[0,0] neg_hi:[1,0]
	v_pk_fma_f32 v[118:119], v[110:111], v[118:119], v[120:121] op_sel_hi:[0,1,1]
	s_waitcnt lgkmcnt(0)
	v_pk_mul_f32 v[120:121], v[8:9], v[118:119] op_sel:[1,1] op_sel_hi:[0,1] neg_lo:[0,1]
	v_pk_fma_f32 v[8:9], v[8:9], v[118:119], v[120:121] op_sel_hi:[1,0,1]
	v_pk_mul_f32 v[120:121], v[24:25], v[118:119] op_sel:[0,1] op_sel_hi:[0,0] neg_hi:[1,0]
	v_pk_fma_f32 v[118:119], v[110:111], v[118:119], v[120:121] op_sel_hi:[0,1,1]
	s_barrier
	v_pk_mul_f32 v[120:121], v[10:11], v[118:119] op_sel:[1,1] op_sel_hi:[0,1] neg_lo:[0,1]
	v_pk_fma_f32 v[10:11], v[10:11], v[118:119], v[120:121] op_sel_hi:[1,0,1]
	v_pk_mul_f32 v[120:121], v[24:25], v[118:119] op_sel:[0,1] op_sel_hi:[0,0] neg_hi:[1,0]
	v_pk_fma_f32 v[118:119], v[110:111], v[118:119], v[120:121] op_sel_hi:[0,1,1]
	s_nop 0
	v_pk_mul_f32 v[120:121], v[12:13], v[118:119] op_sel:[1,1] op_sel_hi:[0,1] neg_lo:[0,1]
	v_pk_fma_f32 v[12:13], v[12:13], v[118:119], v[120:121] op_sel_hi:[1,0,1]
	v_pk_mul_f32 v[120:121], v[24:25], v[118:119] op_sel:[0,1] op_sel_hi:[0,0] neg_hi:[1,0]
	v_pk_fma_f32 v[118:119], v[110:111], v[118:119], v[120:121] op_sel_hi:[0,1,1]
	s_nop 0
	v_pk_mul_f32 v[120:121], v[14:15], v[118:119] op_sel:[1,1] op_sel_hi:[0,1] neg_lo:[0,1]
	v_pk_fma_f32 v[14:15], v[14:15], v[118:119], v[120:121] op_sel_hi:[1,0,1]
	v_pk_mul_f32 v[120:121], v[24:25], v[118:119] op_sel:[0,1] op_sel_hi:[0,0] neg_hi:[1,0]
	v_pk_fma_f32 v[118:119], v[110:111], v[118:119], v[120:121] op_sel_hi:[0,1,1]
	s_nop 0
	v_pk_mul_f32 v[120:121], v[16:17], v[118:119] op_sel:[1,1] op_sel_hi:[0,1] neg_lo:[0,1]
	v_pk_fma_f32 v[16:17], v[16:17], v[118:119], v[120:121] op_sel_hi:[1,0,1]
	v_pk_mul_f32 v[120:121], v[24:25], v[118:119] op_sel:[0,1] op_sel_hi:[0,0] neg_hi:[1,0]
	v_pk_fma_f32 v[118:119], v[110:111], v[118:119], v[120:121] op_sel_hi:[0,1,1]
	s_nop 0
	v_pk_mul_f32 v[120:121], v[18:19], v[118:119] op_sel:[1,1] op_sel_hi:[0,1] neg_lo:[0,1]
	v_pk_fma_f32 v[18:19], v[18:19], v[118:119], v[120:121] op_sel_hi:[1,0,1]
	v_pk_mul_f32 v[120:121], v[24:25], v[118:119] op_sel:[0,1] op_sel_hi:[0,0] neg_hi:[1,0]
	v_pk_fma_f32 v[118:119], v[110:111], v[118:119], v[120:121] op_sel_hi:[0,1,1]
	s_nop 0
	v_pk_mul_f32 v[120:121], v[20:21], v[118:119] op_sel:[1,1] op_sel_hi:[0,1] neg_lo:[0,1]
	v_pk_fma_f32 v[20:21], v[20:21], v[118:119], v[120:121] op_sel_hi:[1,0,1]
	v_pk_mul_f32 v[120:121], v[24:25], v[118:119] op_sel:[0,1] op_sel_hi:[0,0] neg_hi:[1,0]
	v_pk_fma_f32 v[118:119], v[110:111], v[118:119], v[120:121] op_sel_hi:[0,1,1]
	s_nop 0
	v_pk_mul_f32 v[120:121], v[22:23], v[118:119] op_sel:[1,1] op_sel_hi:[0,1] neg_lo:[0,1]
	v_pk_fma_f32 v[22:23], v[22:23], v[118:119], v[120:121] op_sel_hi:[1,0,1]
	v_pk_mul_f32 v[120:121], v[24:25], v[118:119] op_sel:[0,1] op_sel_hi:[0,0] neg_hi:[1,0]
	v_pk_fma_f32 v[118:119], v[110:111], v[118:119], v[120:121] op_sel_hi:[0,1,1]
	s_nop 0
	v_pk_mul_f32 v[120:121], v[26:27], v[118:119] op_sel:[1,1] op_sel_hi:[0,1] neg_lo:[0,1]
	v_pk_fma_f32 v[26:27], v[26:27], v[118:119], v[120:121] op_sel_hi:[1,0,1]
	v_pk_mul_f32 v[120:121], v[24:25], v[118:119] op_sel:[0,1] op_sel_hi:[0,0] neg_hi:[1,0]
	v_pk_fma_f32 v[118:119], v[110:111], v[118:119], v[120:121] op_sel_hi:[0,1,1]
	s_nop 0
	v_pk_mul_f32 v[120:121], v[28:29], v[118:119] op_sel:[1,1] op_sel_hi:[0,1] neg_lo:[0,1]
	v_pk_fma_f32 v[28:29], v[28:29], v[118:119], v[120:121] op_sel_hi:[1,0,1]
	v_pk_mul_f32 v[120:121], v[24:25], v[118:119] op_sel:[0,1] op_sel_hi:[0,0] neg_hi:[1,0]
	v_pk_fma_f32 v[118:119], v[110:111], v[118:119], v[120:121] op_sel_hi:[0,1,1]
	v_pk_mul_f32 v[24:25], v[24:25], v[118:119] op_sel:[0,1] op_sel_hi:[0,0] neg_hi:[1,0]
	v_pk_fma_f32 v[24:25], v[110:111], v[118:119], v[24:25] op_sel_hi:[0,1,1]
	v_pk_mul_f32 v[110:111], v[102:103], v[24:25] op_sel:[1,1] op_sel_hi:[0,1] neg_lo:[0,1]
	v_pk_fma_f32 v[24:25], v[102:103], v[24:25], v[110:111] op_sel_hi:[1,0,1]
	v_pk_add_f32 v[102:103], v[0:1], v[16:17]
	v_pk_add_f32 v[0:1], v[0:1], v[16:17] neg_lo:[0,1] neg_hi:[0,1]
	v_pk_add_f32 v[16:17], v[2:3], v[18:19]
	v_pk_add_f32 v[2:3], v[2:3], v[18:19] neg_lo:[0,1] neg_hi:[0,1]
	v_pk_mul_f32 v[120:121], v[30:31], v[118:119] op_sel:[1,1] op_sel_hi:[0,1] neg_lo:[0,1]
	v_pk_mul_f32 v[18:19], v[2:3], s[18:19]
	v_pk_fma_f32 v[30:31], v[30:31], v[118:119], v[120:121] op_sel_hi:[1,0,1]
	v_pk_fma_f32 v[2:3], v[2:3], s[30:31], v[18:19] op_sel:[0,0,1] op_sel_hi:[1,0,0]
	v_pk_add_f32 v[18:19], v[4:5], v[20:21]
	v_pk_add_f32 v[4:5], v[4:5], v[20:21] neg_lo:[0,1] neg_hi:[0,1]
	s_nop 0
	v_pk_mul_f32 v[20:21], v[4:5], s[10:11]
	s_nop 0
	v_pk_fma_f32 v[4:5], v[4:5], s[14:15], v[20:21] op_sel:[0,0,1] op_sel_hi:[1,0,0]
	v_pk_add_f32 v[20:21], v[6:7], v[22:23]
	v_pk_add_f32 v[6:7], v[6:7], v[22:23] neg_lo:[0,1] neg_hi:[0,1]
	s_nop 0
	v_pk_mul_f32 v[22:23], v[6:7], s[34:35]
	s_nop 0
	v_pk_fma_f32 v[6:7], v[6:7], s[0:1], v[22:23] op_sel:[0,0,1] op_sel_hi:[1,0,0]
	v_pk_add_f32 v[22:23], v[8:9], v[26:27]
	v_pk_add_f32 v[8:9], v[8:9], v[26:27] neg_lo:[0,1] neg_hi:[0,1]
	v_pk_add_f32 v[26:27], v[10:11], v[28:29]
	v_pk_add_f32 v[10:11], v[10:11], v[28:29] neg_lo:[0,1] neg_hi:[0,1]
	s_nop 0
	v_pk_mul_f32 v[28:29], v[10:11], s[34:35]
	s_nop 0
	v_pk_fma_f32 v[10:11], v[10:11], s[0:1], v[28:29] op_sel:[0,0,1] op_sel_hi:[1,0,0] neg_lo:[1,0,0] neg_hi:[1,0,0]
	v_pk_add_f32 v[28:29], v[12:13], v[30:31]
	v_pk_add_f32 v[12:13], v[12:13], v[30:31] neg_lo:[0,1] neg_hi:[0,1]
	s_nop 0
	v_pk_mul_f32 v[30:31], v[12:13], s[10:11]
	s_nop 0
	v_pk_fma_f32 v[12:13], v[12:13], s[14:15], v[30:31] op_sel:[0,0,1] op_sel_hi:[1,0,0] neg_lo:[1,0,0] neg_hi:[1,0,0]
	v_pk_add_f32 v[30:31], v[14:15], v[24:25]
	v_pk_add_f32 v[14:15], v[14:15], v[24:25] neg_lo:[0,1] neg_hi:[0,1]
	s_nop 0
	v_pk_mul_f32 v[24:25], v[14:15], s[18:19]
	s_nop 0
	v_pk_fma_f32 v[14:15], v[14:15], s[30:31], v[24:25] op_sel:[0,0,1] op_sel_hi:[1,0,0] neg_lo:[1,0,0] neg_hi:[1,0,0]
	v_pk_add_f32 v[24:25], v[102:103], v[22:23]
	v_pk_add_f32 v[22:23], v[102:103], v[22:23] neg_lo:[0,1] neg_hi:[0,1]
	v_pk_add_f32 v[102:103], v[16:17], v[26:27]
	v_pk_add_f32 v[16:17], v[16:17], v[26:27] neg_lo:[0,1] neg_hi:[0,1]
	s_nop 0
	v_pk_mul_f32 v[26:27], v[16:17], s[10:11]
	s_nop 0
	v_pk_fma_f32 v[16:17], v[16:17], s[14:15], v[26:27] op_sel:[0,0,1] op_sel_hi:[1,0,0]
	v_pk_add_f32 v[26:27], v[18:19], v[28:29]
	v_pk_add_f32 v[18:19], v[18:19], v[28:29] neg_lo:[0,1] neg_hi:[0,1]
	v_pk_add_f32 v[28:29], v[20:21], v[30:31]
	v_pk_add_f32 v[20:21], v[20:21], v[30:31] neg_lo:[0,1] neg_hi:[0,1]
	s_nop 0
	v_pk_mul_f32 v[30:31], v[20:21], s[10:11]
	s_nop 0
	v_pk_fma_f32 v[20:21], v[20:21], s[14:15], v[30:31] op_sel:[0,0,1] op_sel_hi:[1,0,0] neg_lo:[1,0,0] neg_hi:[1,0,0]
	v_pk_add_f32 v[30:31], v[0:1], v[8:9] op_sel:[0,1] op_sel_hi:[1,0] neg_hi:[0,1]
	v_pk_add_f32 v[0:1], v[0:1], v[8:9] op_sel:[0,1] op_sel_hi:[1,0] neg_lo:[0,1]
	v_pk_add_f32 v[8:9], v[2:3], v[10:11]
	v_pk_add_f32 v[2:3], v[2:3], v[10:11] neg_lo:[0,1] neg_hi:[0,1]
	s_nop 0
	v_pk_mul_f32 v[10:11], v[2:3], s[10:11]
	s_nop 0
	v_pk_fma_f32 v[2:3], v[2:3], s[14:15], v[10:11] op_sel:[0,0,1] op_sel_hi:[1,0,0]
	v_pk_add_f32 v[10:11], v[4:5], v[12:13]
	v_pk_add_f32 v[4:5], v[4:5], v[12:13] neg_lo:[0,1] neg_hi:[0,1]
	v_pk_add_f32 v[12:13], v[6:7], v[14:15]
	v_pk_add_f32 v[6:7], v[6:7], v[14:15] neg_lo:[0,1] neg_hi:[0,1]
	s_nop 0
	v_pk_mul_f32 v[14:15], v[6:7], s[10:11]
	s_nop 0
	v_pk_fma_f32 v[6:7], v[6:7], s[14:15], v[14:15] op_sel:[0,0,1] op_sel_hi:[1,0,0] neg_lo:[1,0,0] neg_hi:[1,0,0]
	v_pk_add_f32 v[14:15], v[24:25], v[26:27]
	v_pk_add_f32 v[24:25], v[24:25], v[26:27] neg_lo:[0,1] neg_hi:[0,1]
	v_pk_add_f32 v[26:27], v[102:103], v[28:29]
	v_pk_add_f32 v[28:29], v[102:103], v[28:29] neg_lo:[0,1] neg_hi:[0,1]
	v_pk_add_f32 v[102:103], v[22:23], v[18:19] op_sel:[0,1] op_sel_hi:[1,0] neg_hi:[0,1]
	v_pk_add_f32 v[18:19], v[22:23], v[18:19] op_sel:[0,1] op_sel_hi:[1,0] neg_lo:[0,1]
	v_pk_add_f32 v[22:23], v[16:17], v[20:21]
	v_pk_add_f32 v[16:17], v[16:17], v[20:21] neg_lo:[0,1] neg_hi:[0,1]
	v_pk_add_f32 v[20:21], v[30:31], v[10:11]
	v_pk_add_f32 v[10:11], v[30:31], v[10:11] neg_lo:[0,1] neg_hi:[0,1]
	v_pk_add_f32 v[30:31], v[8:9], v[12:13]
	v_pk_add_f32 v[8:9], v[8:9], v[12:13] neg_lo:[0,1] neg_hi:[0,1]
	v_pk_add_f32 v[12:13], v[0:1], v[4:5] op_sel:[0,1] op_sel_hi:[1,0] neg_hi:[0,1]
	v_pk_add_f32 v[0:1], v[0:1], v[4:5] op_sel:[0,1] op_sel_hi:[1,0] neg_lo:[0,1]
	v_pk_add_f32 v[4:5], v[2:3], v[6:7]
	v_pk_add_f32 v[2:3], v[2:3], v[6:7] neg_lo:[0,1] neg_hi:[0,1]
	s_nop 0
	v_pk_mul_f32 v[2:3], v[2:3], s[22:23]
	v_pk_add_f32 v[6:7], v[14:15], v[26:27]
	v_pk_add_f32 v[14:15], v[14:15], v[26:27] neg_lo:[0,1] neg_hi:[0,1]
	v_pk_add_f32 v[26:27], v[24:25], v[28:29] op_sel:[0,1] op_sel_hi:[1,0] neg_hi:[0,1]
	v_pk_add_f32 v[24:25], v[24:25], v[28:29] op_sel:[0,1] op_sel_hi:[1,0] neg_lo:[0,1]
	v_pk_add_f32 v[28:29], v[102:103], v[22:23]
	v_pk_add_f32 v[22:23], v[102:103], v[22:23] neg_lo:[0,1] neg_hi:[0,1]
	v_pk_add_f32 v[102:103], v[18:19], v[16:17] op_sel:[0,1] op_sel_hi:[1,0] neg_hi:[0,1]
	v_pk_add_f32 v[16:17], v[18:19], v[16:17] op_sel:[0,1] op_sel_hi:[1,0] neg_lo:[0,1]
	v_pk_add_f32 v[18:19], v[20:21], v[30:31]
	v_pk_add_f32 v[20:21], v[20:21], v[30:31] neg_lo:[0,1] neg_hi:[0,1]
	v_pk_add_f32 v[30:31], v[10:11], v[8:9] op_sel:[0,1] op_sel_hi:[1,0] neg_hi:[0,1]
	v_pk_add_f32 v[8:9], v[10:11], v[8:9] op_sel:[0,1] op_sel_hi:[1,0] neg_lo:[0,1]
	v_pk_add_f32 v[10:11], v[12:13], v[4:5]
	v_pk_add_f32 v[4:5], v[12:13], v[4:5] neg_lo:[0,1] neg_hi:[0,1]
	v_pk_add_f32 v[12:13], v[0:1], v[2:3] op_sel:[0,1] op_sel_hi:[1,0]
	v_pk_add_f32 v[0:1], v[0:1], v[2:3] op_sel:[0,1] op_sel_hi:[1,0] neg_lo:[0,1] neg_hi:[0,1]
	v_lshlrev_b32_e32 v2, 4, v47
	v_and_or_b32 v2, v2, s15, v81
	v_ashrrev_i32_e32 v3, 4, v2
	v_lshlrev_b32_e32 v3, 3, v3
	v_lshlrev_b32_e32 v2, 3, v2
	v_add3_u32 v2, 0, v3, v2
	ds_write_b64 v2, v[6:7]
	ds_write_b64 v2, v[14:15] offset:34816
	ds_write_b64 v2, v[26:27] offset:17408
	ds_write_b64 v2, v[24:25] offset:52224
	ds_write_b64 v2, v[28:29] offset:8704
	ds_write_b64 v2, v[22:23] offset:43520
	ds_write_b64 v2, v[102:103] offset:26112
	ds_write_b64 v2, v[16:17] offset:60928
	ds_write_b64 v2, v[18:19] offset:4352
	ds_write_b64 v2, v[20:21] offset:39168
	ds_write_b64 v2, v[30:31] offset:21760
	ds_write_b64 v2, v[8:9] offset:56576
	ds_write_b64 v2, v[10:11] offset:13056
	ds_write_b64 v2, v[4:5] offset:47872
	ds_write_b64 v2, v[12:13] offset:30464
	ds_write_b64 v2, v[0:1] offset:65280
	s_waitcnt lgkmcnt(0)
	s_barrier
	s_and_saveexec_b64 s[0:1], s[42:43]
	s_cbranch_execz .LBB0_448
	v_lshl_add_u64 v[2:3], v[78:79], 0, v[172:173]
	s_mov_b64 s[4:5], 0x40000
	v_lshl_add_u64 v[0:1], v[2:3], 0, s[4:5]
	v_add_co_u32_e32 v2, vcc, 0x40000, v2
	v_cmp_ne_u32_e64 s[44:45], 0, v39
	s_nop 0
	v_addc_co_u32_e32 v3, vcc, 0, v3, vcc
	global_load_dwordx4 v[12:15], v[2:3], off
	global_load_dwordx4 v[8:11], v[0:1], off offset:16
	v_mov_b32_e32 v19, 0
	v_mov_b32_e32 v18, 0
	v_mov_b32_e32 v33, 0
	s_and_saveexec_b64 s[4:5], s[44:45]
	s_cbranch_execz .LBB0_441
	global_load_ushort v33, v[0:1], off offset:-2
.LBB0_441:
	s_or_b64 exec, exec, s[4:5]
	v_cmp_ne_u32_e64 s[46:47], 15, v39
	v_mov_b32_e32 v80, 0
	s_and_saveexec_b64 s[4:5], s[46:47]
	s_cbranch_execz .LBB0_443
	global_load_ushort v80, v[0:1], off offset:32
.LBB0_443:
	s_or_b64 exec, exec, s[4:5]
	v_lshl_add_u64 v[0:1], v[78:79], 0, v[172:173]
	s_mov_b64 s[4:5], 0x100000
	v_lshl_add_u64 v[16:17], v[0:1], 0, s[4:5]
	v_add_co_u32_e32 v0, vcc, 0x100000, v0
	v_mov_b32_e32 v47, 0
	s_nop 0
	v_addc_co_u32_e32 v1, vcc, 0, v1, vcc
	global_load_dwordx4 v[4:7], v[0:1], off
	s_nop 0
	global_load_dwordx4 v[0:3], v[16:17], off offset:16
	v_mov_b32_e32 v21, 0
	v_mov_b32_e32 v81, 0
	s_and_saveexec_b64 s[4:5], s[44:45]
	s_cbranch_execz .LBB0_445
	global_load_ushort v81, v[16:17], off offset:-2
.LBB0_445:
	s_or_b64 exec, exec, s[4:5]
	v_mov_b32_e32 v102, 0
	s_and_saveexec_b64 s[4:5], s[46:47]
	s_cbranch_execz .LBB0_447
	global_load_ushort v102, v[16:17], off offset:32
.LBB0_447:
	s_or_b64 exec, exec, s[4:5]
	s_waitcnt vmcnt(0)
	v_lshlrev_b32_e32 v18, 16, v33
	v_lshlrev_b32_e32 v19, 16, v80
	v_lshlrev_b32_e32 v21, 16, v81
	v_lshlrev_b32_e32 v47, 16, v102
	v_lshlrev_b32_e32 v17, 16, v13
	v_and_b32_e32 v13, 0xffff0000, v13
	v_lshlrev_b32_e32 v20, 16, v14
	s_waitcnt vmcnt(2)
	v_lshlrev_b32_e32 v23, 16, v8
	v_and_b32_e32 v8, 0xffff0000, v8
	v_fma_f32 v30, v147, v13, v146
	v_lshlrev_b32_e32 v16, 16, v12
	v_and_b32_e32 v14, 0xffff0000, v14
	v_lshlrev_b32_e32 v25, 16, v9
	v_and_b32_e32 v9, 0xffff0000, v9
	v_fma_f32 v124, v147, v18, v146
	v_fmac_f32_e32 v30, v42, v20
	v_fma_f32 v28, v147, v20, v146
	v_fma_f32 v18, v147, v8, v146
	s_waitcnt vmcnt(1)
	v_and_b32_e32 v102, 0xffff0000, v4
	v_and_b32_e32 v12, 0xffff0000, v12
	v_lshlrev_b32_e32 v22, 16, v15
	v_and_b32_e32 v15, 0xffff0000, v15
	v_lshlrev_b32_e32 v27, 16, v10
	v_fmac_f32_e32 v124, v42, v16
	v_fma_f32 v122, v147, v16, v146
	v_fma_f32 v118, v147, v17, v146
	v_fmac_f32_e32 v30, v43, v14
	v_fmac_f32_e32 v28, v42, v14
	v_fma_f32 v26, v147, v14, v146
	v_fmac_f32_e32 v18, v42, v25
	v_fma_f32 v16, v147, v25, v146
	v_fma_f32 v14, v147, v9, v146
	v_lshlrev_b32_e32 v111, 16, v4
	v_mov_b32_e32 v110, v102
	v_mov_b32_e32 v126, v43
	v_mov_b32_e32 v127, v42
	v_and_b32_e32 v10, 0xffff0000, v10
	v_fmac_f32_e32 v124, v43, v12
	v_fmac_f32_e32 v122, v42, v12
	v_fma_f32 v120, v147, v12, v146
	v_fmac_f32_e32 v118, v42, v13
	v_fmac_f32_e32 v28, v43, v22
	v_fmac_f32_e32 v26, v42, v22
	v_fma_f32 v24, v147, v22, v146
	v_fma_f32 v22, v147, v15, v146
	v_fmac_f32_e32 v18, v43, v9
	v_fmac_f32_e32 v16, v42, v9
	v_fmac_f32_e32 v14, v42, v27
	v_fma_f32 v12, v147, v27, v146
	v_fma_f32 v9, v147, v21, v146
	v_pk_mul_f32 v[128:129], v[126:127], v[110:111]
	v_lshlrev_b32_e32 v29, 16, v11
	v_fmac_f32_e32 v118, v43, v20
	v_fmac_f32_e32 v22, v42, v23
	v_fma_f32 v20, v147, v23, v146
	v_fmac_f32_e32 v14, v43, v10
	v_fmac_f32_e32 v12, v42, v10
	v_fma_f32 v10, v147, v10, v146
	v_and_b32_e32 v103, 16, v4
	v_add_f32_e32 v4, v129, v9
	v_and_b32_e32 v110, 0xffff0000, v5
	v_and_b32_e32 v11, 0xffff0000, v11
	v_fmac_f32_e32 v22, v43, v8
	v_fmac_f32_e32 v20, v42, v8
	v_fmac_f32_e32 v10, v42, v29
	v_fma_f32 v8, v147, v29, v146
	v_add_f32_e32 v125, v128, v4
	v_fma_f32 v9, v147, v111, v146
	v_and_b32_e32 v111, 16, v5
	v_lshlrev_b32_e32 v5, 16, v5
	v_mov_b32_e32 v4, v110
	v_fmac_f32_e32 v10, v43, v11
	v_fmac_f32_e32 v8, v42, v11
	v_fma_f32 v11, v147, v102, v146
	v_pk_mov_b32 v[102:103], v[4:5], v[102:103] op_sel:[1,0]
	v_fmac_f32_e32 v12, v43, v29
	v_pk_mul_f32 v[102:103], v[126:127], v[102:103]
	v_fmac_f32_e32 v16, v43, v27
	v_add_f32_e32 v9, v103, v9
	v_add_f32_e32 v123, v102, v9
	v_pk_mul_f32 v[102:103], v[126:127], v[4:5]
	v_fma_f32 v9, v147, v5, v146
	v_add_f32_e32 v4, v103, v11
	v_add_f32_e32 v121, v102, v4
	v_and_b32_e32 v4, 0xffff0000, v6
	v_lshlrev_b32_e32 v103, 16, v6
	v_mov_b32_e32 v102, v4
	v_fma_f32 v11, v147, v110, v146
	v_pk_mov_b32 v[110:111], v[102:103], v[110:111] op_sel:[1,0]
	v_and_b32_e32 v5, 16, v6
	v_pk_mul_f32 v[110:111], v[126:127], v[110:111]
	v_fmac_f32_e32 v20, v43, v25
	v_add_f32_e32 v6, v111, v9
	v_add_f32_e32 v119, v110, v6
	v_pk_mul_f32 v[110:111], v[126:127], v[102:103]
	v_and_b32_e32 v102, 0xffff0000, v7
	v_add_f32_e32 v6, v111, v11
	v_add_f32_e32 v31, v110, v6
	v_fma_f32 v9, v147, v103, v146
	v_and_b32_e32 v103, 16, v7
	v_lshlrev_b32_e32 v7, 16, v7
	v_mov_b32_e32 v6, v102
	v_fma_f32 v11, v147, v4, v146
	v_pk_mov_b32 v[4:5], v[6:7], v[4:5] op_sel:[1,0]
	v_fmac_f32_e32 v24, v42, v15
	v_pk_mul_f32 v[4:5], v[126:127], v[4:5]
	v_fmac_f32_e32 v24, v43, v23
	v_add_f32_e32 v5, v5, v9
	v_add_f32_e32 v29, v4, v5
	v_pk_mul_f32 v[4:5], v[126:127], v[6:7]
	v_fma_f32 v9, v147, v7, v146
	v_add_f32_e32 v5, v5, v11
	v_add_f32_e32 v27, v4, v5
	s_waitcnt vmcnt(0)
	v_and_b32_e32 v4, 0xffff0000, v0
	v_lshlrev_b32_e32 v7, 16, v0
	v_mov_b32_e32 v6, v4
	v_fma_f32 v11, v147, v102, v146
	v_pk_mov_b32 v[102:103], v[6:7], v[102:103] op_sel:[1,0]
	v_and_b32_e32 v5, 16, v0
	v_pk_mul_f32 v[102:103], v[126:127], v[102:103]
	v_fmac_f32_e32 v8, v43, v19
	v_add_f32_e32 v0, v103, v9
	v_add_f32_e32 v25, v102, v0
	v_pk_mul_f32 v[102:103], v[126:127], v[6:7]
	v_and_b32_e32 v6, 0xffff0000, v1
	v_add_f32_e32 v0, v11, v103
	v_add_f32_e32 v23, v102, v0
	v_fma_f32 v9, v147, v7, v146
	v_and_b32_e32 v7, 16, v1
	v_lshlrev_b32_e32 v1, 16, v1
	v_mov_b32_e32 v0, v6
	v_fma_f32 v11, v147, v4, v146
	v_pk_mov_b32 v[4:5], v[0:1], v[4:5] op_sel:[1,0]
	v_fmac_f32_e32 v122, v43, v17
	v_pk_mul_f32 v[4:5], v[126:127], v[4:5]
	v_fmac_f32_e32 v120, v42, v17
	v_add_f32_e32 v5, v5, v9
	v_add_f32_e32 v21, v4, v5
	v_pk_mul_f32 v[4:5], v[126:127], v[0:1]
	v_fma_f32 v9, v147, v1, v146
	v_add_f32_e32 v0, v5, v11
	v_add_f32_e32 v19, v4, v0
	v_and_b32_e32 v0, 0xffff0000, v2
	v_lshlrev_b32_e32 v5, 16, v2
	v_mov_b32_e32 v4, v0
	v_fma_f32 v11, v147, v6, v146
	v_pk_mov_b32 v[6:7], v[4:5], v[6:7] op_sel:[1,0]
	v_and_b32_e32 v1, 16, v2
	v_pk_mul_f32 v[6:7], v[126:127], v[6:7]
	v_fmac_f32_e32 v26, v43, v15
	v_add_f32_e32 v2, v7, v9
	v_add_f32_e32 v17, v6, v2
	v_pk_mul_f32 v[6:7], v[126:127], v[4:5]
	v_fma_f32 v4, v147, v5, v146
	v_add_f32_e32 v2, v7, v11
	v_add_f32_e32 v15, v6, v2
	v_and_b32_e32 v2, 0xffff0000, v3
	v_lshlrev_b32_e32 v3, 16, v3
	v_fma_f32 v5, v147, v0, v146
	v_pk_mov_b32 v[0:1], v[2:3], v[0:1] op_sel:[1,0]
	v_fmac_f32_e32 v120, v43, v13
	v_pk_mul_f32 v[0:1], v[126:127], v[0:1]
	s_nop 0
	v_add_f32_e32 v1, v1, v4
	v_add_f32_e32 v13, v0, v1
	v_pk_mul_f32 v[0:1], v[126:127], v[2:3]
	v_fma_f32 v4, v147, v3, v146
	v_add_f32_e32 v1, v1, v5
	v_mov_b32_e32 v3, v47
	v_add_f32_e32 v11, v0, v1
	v_pk_mul_f32 v[0:1], v[42:43], v[2:3]
	s_nop 0
	v_add_f32_e32 v0, v0, v4
	v_add_f32_e32 v9, v0, v1

.LBB0_490:
	s_or_b64 exec, exec, s[0:1]
	v_mov_b32_e32 v37, v32
	s_waitcnt lgkmcnt(0)
	s_barrier
	s_mov_b32 s11, s14
	v_and_b32_e32 v47, 31, v37
	v_cvt_f32_ubyte0_e32 v24, v47
	v_mul_f32_e32 v81, 0x3b000000, v24
	v_sin_f32_e32 v24, v81
	v_ashrrev_i32_e32 v0, 4, v37
	v_lshlrev_b32_e32 v0, 3, v0
	v_lshlrev_b32_e32 v1, 3, v37
	v_cos_f32_e32 v84, v81
	v_add3_u32 v25, 0, v0, v1
	ds_read_b64 v[0:1], v25
	ds_read_b64 v[2:3], v25 offset:4352
	ds_read_b64 v[4:5], v25 offset:8704
	ds_read_b64 v[6:7], v25 offset:13056
	ds_read_b64 v[8:9], v25 offset:17408
	ds_read_b64 v[10:11], v25 offset:21760
	ds_read_b64 v[12:13], v25 offset:26112
	ds_read_b64 v[14:15], v25 offset:30464
	ds_read_b64 v[16:17], v25 offset:34816
	ds_read_b64 v[18:19], v25 offset:39168
	ds_read_b64 v[20:21], v25 offset:43520
	ds_read_b64 v[22:23], v25 offset:47872
	v_xor_b32_e32 v85, 0x80000000, v24
	s_waitcnt lgkmcnt(10)
	v_pk_mul_f32 v[118:119], v[2:3], v[24:25] op_sel:[1,0] op_sel_hi:[0,0] neg_hi:[0,1]
	v_pk_fma_f32 v[2:3], v[2:3], v[84:85], v[118:119] op_sel_hi:[1,0,1]
	v_pk_mul_f32 v[118:119], v[24:25], v[84:85] op_sel:[0,1] op_sel_hi:[0,0] neg_hi:[1,0]
	v_pk_fma_f32 v[118:119], v[84:85], v[84:85], v[118:119] op_sel_hi:[0,1,1]
	ds_read_b64 v[26:27], v25 offset:52224
	ds_read_b64 v[28:29], v25 offset:56576
	ds_read_b64 v[30:31], v25 offset:60928
	ds_read_b64 v[82:83], v25 offset:65280
	s_waitcnt lgkmcnt(13)
	v_pk_mul_f32 v[120:121], v[4:5], v[118:119] op_sel:[1,1] op_sel_hi:[0,1] neg_lo:[0,1]
	v_pk_fma_f32 v[4:5], v[4:5], v[118:119], v[120:121] op_sel_hi:[1,0,1]
	v_pk_mul_f32 v[120:121], v[24:25], v[118:119] op_sel:[0,1] op_sel_hi:[0,0] neg_hi:[1,0]
	v_pk_fma_f32 v[118:119], v[84:85], v[118:119], v[120:121] op_sel_hi:[0,1,1]
	s_mov_b32 s35, s30
	s_waitcnt lgkmcnt(12)
	v_pk_mul_f32 v[120:121], v[6:7], v[118:119] op_sel:[1,1] op_sel_hi:[0,1] neg_lo:[0,1]
	v_pk_fma_f32 v[6:7], v[6:7], v[118:119], v[120:121] op_sel_hi:[1,0,1]
	v_pk_mul_f32 v[120:121], v[24:25], v[118:119] op_sel:[0,1] op_sel_hi:[0,0] neg_hi:[1,0]
	v_pk_fma_f32 v[118:119], v[84:85], v[118:119], v[120:121] op_sel_hi:[0,1,1]
	s_mov_b32 s0, s19
	s_waitcnt lgkmcnt(11)
	v_pk_mul_f32 v[120:121], v[8:9], v[118:119] op_sel:[1,1] op_sel_hi:[0,1] neg_lo:[0,1]
	v_pk_fma_f32 v[8:9], v[8:9], v[118:119], v[120:121] op_sel_hi:[1,0,1]
	v_pk_mul_f32 v[120:121], v[24:25], v[118:119] op_sel:[0,1] op_sel_hi:[0,0] neg_hi:[1,0]
	v_pk_fma_f32 v[118:119], v[84:85], v[118:119], v[120:121] op_sel_hi:[0,1,1]
	s_waitcnt lgkmcnt(0)
	v_pk_mul_f32 v[120:121], v[10:11], v[118:119] op_sel:[1,1] op_sel_hi:[0,1] neg_lo:[0,1]
	v_pk_fma_f32 v[10:11], v[10:11], v[118:119], v[120:121] op_sel_hi:[1,0,1]
	v_pk_mul_f32 v[120:121], v[24:25], v[118:119] op_sel:[0,1] op_sel_hi:[0,0] neg_hi:[1,0]
	v_pk_fma_f32 v[118:119], v[84:85], v[118:119], v[120:121] op_sel_hi:[0,1,1]
	s_barrier
	v_pk_mul_f32 v[120:121], v[12:13], v[118:119] op_sel:[1,1] op_sel_hi:[0,1] neg_lo:[0,1]
	v_pk_fma_f32 v[12:13], v[12:13], v[118:119], v[120:121] op_sel_hi:[1,0,1]
	v_pk_mul_f32 v[120:121], v[24:25], v[118:119] op_sel:[0,1] op_sel_hi:[0,0] neg_hi:[1,0]
	v_pk_fma_f32 v[118:119], v[84:85], v[118:119], v[120:121] op_sel_hi:[0,1,1]
	s_nop 0
	v_pk_mul_f32 v[120:121], v[14:15], v[118:119] op_sel:[1,1] op_sel_hi:[0,1] neg_lo:[0,1]
	v_pk_fma_f32 v[14:15], v[14:15], v[118:119], v[120:121] op_sel_hi:[1,0,1]
	v_pk_mul_f32 v[120:121], v[24:25], v[118:119] op_sel:[0,1] op_sel_hi:[0,0] neg_hi:[1,0]
	v_pk_fma_f32 v[118:119], v[84:85], v[118:119], v[120:121] op_sel_hi:[0,1,1]
	s_nop 0
	v_pk_mul_f32 v[120:121], v[16:17], v[118:119] op_sel:[1,1] op_sel_hi:[0,1] neg_lo:[0,1]
	v_pk_fma_f32 v[16:17], v[16:17], v[118:119], v[120:121] op_sel_hi:[1,0,1]
	v_pk_mul_f32 v[120:121], v[24:25], v[118:119] op_sel:[0,1] op_sel_hi:[0,0] neg_hi:[1,0]
	v_pk_fma_f32 v[118:119], v[84:85], v[118:119], v[120:121] op_sel_hi:[0,1,1]
	s_nop 0
	v_pk_mul_f32 v[120:121], v[18:19], v[118:119] op_sel:[1,1] op_sel_hi:[0,1] neg_lo:[0,1]
	v_pk_fma_f32 v[18:19], v[18:19], v[118:119], v[120:121] op_sel_hi:[1,0,1]
	v_pk_mul_f32 v[120:121], v[24:25], v[118:119] op_sel:[0,1] op_sel_hi:[0,0] neg_hi:[1,0]
	v_pk_fma_f32 v[118:119], v[84:85], v[118:119], v[120:121] op_sel_hi:[0,1,1]
	s_nop 0
	v_pk_mul_f32 v[120:121], v[20:21], v[118:119] op_sel:[1,1] op_sel_hi:[0,1] neg_lo:[0,1]
	v_pk_fma_f32 v[20:21], v[20:21], v[118:119], v[120:121] op_sel_hi:[1,0,1]
	v_pk_mul_f32 v[120:121], v[24:25], v[118:119] op_sel:[0,1] op_sel_hi:[0,0] neg_hi:[1,0]
	v_pk_fma_f32 v[118:119], v[84:85], v[118:119], v[120:121] op_sel_hi:[0,1,1]
	s_nop 0
	v_pk_mul_f32 v[120:121], v[22:23], v[118:119] op_sel:[1,1] op_sel_hi:[0,1] neg_lo:[0,1]
	v_pk_fma_f32 v[22:23], v[22:23], v[118:119], v[120:121] op_sel_hi:[1,0,1]
	v_pk_mul_f32 v[120:121], v[24:25], v[118:119] op_sel:[0,1] op_sel_hi:[0,0] neg_hi:[1,0]
	v_pk_fma_f32 v[118:119], v[84:85], v[118:119], v[120:121] op_sel_hi:[0,1,1]
	s_nop 0
	v_pk_mul_f32 v[120:121], v[26:27], v[118:119] op_sel:[1,1] op_sel_hi:[0,1] neg_lo:[0,1]
	v_pk_fma_f32 v[26:27], v[26:27], v[118:119], v[120:121] op_sel_hi:[1,0,1]
	v_pk_mul_f32 v[120:121], v[24:25], v[118:119] op_sel:[0,1] op_sel_hi:[0,0] neg_hi:[1,0]
	v_pk_fma_f32 v[118:119], v[84:85], v[118:119], v[120:121] op_sel_hi:[0,1,1]
	s_nop 0
	v_pk_mul_f32 v[120:121], v[28:29], v[118:119] op_sel:[1,1] op_sel_hi:[0,1] neg_lo:[0,1]
	v_pk_fma_f32 v[28:29], v[28:29], v[118:119], v[120:121] op_sel_hi:[1,0,1]
	v_pk_mul_f32 v[120:121], v[24:25], v[118:119] op_sel:[0,1] op_sel_hi:[0,0] neg_hi:[1,0]
	v_pk_fma_f32 v[118:119], v[84:85], v[118:119], v[120:121] op_sel_hi:[0,1,1]
	v_pk_mul_f32 v[24:25], v[24:25], v[118:119] op_sel:[0,1] op_sel_hi:[0,0] neg_hi:[1,0]
	v_pk_fma_f32 v[24:25], v[84:85], v[118:119], v[24:25] op_sel_hi:[0,1,1]
	v_pk_mul_f32 v[84:85], v[82:83], v[24:25] op_sel:[1,1] op_sel_hi:[0,1] neg_lo:[0,1]
	v_pk_fma_f32 v[24:25], v[82:83], v[24:25], v[84:85] op_sel_hi:[1,0,1]
	v_pk_add_f32 v[82:83], v[0:1], v[16:17]
	v_pk_add_f32 v[0:1], v[0:1], v[16:17] neg_lo:[0,1] neg_hi:[0,1]
	v_pk_add_f32 v[16:17], v[2:3], v[18:19]
	v_pk_add_f32 v[2:3], v[2:3], v[18:19] neg_lo:[0,1] neg_hi:[0,1]
	v_pk_mul_f32 v[120:121], v[30:31], v[118:119] op_sel:[1,1] op_sel_hi:[0,1] neg_lo:[0,1]
	v_pk_mul_f32 v[18:19], v[2:3], s[18:19]
	v_pk_fma_f32 v[30:31], v[30:31], v[118:119], v[120:121] op_sel_hi:[1,0,1]
	v_pk_fma_f32 v[2:3], v[2:3], s[30:31], v[18:19] op_sel:[0,0,1] op_sel_hi:[1,0,0]
	v_pk_add_f32 v[18:19], v[4:5], v[20:21]
	v_pk_add_f32 v[4:5], v[4:5], v[20:21] neg_lo:[0,1] neg_hi:[0,1]
	s_nop 0
	v_pk_mul_f32 v[20:21], v[4:5], s[10:11]
	s_nop 0
	v_pk_fma_f32 v[4:5], v[4:5], s[14:15], v[20:21] op_sel:[0,0,1] op_sel_hi:[1,0,0]
	v_pk_add_f32 v[20:21], v[6:7], v[22:23]
	v_pk_add_f32 v[6:7], v[6:7], v[22:23] neg_lo:[0,1] neg_hi:[0,1]
	s_nop 0
	v_pk_mul_f32 v[22:23], v[6:7], s[34:35]
	s_nop 0
	v_pk_fma_f32 v[6:7], v[6:7], s[0:1], v[22:23] op_sel:[0,0,1] op_sel_hi:[1,0,0]
	v_pk_add_f32 v[22:23], v[8:9], v[26:27]
	v_pk_add_f32 v[8:9], v[8:9], v[26:27] neg_lo:[0,1] neg_hi:[0,1]
	v_pk_add_f32 v[26:27], v[10:11], v[28:29]
	v_pk_add_f32 v[10:11], v[10:11], v[28:29] neg_lo:[0,1] neg_hi:[0,1]
	s_nop 0
	v_pk_mul_f32 v[28:29], v[10:11], s[34:35]
	s_nop 0
	v_pk_fma_f32 v[10:11], v[10:11], s[0:1], v[28:29] op_sel:[0,0,1] op_sel_hi:[1,0,0] neg_lo:[1,0,0] neg_hi:[1,0,0]
	v_pk_add_f32 v[28:29], v[12:13], v[30:31]
	v_pk_add_f32 v[12:13], v[12:13], v[30:31] neg_lo:[0,1] neg_hi:[0,1]
	s_nop 0
	v_pk_mul_f32 v[30:31], v[12:13], s[10:11]
	s_nop 0
	v_pk_fma_f32 v[12:13], v[12:13], s[14:15], v[30:31] op_sel:[0,0,1] op_sel_hi:[1,0,0] neg_lo:[1,0,0] neg_hi:[1,0,0]
	v_pk_add_f32 v[30:31], v[14:15], v[24:25]
	v_pk_add_f32 v[14:15], v[14:15], v[24:25] neg_lo:[0,1] neg_hi:[0,1]
	s_nop 0
	v_pk_mul_f32 v[24:25], v[14:15], s[18:19]
	s_nop 0
	v_pk_fma_f32 v[14:15], v[14:15], s[30:31], v[24:25] op_sel:[0,0,1] op_sel_hi:[1,0,0] neg_lo:[1,0,0] neg_hi:[1,0,0]
	v_pk_add_f32 v[24:25], v[82:83], v[22:23]
	v_pk_add_f32 v[22:23], v[82:83], v[22:23] neg_lo:[0,1] neg_hi:[0,1]
	v_pk_add_f32 v[82:83], v[16:17], v[26:27]
	v_pk_add_f32 v[16:17], v[16:17], v[26:27] neg_lo:[0,1] neg_hi:[0,1]
	s_nop 0
	v_pk_mul_f32 v[26:27], v[16:17], s[10:11]
	s_nop 0
	v_pk_fma_f32 v[16:17], v[16:17], s[14:15], v[26:27] op_sel:[0,0,1] op_sel_hi:[1,0,0]
	v_pk_add_f32 v[26:27], v[18:19], v[28:29]
	v_pk_add_f32 v[18:19], v[18:19], v[28:29] neg_lo:[0,1] neg_hi:[0,1]
	v_pk_add_f32 v[28:29], v[20:21], v[30:31]
	v_pk_add_f32 v[20:21], v[20:21], v[30:31] neg_lo:[0,1] neg_hi:[0,1]
	s_nop 0
	v_pk_mul_f32 v[30:31], v[20:21], s[10:11]
	s_nop 0
	v_pk_fma_f32 v[20:21], v[20:21], s[14:15], v[30:31] op_sel:[0,0,1] op_sel_hi:[1,0,0] neg_lo:[1,0,0] neg_hi:[1,0,0]
	v_pk_add_f32 v[30:31], v[0:1], v[8:9] op_sel:[0,1] op_sel_hi:[1,0] neg_hi:[0,1]
	v_pk_add_f32 v[0:1], v[0:1], v[8:9] op_sel:[0,1] op_sel_hi:[1,0] neg_lo:[0,1]
	v_pk_add_f32 v[8:9], v[2:3], v[10:11]
	v_pk_add_f32 v[2:3], v[2:3], v[10:11] neg_lo:[0,1] neg_hi:[0,1]
	s_nop 0
	v_pk_mul_f32 v[10:11], v[2:3], s[10:11]
	s_nop 0
	v_pk_fma_f32 v[2:3], v[2:3], s[14:15], v[10:11] op_sel:[0,0,1] op_sel_hi:[1,0,0]
	v_pk_add_f32 v[10:11], v[4:5], v[12:13]
	v_pk_add_f32 v[4:5], v[4:5], v[12:13] neg_lo:[0,1] neg_hi:[0,1]
	v_pk_add_f32 v[12:13], v[6:7], v[14:15]
	v_pk_add_f32 v[6:7], v[6:7], v[14:15] neg_lo:[0,1] neg_hi:[0,1]
	s_nop 0
	v_pk_mul_f32 v[14:15], v[6:7], s[10:11]
	s_nop 0
	v_pk_fma_f32 v[6:7], v[6:7], s[14:15], v[14:15] op_sel:[0,0,1] op_sel_hi:[1,0,0] neg_lo:[1,0,0] neg_hi:[1,0,0]
	v_pk_add_f32 v[14:15], v[24:25], v[26:27]
	v_pk_add_f32 v[24:25], v[24:25], v[26:27] neg_lo:[0,1] neg_hi:[0,1]
	v_pk_add_f32 v[26:27], v[82:83], v[28:29]
	v_pk_add_f32 v[28:29], v[82:83], v[28:29] neg_lo:[0,1] neg_hi:[0,1]
	v_pk_add_f32 v[82:83], v[22:23], v[18:19] op_sel:[0,1] op_sel_hi:[1,0] neg_hi:[0,1]
	v_pk_add_f32 v[18:19], v[22:23], v[18:19] op_sel:[0,1] op_sel_hi:[1,0] neg_lo:[0,1]
	v_pk_add_f32 v[22:23], v[16:17], v[20:21]
	v_pk_add_f32 v[16:17], v[16:17], v[20:21] neg_lo:[0,1] neg_hi:[0,1]
	v_pk_add_f32 v[20:21], v[30:31], v[10:11]
	v_pk_add_f32 v[10:11], v[30:31], v[10:11] neg_lo:[0,1] neg_hi:[0,1]
	v_pk_add_f32 v[30:31], v[8:9], v[12:13]
	v_pk_add_f32 v[8:9], v[8:9], v[12:13] neg_lo:[0,1] neg_hi:[0,1]
	v_pk_add_f32 v[12:13], v[0:1], v[4:5] op_sel:[0,1] op_sel_hi:[1,0] neg_hi:[0,1]
	v_pk_add_f32 v[0:1], v[0:1], v[4:5] op_sel:[0,1] op_sel_hi:[1,0] neg_lo:[0,1]
	v_pk_add_f32 v[4:5], v[2:3], v[6:7]
	v_pk_add_f32 v[2:3], v[2:3], v[6:7] neg_lo:[0,1] neg_hi:[0,1]
	s_nop 0
	v_pk_mul_f32 v[2:3], v[2:3], s[22:23]
	v_pk_add_f32 v[6:7], v[14:15], v[26:27]
	v_pk_add_f32 v[14:15], v[14:15], v[26:27] neg_lo:[0,1] neg_hi:[0,1]
	v_pk_add_f32 v[26:27], v[24:25], v[28:29] op_sel:[0,1] op_sel_hi:[1,0] neg_hi:[0,1]
	v_pk_add_f32 v[24:25], v[24:25], v[28:29] op_sel:[0,1] op_sel_hi:[1,0] neg_lo:[0,1]
	v_pk_add_f32 v[28:29], v[82:83], v[22:23]
	v_pk_add_f32 v[22:23], v[82:83], v[22:23] neg_lo:[0,1] neg_hi:[0,1]
	v_pk_add_f32 v[82:83], v[18:19], v[16:17] op_sel:[0,1] op_sel_hi:[1,0] neg_hi:[0,1]
	v_pk_add_f32 v[16:17], v[18:19], v[16:17] op_sel:[0,1] op_sel_hi:[1,0] neg_lo:[0,1]
	v_pk_add_f32 v[18:19], v[20:21], v[30:31]
	v_pk_add_f32 v[20:21], v[20:21], v[30:31] neg_lo:[0,1] neg_hi:[0,1]
	v_pk_add_f32 v[30:31], v[10:11], v[8:9] op_sel:[0,1] op_sel_hi:[1,0] neg_hi:[0,1]
	v_pk_add_f32 v[8:9], v[10:11], v[8:9] op_sel:[0,1] op_sel_hi:[1,0] neg_lo:[0,1]
	v_pk_add_f32 v[10:11], v[12:13], v[4:5]
	v_pk_add_f32 v[4:5], v[12:13], v[4:5] neg_lo:[0,1] neg_hi:[0,1]
	v_pk_add_f32 v[12:13], v[0:1], v[2:3] op_sel:[0,1] op_sel_hi:[1,0]
	v_pk_add_f32 v[0:1], v[0:1], v[2:3] op_sel:[0,1] op_sel_hi:[1,0] neg_lo:[0,1] neg_hi:[0,1]
	v_lshlrev_b32_e32 v2, 4, v37
	v_and_or_b32 v2, v2, s7, v47
	v_ashrrev_i32_e32 v3, 4, v2
	v_lshlrev_b32_e32 v3, 3, v3
	v_lshlrev_b32_e32 v2, 3, v2
	v_add3_u32 v2, 0, v3, v2
	v_add_u32_e32 v3, 0x800, v2
	v_mov_b32_e32 v37, v32
	ds_write2_b64 v2, v[6:7], v[18:19] offset1:34
	ds_write2_b64 v3, v[14:15], v[20:21] offset0:16 offset1:50
	ds_write2_b64 v2, v[26:27], v[30:31] offset0:136 offset1:170
	ds_write2_b64 v3, v[24:25], v[8:9] offset0:152 offset1:186
	ds_write2_b64 v2, v[28:29], v[10:11] offset0:68 offset1:102
	ds_write2_b64 v3, v[22:23], v[4:5] offset0:84 offset1:118
	ds_write2_b64 v2, v[82:83], v[12:13] offset0:204 offset1:238
	ds_write2_b64 v3, v[16:17], v[0:1] offset0:220 offset1:254
	s_waitcnt lgkmcnt(0)
	s_barrier
	s_nop 0
	v_and_b32_e32 v47, 0x1ff, v37
	v_cvt_f32_u32_e32 v24, v47
	v_ashrrev_i32_e32 v0, 4, v37
	v_lshlrev_b32_e32 v0, 3, v0
	v_lshlrev_b32_e32 v1, 3, v37
	v_mul_f32_e32 v81, 0x39000000, v24
	v_sin_f32_e32 v24, v81
	v_cos_f32_e32 v84, v81
	v_add3_u32 v25, 0, v0, v1
	ds_read_b64 v[0:1], v25
	ds_read_b64 v[2:3], v25 offset:4352
	ds_read_b64 v[4:5], v25 offset:8704
	ds_read_b64 v[6:7], v25 offset:13056
	ds_read_b64 v[8:9], v25 offset:17408
	ds_read_b64 v[10:11], v25 offset:21760
	ds_read_b64 v[12:13], v25 offset:26112
	ds_read_b64 v[14:15], v25 offset:30464
	v_xor_b32_e32 v85, 0x80000000, v24
	s_waitcnt lgkmcnt(6)
	v_pk_mul_f32 v[118:119], v[2:3], v[24:25] op_sel:[1,0] op_sel_hi:[0,0] neg_hi:[0,1]
	v_pk_fma_f32 v[2:3], v[2:3], v[84:85], v[118:119] op_sel_hi:[1,0,1]
	v_pk_mul_f32 v[118:119], v[24:25], v[84:85] op_sel:[0,1] op_sel_hi:[0,0] neg_hi:[1,0]
	v_pk_fma_f32 v[118:119], v[84:85], v[84:85], v[118:119] op_sel_hi:[0,1,1]
	ds_read_b64 v[16:17], v25 offset:34816
	ds_read_b64 v[18:19], v25 offset:39168
	ds_read_b64 v[20:21], v25 offset:43520
	ds_read_b64 v[22:23], v25 offset:47872
	s_waitcnt lgkmcnt(9)
	v_pk_mul_f32 v[120:121], v[4:5], v[118:119] op_sel:[1,1] op_sel_hi:[0,1] neg_lo:[0,1]
	v_pk_fma_f32 v[4:5], v[4:5], v[118:119], v[120:121] op_sel_hi:[1,0,1]
	v_pk_mul_f32 v[120:121], v[24:25], v[118:119] op_sel:[0,1] op_sel_hi:[0,0] neg_hi:[1,0]
	v_pk_fma_f32 v[118:119], v[84:85], v[118:119], v[120:121] op_sel_hi:[0,1,1]
	ds_read_b64 v[26:27], v25 offset:52224
	ds_read_b64 v[28:29], v25 offset:56576
	ds_read_b64 v[30:31], v25 offset:60928
	ds_read_b64 v[82:83], v25 offset:65280
	s_waitcnt lgkmcnt(12)
	v_pk_mul_f32 v[120:121], v[6:7], v[118:119] op_sel:[1,1] op_sel_hi:[0,1] neg_lo:[0,1]
	v_pk_fma_f32 v[6:7], v[6:7], v[118:119], v[120:121] op_sel_hi:[1,0,1]
	v_pk_mul_f32 v[120:121], v[24:25], v[118:119] op_sel:[0,1] op_sel_hi:[0,0] neg_hi:[1,0]
	v_pk_fma_f32 v[118:119], v[84:85], v[118:119], v[120:121] op_sel_hi:[0,1,1]
	s_waitcnt lgkmcnt(0)
	v_pk_mul_f32 v[120:121], v[8:9], v[118:119] op_sel:[1,1] op_sel_hi:[0,1] neg_lo:[0,1]
	v_pk_fma_f32 v[8:9], v[8:9], v[118:119], v[120:121] op_sel_hi:[1,0,1]
	v_pk_mul_f32 v[120:121], v[24:25], v[118:119] op_sel:[0,1] op_sel_hi:[0,0] neg_hi:[1,0]
	v_pk_fma_f32 v[118:119], v[84:85], v[118:119], v[120:121] op_sel_hi:[0,1,1]
	s_barrier
	v_pk_mul_f32 v[120:121], v[10:11], v[118:119] op_sel:[1,1] op_sel_hi:[0,1] neg_lo:[0,1]
	v_pk_fma_f32 v[10:11], v[10:11], v[118:119], v[120:121] op_sel_hi:[1,0,1]
	v_pk_mul_f32 v[120:121], v[24:25], v[118:119] op_sel:[0,1] op_sel_hi:[0,0] neg_hi:[1,0]
	v_pk_fma_f32 v[118:119], v[84:85], v[118:119], v[120:121] op_sel_hi:[0,1,1]
	s_nop 0
	v_pk_mul_f32 v[120:121], v[12:13], v[118:119] op_sel:[1,1] op_sel_hi:[0,1] neg_lo:[0,1]
	v_pk_fma_f32 v[12:13], v[12:13], v[118:119], v[120:121] op_sel_hi:[1,0,1]
	v_pk_mul_f32 v[120:121], v[24:25], v[118:119] op_sel:[0,1] op_sel_hi:[0,0] neg_hi:[1,0]
	v_pk_fma_f32 v[118:119], v[84:85], v[118:119], v[120:121] op_sel_hi:[0,1,1]
	s_nop 0
	v_pk_mul_f32 v[120:121], v[14:15], v[118:119] op_sel:[1,1] op_sel_hi:[0,1] neg_lo:[0,1]
	v_pk_fma_f32 v[14:15], v[14:15], v[118:119], v[120:121] op_sel_hi:[1,0,1]
	v_pk_mul_f32 v[120:121], v[24:25], v[118:119] op_sel:[0,1] op_sel_hi:[0,0] neg_hi:[1,0]
	v_pk_fma_f32 v[118:119], v[84:85], v[118:119], v[120:121] op_sel_hi:[0,1,1]
	s_nop 0
	v_pk_mul_f32 v[120:121], v[16:17], v[118:119] op_sel:[1,1] op_sel_hi:[0,1] neg_lo:[0,1]
	v_pk_fma_f32 v[16:17], v[16:17], v[118:119], v[120:121] op_sel_hi:[1,0,1]
	v_pk_mul_f32 v[120:121], v[24:25], v[118:119] op_sel:[0,1] op_sel_hi:[0,0] neg_hi:[1,0]
	v_pk_fma_f32 v[118:119], v[84:85], v[118:119], v[120:121] op_sel_hi:[0,1,1]
	s_nop 0
	v_pk_mul_f32 v[120:121], v[18:19], v[118:119] op_sel:[1,1] op_sel_hi:[0,1] neg_lo:[0,1]
	v_pk_fma_f32 v[18:19], v[18:19], v[118:119], v[120:121] op_sel_hi:[1,0,1]
	v_pk_mul_f32 v[120:121], v[24:25], v[118:119] op_sel:[0,1] op_sel_hi:[0,0] neg_hi:[1,0]
	v_pk_fma_f32 v[118:119], v[84:85], v[118:119], v[120:121] op_sel_hi:[0,1,1]
	s_nop 0
	v_pk_mul_f32 v[120:121], v[20:21], v[118:119] op_sel:[1,1] op_sel_hi:[0,1] neg_lo:[0,1]
	v_pk_fma_f32 v[20:21], v[20:21], v[118:119], v[120:121] op_sel_hi:[1,0,1]
	v_pk_mul_f32 v[120:121], v[24:25], v[118:119] op_sel:[0,1] op_sel_hi:[0,0] neg_hi:[1,0]
	v_pk_fma_f32 v[118:119], v[84:85], v[118:119], v[120:121] op_sel_hi:[0,1,1]
	s_nop 0
	v_pk_mul_f32 v[120:121], v[22:23], v[118:119] op_sel:[1,1] op_sel_hi:[0,1] neg_lo:[0,1]
	v_pk_fma_f32 v[22:23], v[22:23], v[118:119], v[120:121] op_sel_hi:[1,0,1]
	v_pk_mul_f32 v[120:121], v[24:25], v[118:119] op_sel:[0,1] op_sel_hi:[0,0] neg_hi:[1,0]
	v_pk_fma_f32 v[118:119], v[84:85], v[118:119], v[120:121] op_sel_hi:[0,1,1]
	s_nop 0
	v_pk_mul_f32 v[120:121], v[26:27], v[118:119] op_sel:[1,1] op_sel_hi:[0,1] neg_lo:[0,1]
	v_pk_fma_f32 v[26:27], v[26:27], v[118:119], v[120:121] op_sel_hi:[1,0,1]
	v_pk_mul_f32 v[120:121], v[24:25], v[118:119] op_sel:[0,1] op_sel_hi:[0,0] neg_hi:[1,0]
	v_pk_fma_f32 v[118:119], v[84:85], v[118:119], v[120:121] op_sel_hi:[0,1,1]
	s_nop 0
	v_pk_mul_f32 v[120:121], v[28:29], v[118:119] op_sel:[1,1] op_sel_hi:[0,1] neg_lo:[0,1]
	v_pk_fma_f32 v[28:29], v[28:29], v[118:119], v[120:121] op_sel_hi:[1,0,1]
	v_pk_mul_f32 v[120:121], v[24:25], v[118:119] op_sel:[0,1] op_sel_hi:[0,0] neg_hi:[1,0]
	v_pk_fma_f32 v[118:119], v[84:85], v[118:119], v[120:121] op_sel_hi:[0,1,1]
	v_pk_mul_f32 v[24:25], v[24:25], v[118:119] op_sel:[0,1] op_sel_hi:[0,0] neg_hi:[1,0]
	v_pk_fma_f32 v[24:25], v[84:85], v[118:119], v[24:25] op_sel_hi:[0,1,1]
	v_pk_mul_f32 v[84:85], v[82:83], v[24:25] op_sel:[1,1] op_sel_hi:[0,1] neg_lo:[0,1]
	v_pk_fma_f32 v[24:25], v[82:83], v[24:25], v[84:85] op_sel_hi:[1,0,1]
	v_pk_add_f32 v[82:83], v[0:1], v[16:17]
	v_pk_add_f32 v[0:1], v[0:1], v[16:17] neg_lo:[0,1] neg_hi:[0,1]
	v_pk_add_f32 v[16:17], v[2:3], v[18:19]
	v_pk_add_f32 v[2:3], v[2:3], v[18:19] neg_lo:[0,1] neg_hi:[0,1]
	v_pk_mul_f32 v[120:121], v[30:31], v[118:119] op_sel:[1,1] op_sel_hi:[0,1] neg_lo:[0,1]
	v_pk_mul_f32 v[18:19], v[2:3], s[18:19]
	v_pk_fma_f32 v[30:31], v[30:31], v[118:119], v[120:121] op_sel_hi:[1,0,1]
	v_pk_fma_f32 v[2:3], v[2:3], s[30:31], v[18:19] op_sel:[0,0,1] op_sel_hi:[1,0,0]
	v_pk_add_f32 v[18:19], v[4:5], v[20:21]
	v_pk_add_f32 v[4:5], v[4:5], v[20:21] neg_lo:[0,1] neg_hi:[0,1]
	s_nop 0
	v_pk_mul_f32 v[20:21], v[4:5], s[10:11]
	s_nop 0
	v_pk_fma_f32 v[4:5], v[4:5], s[14:15], v[20:21] op_sel:[0,0,1] op_sel_hi:[1,0,0]
	v_pk_add_f32 v[20:21], v[6:7], v[22:23]
	v_pk_add_f32 v[6:7], v[6:7], v[22:23] neg_lo:[0,1] neg_hi:[0,1]
	s_nop 0
	v_pk_mul_f32 v[22:23], v[6:7], s[34:35]
	s_nop 0
	v_pk_fma_f32 v[6:7], v[6:7], s[0:1], v[22:23] op_sel:[0,0,1] op_sel_hi:[1,0,0]
	v_pk_add_f32 v[22:23], v[8:9], v[26:27]
	v_pk_add_f32 v[8:9], v[8:9], v[26:27] neg_lo:[0,1] neg_hi:[0,1]
	v_pk_add_f32 v[26:27], v[10:11], v[28:29]
	v_pk_add_f32 v[10:11], v[10:11], v[28:29] neg_lo:[0,1] neg_hi:[0,1]
	s_nop 0
	v_pk_mul_f32 v[28:29], v[10:11], s[34:35]
	s_nop 0
	v_pk_fma_f32 v[10:11], v[10:11], s[0:1], v[28:29] op_sel:[0,0,1] op_sel_hi:[1,0,0] neg_lo:[1,0,0] neg_hi:[1,0,0]
	v_pk_add_f32 v[28:29], v[12:13], v[30:31]
	v_pk_add_f32 v[12:13], v[12:13], v[30:31] neg_lo:[0,1] neg_hi:[0,1]
	s_nop 0
	v_pk_mul_f32 v[30:31], v[12:13], s[10:11]
	s_nop 0
	v_pk_fma_f32 v[12:13], v[12:13], s[14:15], v[30:31] op_sel:[0,0,1] op_sel_hi:[1,0,0] neg_lo:[1,0,0] neg_hi:[1,0,0]
	v_pk_add_f32 v[30:31], v[14:15], v[24:25]
	v_pk_add_f32 v[14:15], v[14:15], v[24:25] neg_lo:[0,1] neg_hi:[0,1]
	s_nop 0
	v_pk_mul_f32 v[24:25], v[14:15], s[18:19]
	s_nop 0
	v_pk_fma_f32 v[14:15], v[14:15], s[30:31], v[24:25] op_sel:[0,0,1] op_sel_hi:[1,0,0] neg_lo:[1,0,0] neg_hi:[1,0,0]
	v_pk_add_f32 v[24:25], v[82:83], v[22:23]
	v_pk_add_f32 v[22:23], v[82:83], v[22:23] neg_lo:[0,1] neg_hi:[0,1]
	v_pk_add_f32 v[82:83], v[16:17], v[26:27]
	v_pk_add_f32 v[16:17], v[16:17], v[26:27] neg_lo:[0,1] neg_hi:[0,1]
	s_nop 0
	v_pk_mul_f32 v[26:27], v[16:17], s[10:11]
	s_nop 0
	v_pk_fma_f32 v[16:17], v[16:17], s[14:15], v[26:27] op_sel:[0,0,1] op_sel_hi:[1,0,0]
	v_pk_add_f32 v[26:27], v[18:19], v[28:29]
	v_pk_add_f32 v[18:19], v[18:19], v[28:29] neg_lo:[0,1] neg_hi:[0,1]
	v_pk_add_f32 v[28:29], v[20:21], v[30:31]
	v_pk_add_f32 v[20:21], v[20:21], v[30:31] neg_lo:[0,1] neg_hi:[0,1]
	s_nop 0
	v_pk_mul_f32 v[30:31], v[20:21], s[10:11]
	s_nop 0
	v_pk_fma_f32 v[20:21], v[20:21], s[14:15], v[30:31] op_sel:[0,0,1] op_sel_hi:[1,0,0] neg_lo:[1,0,0] neg_hi:[1,0,0]
	v_pk_add_f32 v[30:31], v[0:1], v[8:9] op_sel:[0,1] op_sel_hi:[1,0] neg_hi:[0,1]
	v_pk_add_f32 v[0:1], v[0:1], v[8:9] op_sel:[0,1] op_sel_hi:[1,0] neg_lo:[0,1]
	v_pk_add_f32 v[8:9], v[2:3], v[10:11]
	v_pk_add_f32 v[2:3], v[2:3], v[10:11] neg_lo:[0,1] neg_hi:[0,1]
	s_nop 0
	v_pk_mul_f32 v[10:11], v[2:3], s[10:11]
	s_nop 0
	v_pk_fma_f32 v[2:3], v[2:3], s[14:15], v[10:11] op_sel:[0,0,1] op_sel_hi:[1,0,0]
	v_pk_add_f32 v[10:11], v[4:5], v[12:13]
	v_pk_add_f32 v[4:5], v[4:5], v[12:13] neg_lo:[0,1] neg_hi:[0,1]
	v_pk_add_f32 v[12:13], v[6:7], v[14:15]
	v_pk_add_f32 v[6:7], v[6:7], v[14:15] neg_lo:[0,1] neg_hi:[0,1]
	s_nop 0
	v_pk_mul_f32 v[14:15], v[6:7], s[10:11]
	s_nop 0
	v_pk_fma_f32 v[6:7], v[6:7], s[14:15], v[14:15] op_sel:[0,0,1] op_sel_hi:[1,0,0] neg_lo:[1,0,0] neg_hi:[1,0,0]
	v_pk_add_f32 v[14:15], v[24:25], v[26:27]
	v_pk_add_f32 v[24:25], v[24:25], v[26:27] neg_lo:[0,1] neg_hi:[0,1]
	v_pk_add_f32 v[26:27], v[82:83], v[28:29]
	v_pk_add_f32 v[28:29], v[82:83], v[28:29] neg_lo:[0,1] neg_hi:[0,1]
	v_pk_add_f32 v[82:83], v[22:23], v[18:19] op_sel:[0,1] op_sel_hi:[1,0] neg_hi:[0,1]
	v_pk_add_f32 v[18:19], v[22:23], v[18:19] op_sel:[0,1] op_sel_hi:[1,0] neg_lo:[0,1]
	v_pk_add_f32 v[22:23], v[16:17], v[20:21]
	v_pk_add_f32 v[16:17], v[16:17], v[20:21] neg_lo:[0,1] neg_hi:[0,1]
	v_pk_add_f32 v[20:21], v[30:31], v[10:11]
	v_pk_add_f32 v[10:11], v[30:31], v[10:11] neg_lo:[0,1] neg_hi:[0,1]
	v_pk_add_f32 v[30:31], v[8:9], v[12:13]
	v_pk_add_f32 v[8:9], v[8:9], v[12:13] neg_lo:[0,1] neg_hi:[0,1]
	v_pk_add_f32 v[12:13], v[0:1], v[4:5] op_sel:[0,1] op_sel_hi:[1,0] neg_hi:[0,1]
	v_pk_add_f32 v[0:1], v[0:1], v[4:5] op_sel:[0,1] op_sel_hi:[1,0] neg_lo:[0,1]
	v_pk_add_f32 v[4:5], v[2:3], v[6:7]
	v_pk_add_f32 v[2:3], v[2:3], v[6:7] neg_lo:[0,1] neg_hi:[0,1]
	s_nop 0
	v_pk_mul_f32 v[2:3], v[2:3], s[22:23]
	v_pk_add_f32 v[6:7], v[14:15], v[26:27]
	v_pk_add_f32 v[14:15], v[14:15], v[26:27] neg_lo:[0,1] neg_hi:[0,1]
	v_pk_add_f32 v[26:27], v[24:25], v[28:29] op_sel:[0,1] op_sel_hi:[1,0] neg_hi:[0,1]
	v_pk_add_f32 v[24:25], v[24:25], v[28:29] op_sel:[0,1] op_sel_hi:[1,0] neg_lo:[0,1]
	v_pk_add_f32 v[28:29], v[82:83], v[22:23]
	v_pk_add_f32 v[22:23], v[82:83], v[22:23] neg_lo:[0,1] neg_hi:[0,1]
	v_pk_add_f32 v[82:83], v[18:19], v[16:17] op_sel:[0,1] op_sel_hi:[1,0] neg_hi:[0,1]
	v_pk_add_f32 v[16:17], v[18:19], v[16:17] op_sel:[0,1] op_sel_hi:[1,0] neg_lo:[0,1]
	v_pk_add_f32 v[18:19], v[20:21], v[30:31]
	v_pk_add_f32 v[20:21], v[20:21], v[30:31] neg_lo:[0,1] neg_hi:[0,1]
	v_pk_add_f32 v[30:31], v[10:11], v[8:9] op_sel:[0,1] op_sel_hi:[1,0] neg_hi:[0,1]
	v_pk_add_f32 v[8:9], v[10:11], v[8:9] op_sel:[0,1] op_sel_hi:[1,0] neg_lo:[0,1]
	v_pk_add_f32 v[10:11], v[12:13], v[4:5]
	v_pk_add_f32 v[4:5], v[12:13], v[4:5] neg_lo:[0,1] neg_hi:[0,1]
	v_pk_add_f32 v[12:13], v[0:1], v[2:3] op_sel:[0,1] op_sel_hi:[1,0]
	v_pk_add_f32 v[0:1], v[0:1], v[2:3] op_sel:[0,1] op_sel_hi:[1,0] neg_lo:[0,1] neg_hi:[0,1]
	v_lshlrev_b32_e32 v2, 4, v37
	v_and_or_b32 v2, v2, s15, v47
	v_ashrrev_i32_e32 v3, 4, v2
	v_lshlrev_b32_e32 v3, 3, v3
	v_lshlrev_b32_e32 v2, 3, v2
	v_add3_u32 v2, 0, v3, v2
	ds_write_b64 v2, v[6:7]
	ds_write_b64 v2, v[14:15] offset:34816
	ds_write_b64 v2, v[26:27] offset:17408
	ds_write_b64 v2, v[24:25] offset:52224
	ds_write_b64 v2, v[28:29] offset:8704
	ds_write_b64 v2, v[22:23] offset:43520
	ds_write_b64 v2, v[82:83] offset:26112
	ds_write_b64 v2, v[16:17] offset:60928
	ds_write_b64 v2, v[18:19] offset:4352
	ds_write_b64 v2, v[20:21] offset:39168
	ds_write_b64 v2, v[30:31] offset:21760
	ds_write_b64 v2, v[8:9] offset:56576
	ds_write_b64 v2, v[10:11] offset:13056
	ds_write_b64 v2, v[4:5] offset:47872
	ds_write_b64 v2, v[12:13] offset:30464
	ds_write_b64 v2, v[0:1] offset:65280
	s_waitcnt lgkmcnt(0)
	s_barrier
	s_and_saveexec_b64 s[0:1], s[42:43]
	s_cbranch_execz .LBB0_500
	v_lshl_add_u64 v[2:3], v[78:79], 0, v[172:173]
	s_mov_b64 s[4:5], 0x80000
	v_lshl_add_u64 v[0:1], v[2:3], 0, s[4:5]
	v_add_co_u32_e32 v2, vcc, 0x80000, v2
	v_cmp_ne_u32_e64 s[42:43], 0, v39
	s_nop 0
	v_addc_co_u32_e32 v3, vcc, 0, v3, vcc
	global_load_dwordx4 v[12:15], v[2:3], off
	global_load_dwordx4 v[8:11], v[0:1], off offset:16
	v_mov_b32_e32 v19, 0
	v_mov_b32_e32 v21, 0
	v_mov_b32_e32 v33, 0
	s_and_saveexec_b64 s[4:5], s[42:43]
	s_cbranch_execz .LBB0_493
	global_load_ushort v33, v[0:1], off offset:-2
.LBB0_493:
	s_or_b64 exec, exec, s[4:5]
	v_cmp_ne_u32_e64 s[44:45], 15, v39
	v_mov_b32_e32 v37, 0
	s_and_saveexec_b64 s[4:5], s[44:45]
	s_cbranch_execz .LBB0_495
	global_load_ushort v37, v[0:1], off offset:32
.LBB0_495:
	s_or_b64 exec, exec, s[4:5]
	v_lshl_add_u64 v[0:1], v[78:79], 0, v[172:173]
	s_mov_b64 s[4:5], 0x140000
	v_lshl_add_u64 v[16:17], v[0:1], 0, s[4:5]
	v_add_co_u32_e32 v0, vcc, 0x140000, v0
	v_mov_b32_e32 v18, 0
	s_nop 0
	v_addc_co_u32_e32 v1, vcc, 0, v1, vcc
	global_load_dwordx4 v[4:7], v[0:1], off
	s_nop 0
	global_load_dwordx4 v[0:3], v[16:17], off offset:16
	v_mov_b32_e32 v20, 0
	v_mov_b32_e32 v47, 0
	s_and_saveexec_b64 s[4:5], s[42:43]
	s_cbranch_execz .LBB0_497
	global_load_ushort v47, v[16:17], off offset:-2
.LBB0_497:
	s_or_b64 exec, exec, s[4:5]
	v_mov_b32_e32 v80, 0
	s_and_saveexec_b64 s[4:5], s[44:45]
	s_cbranch_execz .LBB0_499
	global_load_ushort v80, v[16:17], off offset:32
.LBB0_499:
	s_or_b64 exec, exec, s[4:5]
	s_waitcnt vmcnt(0)
	v_lshlrev_b32_e32 v21, 16, v33
	v_lshlrev_b32_e32 v19, 16, v37
	v_lshlrev_b32_e32 v20, 16, v47
	v_lshlrev_b32_e32 v18, 16, v80
	v_lshlrev_b32_e32 v16, 16, v12
	v_fma_f32 v21, v148, v21, v149
	v_and_b32_e32 v12, 0xffff0000, v12
	v_fmac_f32_e32 v21, v45, v16
	v_fma_f32 v16, v148, v16, v149
	v_lshlrev_b32_e32 v17, 16, v13
	v_fmac_f32_e32 v16, v45, v12
	v_fma_f32 v28, v148, v12, v149
	v_and_b32_e32 v13, 0xffff0000, v13
	v_fmac_f32_e32 v16, v44, v17
	v_fmac_f32_e32 v28, v45, v17
	v_fma_f32 v17, v148, v17, v149
	v_lshlrev_b32_e32 v22, 16, v14
	v_fmac_f32_e32 v17, v45, v13
	v_fma_f32 v29, v148, v13, v149
	v_and_b32_e32 v14, 0xffff0000, v14
	v_fmac_f32_e32 v17, v44, v22
	v_fmac_f32_e32 v29, v45, v22
	v_fma_f32 v22, v148, v22, v149
	v_lshlrev_b32_e32 v23, 16, v15
	v_fmac_f32_e32 v22, v45, v14
	v_fma_f32 v30, v148, v14, v149
	v_and_b32_e32 v15, 0xffff0000, v15
	v_fmac_f32_e32 v22, v44, v23
	v_fmac_f32_e32 v30, v45, v23
	v_fma_f32 v23, v148, v23, v149
	s_waitcnt vmcnt(2)
	v_lshlrev_b32_e32 v24, 16, v8
	v_fmac_f32_e32 v23, v45, v15
	v_fma_f32 v31, v148, v15, v149
	v_and_b32_e32 v8, 0xffff0000, v8
	v_fmac_f32_e32 v23, v44, v24
	v_fmac_f32_e32 v31, v45, v24
	v_fma_f32 v24, v148, v24, v149
	v_lshlrev_b32_e32 v25, 16, v9
	v_fmac_f32_e32 v24, v45, v8
	v_fma_f32 v37, v148, v8, v149
	v_and_b32_e32 v9, 0xffff0000, v9
	v_fmac_f32_e32 v24, v44, v25
	v_fmac_f32_e32 v37, v45, v25
	v_fma_f32 v25, v148, v25, v149
	v_lshlrev_b32_e32 v26, 16, v10
	v_fmac_f32_e32 v25, v45, v9
	v_fma_f32 v39, v148, v9, v149
	v_and_b32_e32 v10, 0xffff0000, v10
	v_lshlrev_b32_e32 v27, 16, v11
	v_fmac_f32_e32 v25, v44, v26
	v_fmac_f32_e32 v39, v45, v26
	v_fma_f32 v26, v148, v26, v149
	v_and_b32_e32 v11, 0xffff0000, v11
	v_fmac_f32_e32 v31, v44, v8
	v_fmac_f32_e32 v37, v44, v9
	v_fmac_f32_e32 v39, v44, v10
	v_fmac_f32_e32 v26, v45, v10
	v_fma_f32 v8, v148, v10, v149
	v_fma_f32 v9, v148, v27, v149
	s_waitcnt vmcnt(1)
	v_and_b32_e32 v10, 0xffff0000, v4
	v_fmac_f32_e32 v21, v44, v12
	v_fmac_f32_e32 v28, v44, v13
	v_fmac_f32_e32 v9, v45, v11
	v_lshlrev_b32_e32 v13, 16, v4
	v_mov_b32_e32 v12, v10
	v_fmac_f32_e32 v29, v44, v14
	v_fmac_f32_e32 v30, v44, v15
	v_fmac_f32_e32 v8, v45, v27
	v_fmac_f32_e32 v9, v44, v19
	v_fma_f32 v19, v148, v20, v149
	v_pk_mul_f32 v[14:15], v[44:45], v[12:13]
	v_fmac_f32_e32 v8, v44, v11
	v_and_b32_e32 v11, 16, v4
	v_add_f32_e32 v4, v15, v19
	v_and_b32_e32 v12, 0xffff0000, v5
	v_add_f32_e32 v14, v14, v4
	v_fma_f32 v15, v148, v13, v149
	v_and_b32_e32 v13, 16, v5
	v_lshlrev_b32_e32 v5, 16, v5
	v_mov_b32_e32 v4, v12
	v_fma_f32 v19, v148, v10, v149
	v_pk_mov_b32 v[10:11], v[4:5], v[10:11] op_sel:[1,0]
	v_fmac_f32_e32 v26, v44, v27
	v_pk_mul_f32 v[10:11], v[44:45], v[10:11]
	v_fma_f32 v27, v148, v12, v149
	v_add_f32_e32 v11, v11, v15
	v_add_f32_e32 v15, v10, v11
	v_pk_mul_f32 v[10:11], v[44:45], v[4:5]
	v_fma_f32 v20, v148, v5, v149
	v_add_f32_e32 v4, v11, v19
	v_add_f32_e32 v19, v10, v4
	v_and_b32_e32 v4, 0xffff0000, v6
	v_lshlrev_b32_e32 v11, 16, v6
	v_mov_b32_e32 v10, v4
	v_pk_mov_b32 v[12:13], v[10:11], v[12:13] op_sel:[1,0]
	v_and_b32_e32 v5, 16, v6
	v_pk_mul_f32 v[12:13], v[44:45], v[12:13]
	s_mov_b64 s[4:5], 0xc0000
	v_add_f32_e32 v6, v13, v20
	v_add_f32_e32 v20, v12, v6
	v_pk_mul_f32 v[12:13], v[44:45], v[10:11]
	v_and_b32_e32 v10, 0xffff0000, v7
	v_add_f32_e32 v6, v13, v27
	v_add_f32_e32 v12, v12, v6
	v_fma_f32 v13, v148, v11, v149
	v_and_b32_e32 v11, 16, v7
	v_lshlrev_b32_e32 v7, 16, v7
	v_mov_b32_e32 v6, v10
	v_fma_f32 v27, v148, v4, v149
	v_pk_mov_b32 v[4:5], v[6:7], v[4:5] op_sel:[1,0]
	v_fma_f32 v47, v148, v7, v149
	v_pk_mul_f32 v[4:5], v[44:45], v[4:5]
	v_fma_f32 v81, v148, v10, v149
	v_add_f32_e32 v5, v5, v13
	v_add_f32_e32 v13, v4, v5
	v_pk_mul_f32 v[4:5], v[44:45], v[6:7]
	s_waitcnt vmcnt(0)
	v_lshlrev_b32_e32 v7, 16, v0
	v_add_f32_e32 v5, v5, v27
	v_add_f32_e32 v27, v4, v5
	v_and_b32_e32 v4, 0xffff0000, v0
	v_mov_b32_e32 v6, v4
	v_pk_mov_b32 v[10:11], v[6:7], v[10:11] op_sel:[1,0]
	v_and_b32_e32 v5, 16, v0
	v_pk_mul_f32 v[10:11], v[44:45], v[10:11]
	s_nop 0
	v_add_f32_e32 v0, v11, v47
	v_add_f32_e32 v47, v10, v0
	v_pk_mul_f32 v[10:11], v[44:45], v[6:7]
	v_and_b32_e32 v6, 0xffff0000, v1
	v_add_f32_e32 v0, v81, v11
	v_add_f32_e32 v10, v10, v0
	v_fma_f32 v11, v148, v7, v149
	v_and_b32_e32 v7, 16, v1
	v_lshlrev_b32_e32 v1, 16, v1
	v_mov_b32_e32 v0, v6
	v_fma_f32 v81, v148, v4, v149
	v_pk_mov_b32 v[4:5], v[0:1], v[4:5] op_sel:[1,0]
	v_fma_f32 v83, v148, v6, v149
	v_pk_mul_f32 v[4:5], v[44:45], v[4:5]
	v_fma_f32 v82, v148, v1, v149
	v_add_f32_e32 v5, v5, v11
	v_add_f32_e32 v11, v4, v5
	v_pk_mul_f32 v[4:5], v[44:45], v[0:1]
	v_and_b32_e32 v1, 16, v2
	v_add_f32_e32 v0, v5, v81
	v_add_f32_e32 v81, v4, v0
	v_and_b32_e32 v0, 0xffff0000, v2
	v_lshlrev_b32_e32 v5, 16, v2
	v_mov_b32_e32 v4, v0
	v_pk_mov_b32 v[6:7], v[4:5], v[6:7] op_sel:[1,0]
	s_nop 0
	v_pk_mul_f32 v[6:7], v[44:45], v[6:7]
	s_nop 0
	v_add_f32_e32 v2, v7, v82
	v_add_f32_e32 v82, v6, v2
	v_pk_mul_f32 v[6:7], v[44:45], v[4:5]
	v_fma_f32 v5, v148, v5, v149
	v_add_f32_e32 v2, v7, v83
	v_add_f32_e32 v4, v6, v2
	v_and_b32_e32 v2, 0xffff0000, v3
	v_lshlrev_b32_e32 v3, 16, v3
	v_fma_f32 v6, v148, v0, v149
	v_pk_mov_b32 v[0:1], v[2:3], v[0:1] op_sel:[1,0]
	v_fma_f32 v7, v148, v3, v149
	v_pk_mul_f32 v[0:1], v[44:45], v[0:1]
	s_nop 0
	v_add_f32_e32 v1, v1, v5
	v_add_f32_e32 v5, v0, v1
	v_pk_mul_f32 v[0:1], v[44:45], v[2:3]
	v_mov_b32_e32 v3, v18
	v_add_f32_e32 v1, v1, v6
	v_add_f32_e32 v6, v0, v1
	v_mov_b32_e32 v0, v45
	v_mov_b32_e32 v1, v44
	v_pk_mul_f32 v[0:1], v[0:1], v[2:3]
	s_nop 0
	v_add_f32_e32 v0, v0, v7
	v_add_f32_e32 v7, v0, v1
	ds_read2_b64 v[0:3], v152 offset1:1
	s_waitcnt lgkmcnt(0)
	v_fma_f32 v0, v150, v110, v0
	v_mul_f32_e32 v18, v21, v0
	v_fma_f32 v0, v150, v111, -v1
	v_mul_f32_e32 v14, v14, v0
	v_fma_f32 v0, v150, v102, v2
	v_mul_f32_e32 v16, v16, v0
	v_fma_f32 v0, v150, v103, -v3
	v_mul_f32_e32 v15, v15, v0
	ds_read2_b64 v[0:3], v152 offset0:2 offset1:3
	s_waitcnt lgkmcnt(0)
	v_fma_f32 v0, v150, v94, v0
	v_mul_f32_e32 v21, v28, v0
	v_fma_f32 v0, v150, v95, -v1
	v_mul_f32_e32 v19, v19, v0
	v_fma_f32 v0, v150, v88, v2
	v_mul_f32_e32 v17, v17, v0
	v_fma_f32 v0, v150, v89, -v3
	v_mul_f32_e32 v20, v20, v0
	ds_read2_b64 v[0:3], v152 offset0:4 offset1:5
	s_waitcnt lgkmcnt(0)
	v_fma_f32 v0, v150, v112, v0
	v_mul_f32_e32 v28, v29, v0
	v_fma_f32 v0, v150, v113, -v1
	v_mul_f32_e32 v12, v12, v0
	v_fma_f32 v0, v150, v104, v2
	v_mul_f32_e32 v22, v22, v0
	v_fma_f32 v0, v150, v105, -v3
	v_mul_f32_e32 v13, v13, v0
	ds_read2_b64 v[0:3], v152 offset0:6 offset1:7
	s_waitcnt lgkmcnt(0)
	v_fma_f32 v0, v150, v96, v0
	v_mul_f32_e32 v29, v30, v0
	v_fma_f32 v0, v150, v97, -v1
	v_mul_f32_e32 v27, v27, v0
	v_fma_f32 v0, v150, v90, v2
	v_mul_f32_e32 v23, v23, v0
	v_fma_f32 v0, v150, v91, -v3
	v_mul_f32_e32 v30, v47, v0
	ds_read2_b64 v[0:3], v152 offset0:8 offset1:9
	s_waitcnt lgkmcnt(0)
	v_fma_f32 v0, v150, v114, v0
	v_mul_f32_e32 v31, v31, v0
	v_fma_f32 v0, v150, v115, -v1
	v_mul_f32_e32 v47, v10, v0
	v_fma_f32 v0, v150, v106, v2
	v_mul_f32_e32 v10, v24, v0
	v_fma_f32 v0, v150, v107, -v3
	v_mul_f32_e32 v24, v11, v0
	ds_read2_b64 v[0:3], v152 offset0:10 offset1:11
	s_waitcnt lgkmcnt(0)
	v_fma_f32 v0, v150, v98, v0
	v_mul_f32_e32 v11, v37, v0
	v_fma_f32 v0, v150, v99, -v1
	v_mul_f32_e32 v37, v81, v0
	v_fma_f32 v0, v150, v92, v2
	v_mul_f32_e32 v25, v25, v0
	v_fma_f32 v0, v150, v93, -v3
	v_mul_f32_e32 v81, v82, v0
	ds_read2_b64 v[0:3], v152 offset0:12 offset1:13
	s_waitcnt lgkmcnt(0)
	v_fma_f32 v0, v150, v116, v0
	v_mul_f32_e32 v39, v39, v0
	v_fma_f32 v0, v150, v117, -v1
	v_mul_f32_e32 v82, v4, v0
	v_fma_f32 v0, v150, v108, v2
	v_mul_f32_e32 v26, v26, v0
	v_fma_f32 v0, v150, v109, -v3
	v_mul_f32_e32 v83, v5, v0
	ds_read2_b64 v[0:3], v152 offset0:14 offset1:15
	s_waitcnt lgkmcnt(0)
	v_fma_f32 v0, v150, v100, v0
	v_mul_f32_e32 v8, v8, v0
	v_fma_f32 v0, v150, v101, -v1
	v_mul_f32_e32 v84, v6, v0
	v_fma_f32 v0, v150, v86, v2
	v_mul_f32_e32 v9, v9, v0
	v_fma_f32 v0, v150, v87, -v3
	v_mul_f32_e32 v85, v7, v0
	v_cvt_pk_bf16_f32 v0, v18, v16
	v_cvt_pk_bf16_f32 v1, v21, v17
	v_cvt_pk_bf16_f32 v2, v28, v22
	v_cvt_pk_bf16_f32 v3, v29, v23
	v_lshl_add_u64 v[16:17], v[78:79], 0, v[172:173]
	v_cvt_pk_bf16_f32 v4, v31, v10
	v_cvt_pk_bf16_f32 v5, v11, v25
	v_cvt_pk_bf16_f32 v6, v39, v26
	v_cvt_pk_bf16_f32 v7, v8, v9
	v_cvt_pk_bf16_f32 v8, v14, v15
	v_cvt_pk_bf16_f32 v9, v19, v20
	v_cvt_pk_bf16_f32 v10, v12, v13
	v_cvt_pk_bf16_f32 v11, v27, v30
	v_cvt_pk_bf16_f32 v12, v47, v24
	v_cvt_pk_bf16_f32 v13, v37, v81
	v_cvt_pk_bf16_f32 v14, v82, v83
	v_cvt_pk_bf16_f32 v15, v84, v85
	global_store_dwordx4 v[16:17], v[0:3], off
	global_store_dwordx4 v[16:17], v[4:7], off offset:16
	s_nop 0
	v_add_co_u32_e32 v2, vcc, 0xc0000, v16
	v_lshl_add_u64 v[0:1], v[16:17], 0, s[4:5]
	s_nop 0
	v_addc_co_u32_e32 v3, vcc, 0, v17, vcc
	global_store_dwordx4 v[2:3], v[8:11], off
	global_store_dwordx4 v[0:1], v[12:15], off offset:16
.LBB0_500:
	s_or_b64 exec, exec, s[0:1]
	s_lshl_b32 s0, s57, 14
	s_add_u32 s4, s60, s0
	s_addc_u32 s5, s61, 0
	s_add_u32 s0, s4, 0xcbb2000
	s_addc_u32 s1, s5, 0
	s_add_u32 s38, s4, 0xd3b2000
	s_addc_u32 s39, s5, 0
	s_add_u32 s28, s4, 0xdbb2000
	s_addc_u32 s29, s5, 0
	s_add_u32 s42, s4, 0xe3b2000
	s_movk_i32 s4, 0xfff
	s_addc_u32 s43, s5, 0
	v_cmp_lt_i32_e32 vcc, s4, v32
	s_barrier
	v_lshlrev_b32_e32 v188, 2, v32
	v_add_u32_e32 v189, 0x1000, v188
	v_add_u32_e32 v190, 0x2000, v188
	v_add_u32_e32 v191, 0x3000, v188
	v_sub_u32_e32 v192, 0x800, v188
	v_add_u32_e32 v193, 0x1000, v192
	v_add_u32_e32 v194, 0x2000, v192
	v_add_u32_e32 v195, 0x3000, v192
	global_load_dword v214, v188, s[0:1]
	global_load_dword v215, v188, s[28:29]
	global_load_dword v216, v188, s[0:1] offset:2048
	global_load_dword v217, v188, s[28:29] offset:2048
	global_load_dword v218, v189, s[0:1]
	global_load_dword v219, v189, s[28:29]
	global_load_dword v220, v189, s[0:1] offset:2048
	global_load_dword v221, v189, s[28:29] offset:2048
	global_load_dword v222, v190, s[0:1]
	global_load_dword v223, v190, s[28:29]
	global_load_dword v224, v190, s[0:1] offset:2048
	global_load_dword v225, v190, s[28:29] offset:2048
	global_load_dword v226, v191, s[0:1]
	global_load_dword v227, v191, s[28:29]
	global_load_dword v228, v191, s[0:1] offset:2048
	global_load_dword v229, v191, s[28:29] offset:2048
	global_load_dword v230, v192, s[38:39]
	global_load_dword v231, v192, s[42:43]
	global_load_dword v232, v192, s[38:39] offset:2048
	global_load_dword v233, v192, s[42:43] offset:2048
	global_load_dword v234, v193, s[38:39]
	global_load_dword v235, v193, s[42:43]
	global_load_dword v236, v193, s[38:39] offset:2048
	global_load_dword v237, v193, s[42:43] offset:2048
	global_load_dword v238, v194, s[38:39]
	global_load_dword v239, v194, s[42:43]
	global_load_dword v182, v194, s[38:39] offset:2048
	global_load_dword v183, v194, s[42:43] offset:2048
	global_load_dword v184, v195, s[38:39]
	global_load_dword v185, v195, s[42:43]
	v_mov_b32_e32 v186, 0
	v_mov_b32_e32 v187, 0
	v_cmp_ne_u32_e32 vcc, 0, v32
	s_and_saveexec_b64 s[44:45], vcc
	global_load_dword v186, v195, s[38:39] offset:2048
	global_load_dword v187, v195, s[42:43] offset:2048
	s_mov_b64 exec, s[44:45]
	s_waitcnt vmcnt(30)
	ds_write_b64 v35, v[214:215]
	s_waitcnt vmcnt(28)
	ds_write_b64 v35, v[216:217] offset:4352
	s_waitcnt vmcnt(26)
	ds_write_b64 v35, v[218:219] offset:8704
	s_waitcnt vmcnt(24)
	ds_write_b64 v35, v[220:221] offset:13056
	s_waitcnt vmcnt(22)
	ds_write_b64 v35, v[222:223] offset:17408
	s_waitcnt vmcnt(20)
	ds_write_b64 v35, v[224:225] offset:21760
	s_waitcnt vmcnt(18)
	ds_write_b64 v35, v[226:227] offset:26112
	s_waitcnt vmcnt(16)
	ds_write_b64 v35, v[228:229] offset:30464
	s_waitcnt vmcnt(14)
	ds_write_b64 v35, v[230:231] offset:65280
	s_waitcnt vmcnt(12)
	ds_write_b64 v35, v[232:233] offset:60928
	s_waitcnt vmcnt(10)
	ds_write_b64 v35, v[234:235] offset:56576
	s_waitcnt vmcnt(8)
	ds_write_b64 v35, v[236:237] offset:52224
	s_waitcnt vmcnt(6)
	ds_write_b64 v35, v[238:239] offset:47872
	s_waitcnt vmcnt(4)
	ds_write_b64 v35, v[182:183] offset:43520
	s_waitcnt vmcnt(2)
	ds_write_b64 v35, v[184:185] offset:39168
	s_waitcnt vmcnt(0)
	ds_write_b64 v35, v[186:187] offset:34816
	s_waitcnt lgkmcnt(0)
	s_barrier
	s_and_saveexec_b64 s[0:1], s[40:41]
	s_xor_b64 s[0:1], exec, s[0:1]
	s_cbranch_execz .LBB0_598
	v_add3_u32 v33, s26, v41, v157
	ds_read_b64 v[0:1], v33 offset:2176
	ds_read_b64 v[2:3], v33 offset:4352
	ds_read_b64 v[4:5], v33 offset:6528
	ds_read_b64 v[6:7], v33 offset:8704
	ds_read_b64 v[8:9], v33 offset:10880
	ds_read_b64 v[10:11], v33 offset:13056
	ds_read_b64 v[12:13], v33 offset:15232
	ds_read_b64 v[14:15], v33 offset:17408
	ds_read_b64 v[16:17], v33 offset:19584
	ds_read_b64 v[18:19], v33 offset:21760
	ds_read_b64 v[20:21], v33 offset:23936
	ds_read_b64 v[22:23], v33 offset:26112
	ds_read_b64 v[24:25], v33 offset:34816
	ds_read_b64 v[26:27], v33 offset:36992
	ds_read_b64 v[28:29], v33 offset:39168
	ds_read_b64 v[30:31], v33 offset:41344
	ds_read_b64 v[48:49], v33 offset:43520
	ds_read_b64 v[50:51], v33 offset:45696
	ds_read_b64 v[52:53], v33 offset:47872
	ds_read_b64 v[54:55], v33 offset:50048
	ds_read_b64 v[56:57], v33 offset:52224
	ds_read_b64 v[58:59], v33 offset:54400
	ds_read_b64 v[60:61], v33 offset:56576
	ds_read_b64 v[62:63], v33 offset:58752
	ds_read_b64 v[64:65], v33
	ds_read_b64 v[66:67], v33 offset:60928
	ds_read_b64 v[68:69], v33 offset:63104
	ds_read_b64 v[70:71], v33 offset:65280
	s_mov_b32 s11, s14
	s_waitcnt lgkmcnt(3)
	v_pk_add_f32 v[80:81], v[64:65], v[24:25]
	v_pk_add_f32 v[24:25], v[64:65], v[24:25] neg_lo:[0,1] neg_hi:[0,1]
	v_pk_add_f32 v[64:65], v[0:1], v[26:27]
	v_pk_add_f32 v[0:1], v[0:1], v[26:27] neg_lo:[0,1] neg_hi:[0,1]
	s_mov_b32 s13, s86
	v_pk_mul_f32 v[26:27], v[0:1], s[16:17]
	s_mov_b32 s4, s21
	v_pk_fma_f32 v[0:1], v[0:1], s[6:7], v[26:27] op_sel:[0,0,1] op_sel_hi:[1,0,0]
	v_pk_add_f32 v[26:27], v[2:3], v[28:29]
	v_pk_add_f32 v[2:3], v[2:3], v[28:29] neg_lo:[0,1] neg_hi:[0,1]
	s_mov_b32 s35, s30
	v_pk_mul_f32 v[28:29], v[2:3], s[18:19]
	s_mov_b32 s8, s19
	v_pk_fma_f32 v[2:3], v[2:3], s[30:31], v[28:29] op_sel:[0,0,1] op_sel_hi:[1,0,0]
	v_pk_add_f32 v[28:29], v[4:5], v[30:31]
	v_pk_add_f32 v[4:5], v[4:5], v[30:31] neg_lo:[0,1] neg_hi:[0,1]
	s_mov_b32 s77, s6
	v_pk_mul_f32 v[30:31], v[4:5], s[20:21]
	s_mov_b32 s28, s17
	v_pk_fma_f32 v[4:5], v[4:5], s[86:87], v[30:31] op_sel:[0,0,1] op_sel_hi:[1,0,0]
	v_pk_add_f32 v[30:31], v[6:7], v[48:49]
	v_pk_add_f32 v[6:7], v[6:7], v[48:49] neg_lo:[0,1] neg_hi:[0,1]
	v_add_u32_e32 v35, 0x10780, v33
	v_pk_mul_f32 v[48:49], v[6:7], s[10:11]
	ds_read_b64 v[72:73], v33 offset:28288
	ds_read_b64 v[74:75], v33 offset:30464
	ds_read_b64 v[76:77], v33 offset:32640
	ds_read_b64 v[78:79], v35
	v_pk_fma_f32 v[6:7], v[6:7], s[14:15], v[48:49] op_sel:[0,0,1] op_sel_hi:[1,0,0]
	v_pk_add_f32 v[48:49], v[8:9], v[50:51]
	v_pk_add_f32 v[8:9], v[8:9], v[50:51] neg_lo:[0,1] neg_hi:[0,1]
	s_nop 0
	v_pk_mul_f32 v[50:51], v[8:9], s[12:13]
	s_nop 0
	v_pk_fma_f32 v[8:9], v[8:9], s[4:5], v[50:51] op_sel:[0,0,1] op_sel_hi:[1,0,0]
	v_pk_add_f32 v[50:51], v[10:11], v[52:53]
	v_pk_add_f32 v[10:11], v[10:11], v[52:53] neg_lo:[0,1] neg_hi:[0,1]
	s_nop 0
	v_pk_mul_f32 v[52:53], v[10:11], s[34:35]
	s_nop 0
	v_pk_fma_f32 v[10:11], v[10:11], s[8:9], v[52:53] op_sel:[0,0,1] op_sel_hi:[1,0,0]
	v_pk_add_f32 v[52:53], v[12:13], v[54:55]
	v_pk_add_f32 v[12:13], v[12:13], v[54:55] neg_lo:[0,1] neg_hi:[0,1]
	s_nop 0
	v_pk_mul_f32 v[54:55], v[12:13], s[76:77]
	s_nop 0
	v_pk_fma_f32 v[12:13], v[12:13], s[28:29], v[54:55] op_sel:[0,0,1] op_sel_hi:[1,0,0]
	v_pk_add_f32 v[54:55], v[14:15], v[56:57]
	v_pk_add_f32 v[14:15], v[14:15], v[56:57] neg_lo:[0,1] neg_hi:[0,1]
	v_pk_add_f32 v[56:57], v[16:17], v[58:59]
	v_pk_add_f32 v[16:17], v[16:17], v[58:59] neg_lo:[0,1] neg_hi:[0,1]
	s_nop 0
	v_pk_mul_f32 v[58:59], v[16:17], s[76:77]
	s_nop 0
	v_pk_fma_f32 v[16:17], v[16:17], s[28:29], v[58:59] op_sel:[0,0,1] op_sel_hi:[1,0,0] neg_lo:[1,0,0] neg_hi:[1,0,0]
	v_pk_add_f32 v[58:59], v[18:19], v[60:61]
	v_pk_add_f32 v[18:19], v[18:19], v[60:61] neg_lo:[0,1] neg_hi:[0,1]
	s_nop 0
	v_pk_mul_f32 v[60:61], v[18:19], s[34:35]
	s_nop 0
	v_pk_fma_f32 v[18:19], v[18:19], s[8:9], v[60:61] op_sel:[0,0,1] op_sel_hi:[1,0,0] neg_lo:[1,0,0] neg_hi:[1,0,0]
	v_pk_add_f32 v[60:61], v[20:21], v[62:63]
	v_pk_add_f32 v[20:21], v[20:21], v[62:63] neg_lo:[0,1] neg_hi:[0,1]
	s_nop 0
	v_pk_mul_f32 v[62:63], v[20:21], s[12:13]
	s_nop 0
	v_pk_fma_f32 v[20:21], v[20:21], s[4:5], v[62:63] op_sel:[0,0,1] op_sel_hi:[1,0,0] neg_lo:[1,0,0] neg_hi:[1,0,0]
	s_waitcnt lgkmcnt(6)
	v_pk_add_f32 v[62:63], v[22:23], v[66:67]
	v_pk_add_f32 v[22:23], v[22:23], v[66:67] neg_lo:[0,1] neg_hi:[0,1]
	s_nop 0
	v_pk_mul_f32 v[66:67], v[22:23], s[10:11]
	s_nop 0
	v_pk_fma_f32 v[22:23], v[22:23], s[14:15], v[66:67] op_sel:[0,0,1] op_sel_hi:[1,0,0] neg_lo:[1,0,0] neg_hi:[1,0,0]
	s_waitcnt lgkmcnt(3)
	v_pk_add_f32 v[66:67], v[72:73], v[68:69]
	v_pk_add_f32 v[68:69], v[72:73], v[68:69] neg_lo:[0,1] neg_hi:[0,1]
	s_nop 0
	v_pk_mul_f32 v[72:73], v[68:69], s[20:21]
	s_nop 0
	v_pk_fma_f32 v[68:69], v[68:69], s[86:87], v[72:73] op_sel:[0,0,1] op_sel_hi:[1,0,0] neg_lo:[1,0,0] neg_hi:[1,0,0]
	s_waitcnt lgkmcnt(2)
	v_pk_add_f32 v[72:73], v[74:75], v[70:71]
	v_pk_add_f32 v[70:71], v[74:75], v[70:71] neg_lo:[0,1] neg_hi:[0,1]
	s_nop 0
	v_pk_mul_f32 v[74:75], v[70:71], s[18:19]
	s_nop 0
	v_pk_fma_f32 v[70:71], v[70:71], s[30:31], v[74:75] op_sel:[0,0,1] op_sel_hi:[1,0,0] neg_lo:[1,0,0] neg_hi:[1,0,0]
	s_waitcnt lgkmcnt(0)
	v_pk_add_f32 v[74:75], v[76:77], v[78:79]
	v_pk_add_f32 v[76:77], v[76:77], v[78:79] neg_lo:[0,1] neg_hi:[0,1]
	s_nop 0
	v_pk_mul_f32 v[78:79], v[76:77], s[16:17]
	s_nop 0
	v_pk_fma_f32 v[76:77], v[76:77], s[6:7], v[78:79] op_sel:[0,0,1] op_sel_hi:[1,0,0] neg_lo:[1,0,0] neg_hi:[1,0,0]
	v_pk_add_f32 v[78:79], v[80:81], v[54:55]
	v_pk_add_f32 v[54:55], v[80:81], v[54:55] neg_lo:[0,1] neg_hi:[0,1]
	v_pk_add_f32 v[80:81], v[64:65], v[56:57]
	v_pk_add_f32 v[56:57], v[64:65], v[56:57] neg_lo:[0,1] neg_hi:[0,1]
	s_nop 0
	v_pk_mul_f32 v[64:65], v[56:57], s[18:19]
	s_nop 0
	v_pk_fma_f32 v[56:57], v[56:57], s[30:31], v[64:65] op_sel:[0,0,1] op_sel_hi:[1,0,0]
	v_pk_add_f32 v[64:65], v[26:27], v[58:59]
	v_pk_add_f32 v[26:27], v[26:27], v[58:59] neg_lo:[0,1] neg_hi:[0,1]
	s_nop 0
	v_pk_mul_f32 v[58:59], v[26:27], s[10:11]
	s_nop 0
	v_pk_fma_f32 v[26:27], v[26:27], s[14:15], v[58:59] op_sel:[0,0,1] op_sel_hi:[1,0,0]
	v_pk_add_f32 v[58:59], v[28:29], v[60:61]
	v_pk_add_f32 v[28:29], v[28:29], v[60:61] neg_lo:[0,1] neg_hi:[0,1]
	s_nop 0
	v_pk_mul_f32 v[60:61], v[28:29], s[34:35]
	s_nop 0
	v_pk_fma_f32 v[28:29], v[28:29], s[8:9], v[60:61] op_sel:[0,0,1] op_sel_hi:[1,0,0]
	v_pk_add_f32 v[60:61], v[30:31], v[62:63]
	v_pk_add_f32 v[30:31], v[30:31], v[62:63] neg_lo:[0,1] neg_hi:[0,1]
	v_pk_add_f32 v[62:63], v[48:49], v[66:67]
	v_pk_add_f32 v[48:49], v[48:49], v[66:67] neg_lo:[0,1] neg_hi:[0,1]
	s_nop 0
	v_pk_mul_f32 v[66:67], v[48:49], s[34:35]
	s_nop 0
	v_pk_fma_f32 v[48:49], v[48:49], s[8:9], v[66:67] op_sel:[0,0,1] op_sel_hi:[1,0,0] neg_lo:[1,0,0] neg_hi:[1,0,0]
	v_pk_add_f32 v[66:67], v[50:51], v[72:73]
	v_pk_add_f32 v[50:51], v[50:51], v[72:73] neg_lo:[0,1] neg_hi:[0,1]
	s_nop 0
	v_pk_mul_f32 v[72:73], v[50:51], s[10:11]
	s_nop 0
	v_pk_fma_f32 v[50:51], v[50:51], s[14:15], v[72:73] op_sel:[0,0,1] op_sel_hi:[1,0,0] neg_lo:[1,0,0] neg_hi:[1,0,0]
	v_pk_add_f32 v[72:73], v[52:53], v[74:75]
	v_pk_add_f32 v[52:53], v[52:53], v[74:75] neg_lo:[0,1] neg_hi:[0,1]
	s_nop 0
	v_pk_mul_f32 v[74:75], v[52:53], s[18:19]
	s_nop 0
	v_pk_fma_f32 v[52:53], v[52:53], s[30:31], v[74:75] op_sel:[0,0,1] op_sel_hi:[1,0,0] neg_lo:[1,0,0] neg_hi:[1,0,0]
	v_pk_add_f32 v[74:75], v[24:25], v[14:15] op_sel:[0,1] op_sel_hi:[1,0] neg_hi:[0,1]
	v_pk_add_f32 v[14:15], v[24:25], v[14:15] op_sel:[0,1] op_sel_hi:[1,0] neg_lo:[0,1]
	v_pk_add_f32 v[24:25], v[0:1], v[16:17]
	v_pk_add_f32 v[0:1], v[0:1], v[16:17] neg_lo:[0,1] neg_hi:[0,1]
	s_nop 0
	v_pk_mul_f32 v[16:17], v[0:1], s[18:19]
	s_nop 0
	v_pk_fma_f32 v[0:1], v[0:1], s[30:31], v[16:17] op_sel:[0,0,1] op_sel_hi:[1,0,0]
	v_pk_add_f32 v[16:17], v[2:3], v[18:19]
	v_pk_add_f32 v[2:3], v[2:3], v[18:19] neg_lo:[0,1] neg_hi:[0,1]
	s_nop 0
	v_pk_mul_f32 v[18:19], v[2:3], s[10:11]
	s_nop 0
	v_pk_fma_f32 v[2:3], v[2:3], s[14:15], v[18:19] op_sel:[0,0,1] op_sel_hi:[1,0,0]
	v_pk_add_f32 v[18:19], v[4:5], v[20:21]
	v_pk_add_f32 v[4:5], v[4:5], v[20:21] neg_lo:[0,1] neg_hi:[0,1]
	s_nop 0
	v_pk_mul_f32 v[20:21], v[4:5], s[34:35]
	s_nop 0
	v_pk_fma_f32 v[4:5], v[4:5], s[8:9], v[20:21] op_sel:[0,0,1] op_sel_hi:[1,0,0]
	v_pk_add_f32 v[20:21], v[6:7], v[22:23]
	v_pk_add_f32 v[6:7], v[6:7], v[22:23] neg_lo:[0,1] neg_hi:[0,1]
	v_pk_add_f32 v[22:23], v[8:9], v[68:69]
	v_pk_add_f32 v[8:9], v[8:9], v[68:69] neg_lo:[0,1] neg_hi:[0,1]
	s_nop 0
	v_pk_mul_f32 v[68:69], v[8:9], s[34:35]
	s_nop 0
	v_pk_fma_f32 v[8:9], v[8:9], s[8:9], v[68:69] op_sel:[0,0,1] op_sel_hi:[1,0,0] neg_lo:[1,0,0] neg_hi:[1,0,0]
	v_pk_add_f32 v[68:69], v[10:11], v[70:71]
	v_pk_add_f32 v[10:11], v[10:11], v[70:71] neg_lo:[0,1] neg_hi:[0,1]
	s_nop 0
	v_pk_mul_f32 v[70:71], v[10:11], s[10:11]
	s_nop 0
	v_pk_fma_f32 v[10:11], v[10:11], s[14:15], v[70:71] op_sel:[0,0,1] op_sel_hi:[1,0,0] neg_lo:[1,0,0] neg_hi:[1,0,0]
	v_pk_add_f32 v[70:71], v[12:13], v[76:77]
	v_pk_add_f32 v[12:13], v[12:13], v[76:77] neg_lo:[0,1] neg_hi:[0,1]
	s_nop 0
	v_pk_mul_f32 v[76:77], v[12:13], s[18:19]
	s_nop 0
	v_pk_fma_f32 v[12:13], v[12:13], s[30:31], v[76:77] op_sel:[0,0,1] op_sel_hi:[1,0,0] neg_lo:[1,0,0] neg_hi:[1,0,0]
	v_pk_add_f32 v[76:77], v[78:79], v[60:61]
	v_pk_add_f32 v[60:61], v[78:79], v[60:61] neg_lo:[0,1] neg_hi:[0,1]
	v_pk_add_f32 v[78:79], v[80:81], v[62:63]
	v_pk_add_f32 v[62:63], v[80:81], v[62:63] neg_lo:[0,1] neg_hi:[0,1]
	s_nop 0
	v_pk_mul_f32 v[80:81], v[62:63], s[10:11]
	s_nop 0
	v_pk_fma_f32 v[62:63], v[62:63], s[14:15], v[80:81] op_sel:[0,0,1] op_sel_hi:[1,0,0]
	v_pk_add_f32 v[80:81], v[64:65], v[66:67]
	v_pk_add_f32 v[64:65], v[64:65], v[66:67] neg_lo:[0,1] neg_hi:[0,1]
	v_pk_add_f32 v[66:67], v[58:59], v[72:73]
	v_pk_add_f32 v[58:59], v[58:59], v[72:73] neg_lo:[0,1] neg_hi:[0,1]
	s_nop 0
	v_pk_mul_f32 v[72:73], v[58:59], s[10:11]
	s_nop 0
	v_pk_fma_f32 v[58:59], v[58:59], s[14:15], v[72:73] op_sel:[0,0,1] op_sel_hi:[1,0,0] neg_lo:[1,0,0] neg_hi:[1,0,0]
	v_pk_add_f32 v[72:73], v[54:55], v[30:31] op_sel:[0,1] op_sel_hi:[1,0] neg_hi:[0,1]
	v_pk_add_f32 v[30:31], v[54:55], v[30:31] op_sel:[0,1] op_sel_hi:[1,0] neg_lo:[0,1]
	v_pk_add_f32 v[54:55], v[56:57], v[48:49]
	v_pk_add_f32 v[48:49], v[56:57], v[48:49] neg_lo:[0,1] neg_hi:[0,1]
	v_pk_add_f32 v[82:83], v[62:63], v[58:59]
	v_pk_mul_f32 v[56:57], v[48:49], s[10:11]
	v_pk_add_f32 v[58:59], v[62:63], v[58:59] neg_lo:[0,1] neg_hi:[0,1]
	v_pk_fma_f32 v[48:49], v[48:49], s[14:15], v[56:57] op_sel:[0,0,1] op_sel_hi:[1,0,0]
	v_pk_add_f32 v[56:57], v[26:27], v[50:51]
	v_pk_add_f32 v[26:27], v[26:27], v[50:51] neg_lo:[0,1] neg_hi:[0,1]
	v_pk_add_f32 v[50:51], v[28:29], v[52:53]
	v_pk_add_f32 v[28:29], v[28:29], v[52:53] neg_lo:[0,1] neg_hi:[0,1]
	s_nop 0
	v_pk_mul_f32 v[52:53], v[28:29], s[10:11]
	v_pk_add_f32 v[88:89], v[54:55], v[50:51]
	v_pk_fma_f32 v[28:29], v[28:29], s[14:15], v[52:53] op_sel:[0,0,1] op_sel_hi:[1,0,0] neg_lo:[1,0,0] neg_hi:[1,0,0]
	v_pk_add_f32 v[52:53], v[74:75], v[20:21]
	v_pk_add_f32 v[20:21], v[74:75], v[20:21] neg_lo:[0,1] neg_hi:[0,1]
	v_pk_add_f32 v[74:75], v[24:25], v[22:23]
	v_pk_add_f32 v[22:23], v[24:25], v[22:23] neg_lo:[0,1] neg_hi:[0,1]
	v_pk_add_f32 v[50:51], v[54:55], v[50:51] neg_lo:[0,1] neg_hi:[0,1]
	v_pk_mul_f32 v[24:25], v[22:23], s[10:11]
	v_pk_add_f32 v[90:91], v[30:31], v[26:27] op_sel:[0,1] op_sel_hi:[1,0] neg_hi:[0,1]
	v_pk_fma_f32 v[22:23], v[22:23], s[14:15], v[24:25] op_sel:[0,0,1] op_sel_hi:[1,0,0]
	v_pk_add_f32 v[24:25], v[16:17], v[68:69]
	v_pk_add_f32 v[16:17], v[16:17], v[68:69] neg_lo:[0,1] neg_hi:[0,1]
	v_pk_add_f32 v[68:69], v[18:19], v[70:71]
	v_pk_add_f32 v[18:19], v[18:19], v[70:71] neg_lo:[0,1] neg_hi:[0,1]
	s_nop 0
	v_pk_mul_f32 v[70:71], v[18:19], s[10:11]
	v_pk_add_f32 v[26:27], v[30:31], v[26:27] op_sel:[0,1] op_sel_hi:[1,0] neg_lo:[0,1]
	v_pk_fma_f32 v[18:19], v[18:19], s[14:15], v[70:71] op_sel:[0,0,1] op_sel_hi:[1,0,0] neg_lo:[1,0,0] neg_hi:[1,0,0]
	v_pk_add_f32 v[70:71], v[14:15], v[6:7] op_sel:[0,1] op_sel_hi:[1,0] neg_hi:[0,1]
	v_pk_add_f32 v[6:7], v[14:15], v[6:7] op_sel:[0,1] op_sel_hi:[1,0] neg_lo:[0,1]
	v_pk_add_f32 v[14:15], v[0:1], v[8:9]
	v_pk_add_f32 v[0:1], v[0:1], v[8:9] neg_lo:[0,1] neg_hi:[0,1]
	v_pk_add_f32 v[30:31], v[48:49], v[28:29]
	v_pk_mul_f32 v[8:9], v[0:1], s[10:11]
	v_pk_add_f32 v[28:29], v[48:49], v[28:29] neg_lo:[0,1] neg_hi:[0,1]
	v_pk_fma_f32 v[0:1], v[0:1], s[14:15], v[8:9] op_sel:[0,0,1] op_sel_hi:[1,0,0]
	v_pk_add_f32 v[8:9], v[2:3], v[10:11]
	v_pk_add_f32 v[2:3], v[2:3], v[10:11] neg_lo:[0,1] neg_hi:[0,1]
	v_pk_add_f32 v[10:11], v[4:5], v[12:13]
	v_pk_add_f32 v[4:5], v[4:5], v[12:13] neg_lo:[0,1] neg_hi:[0,1]
	s_nop 0
	v_pk_mul_f32 v[12:13], v[4:5], s[10:11]
	v_pk_add_f32 v[92:93], v[52:53], v[24:25]
	v_pk_fma_f32 v[4:5], v[4:5], s[14:15], v[12:13] op_sel:[0,0,1] op_sel_hi:[1,0,0] neg_lo:[1,0,0] neg_hi:[1,0,0]
	v_pk_add_f32 v[12:13], v[76:77], v[80:81]
	v_pk_add_f32 v[76:77], v[76:77], v[80:81] neg_lo:[0,1] neg_hi:[0,1]
	v_pk_add_f32 v[80:81], v[78:79], v[66:67]
	v_pk_add_f32 v[66:67], v[78:79], v[66:67] neg_lo:[0,1] neg_hi:[0,1]
	v_pk_add_f32 v[94:95], v[52:53], v[24:25] neg_lo:[0,1] neg_hi:[0,1]
	v_pk_add_f32 v[96:97], v[74:75], v[68:69]
	v_pk_add_f32 v[24:25], v[74:75], v[68:69] neg_lo:[0,1] neg_hi:[0,1]
	v_pk_add_f32 v[74:75], v[20:21], v[16:17] op_sel:[0,1] op_sel_hi:[1,0] neg_hi:[0,1]
	v_pk_add_f32 v[98:99], v[20:21], v[16:17] op_sel:[0,1] op_sel_hi:[1,0] neg_lo:[0,1]
	v_pk_add_f32 v[16:17], v[22:23], v[18:19] neg_lo:[0,1] neg_hi:[0,1]
	v_pk_add_f32 v[104:105], v[70:71], v[8:9]
	v_pk_add_f32 v[106:107], v[70:71], v[8:9] neg_lo:[0,1] neg_hi:[0,1]
	v_pk_add_f32 v[8:9], v[14:15], v[10:11] neg_lo:[0,1] neg_hi:[0,1]
	v_pk_add_f32 v[110:111], v[6:7], v[2:3] op_sel:[0,1] op_sel_hi:[1,0] neg_hi:[0,1]
	v_pk_add_f32 v[112:113], v[6:7], v[2:3] op_sel:[0,1] op_sel_hi:[1,0] neg_lo:[0,1]
	v_pk_add_f32 v[2:3], v[0:1], v[4:5]
	v_pk_add_f32 v[0:1], v[0:1], v[4:5] neg_lo:[0,1] neg_hi:[0,1]
	v_pk_add_f32 v[78:79], v[60:61], v[64:65] op_sel:[0,1] op_sel_hi:[1,0] neg_hi:[0,1]
	v_pk_add_f32 v[64:65], v[60:61], v[64:65] op_sel:[0,1] op_sel_hi:[1,0] neg_lo:[0,1]
	v_pk_mul_f32 v[84:85], v[58:59], s[22:23]
	v_pk_add_f32 v[86:87], v[72:73], v[56:57]
	v_pk_add_f32 v[72:73], v[72:73], v[56:57] neg_lo:[0,1] neg_hi:[0,1]
	v_pk_mul_f32 v[48:49], v[28:29], s[22:23]
	v_pk_mul_f32 v[68:69], v[24:25], s[22:23]
	v_pk_add_f32 v[100:101], v[22:23], v[18:19]
	v_pk_mul_f32 v[102:103], v[16:17], s[22:23]
	v_pk_add_f32 v[70:71], v[14:15], v[10:11]
	v_pk_mul_f32 v[108:109], v[8:9], s[22:23]
	v_pk_mul_f32 v[114:115], v[0:1], s[22:23]
	v_pk_add_f32 v[28:29], v[12:13], v[80:81]
	v_pk_add_f32 v[62:63], v[12:13], v[80:81] neg_lo:[0,1] neg_hi:[0,1]
	v_pk_add_f32 v[24:25], v[76:77], v[66:67] op_sel:[0,1] op_sel_hi:[1,0] neg_hi:[0,1]
	v_pk_add_f32 v[60:61], v[76:77], v[66:67] op_sel:[0,1] op_sel_hi:[1,0] neg_lo:[0,1]
	v_pk_add_f32 v[20:21], v[78:79], v[82:83]
	v_pk_add_f32 v[58:59], v[78:79], v[82:83] neg_lo:[0,1] neg_hi:[0,1]
	v_pk_add_f32 v[16:17], v[64:65], v[84:85] op_sel:[0,1] op_sel_hi:[1,0]
	v_pk_add_f32 v[56:57], v[64:65], v[84:85] op_sel:[0,1] op_sel_hi:[1,0] neg_lo:[0,1] neg_hi:[0,1]
	v_pk_add_f32 v[12:13], v[86:87], v[88:89]
	v_pk_add_f32 v[54:55], v[86:87], v[88:89] neg_lo:[0,1] neg_hi:[0,1]
	v_pk_add_f32 v[8:9], v[72:73], v[50:51] op_sel:[0,1] op_sel_hi:[1,0] neg_hi:[0,1]
	v_pk_add_f32 v[52:53], v[72:73], v[50:51] op_sel:[0,1] op_sel_hi:[1,0] neg_lo:[0,1]
	v_pk_add_f32 v[4:5], v[90:91], v[30:31]
	v_pk_add_f32 v[50:51], v[90:91], v[30:31] neg_lo:[0,1] neg_hi:[0,1]
	v_pk_add_f32 v[0:1], v[26:27], v[48:49] op_sel:[0,1] op_sel_hi:[1,0]
	v_pk_add_f32 v[48:49], v[26:27], v[48:49] op_sel:[0,1] op_sel_hi:[1,0] neg_lo:[0,1] neg_hi:[0,1]
	v_pk_add_f32 v[30:31], v[92:93], v[96:97]
	v_pk_add_f32 v[78:79], v[92:93], v[96:97] neg_lo:[0,1] neg_hi:[0,1]
	v_pk_add_f32 v[26:27], v[94:95], v[68:69] op_sel:[0,1] op_sel_hi:[1,0]
	v_pk_add_f32 v[76:77], v[94:95], v[68:69] op_sel:[0,1] op_sel_hi:[1,0] neg_lo:[0,1] neg_hi:[0,1]
	v_pk_add_f32 v[22:23], v[74:75], v[100:101]
	v_pk_add_f32 v[74:75], v[74:75], v[100:101] neg_lo:[0,1] neg_hi:[0,1]
	v_pk_add_f32 v[18:19], v[98:99], v[102:103] op_sel:[0,1] op_sel_hi:[1,0]
	v_pk_add_f32 v[72:73], v[98:99], v[102:103] op_sel:[0,1] op_sel_hi:[1,0] neg_lo:[0,1] neg_hi:[0,1]
	v_pk_add_f32 v[14:15], v[104:105], v[70:71]
	v_pk_add_f32 v[70:71], v[104:105], v[70:71] neg_lo:[0,1] neg_hi:[0,1]
	v_pk_add_f32 v[10:11], v[106:107], v[108:109] op_sel:[0,1] op_sel_hi:[1,0]
	v_pk_add_f32 v[68:69], v[106:107], v[108:109] op_sel:[0,1] op_sel_hi:[1,0] neg_lo:[0,1] neg_hi:[0,1]
	v_pk_add_f32 v[6:7], v[110:111], v[2:3]
	v_pk_add_f32 v[66:67], v[110:111], v[2:3] neg_lo:[0,1] neg_hi:[0,1]
	v_pk_add_f32 v[2:3], v[112:113], v[114:115] op_sel:[0,1] op_sel_hi:[1,0]
	v_pk_add_f32 v[64:65], v[112:113], v[114:115] op_sel:[0,1] op_sel_hi:[1,0] neg_lo:[0,1] neg_hi:[0,1]

.LBB0_601:
	s_or_b64 exec, exec, s[4:5]
	s_waitcnt vmcnt(0)
	v_lshlrev_b32_e32 v21, 16, v157
	v_lshlrev_b32_e32 v19, 16, v158
	v_lshlrev_b32_e32 v20, 16, v159
	v_lshlrev_b32_e32 v18, 16, v160
	v_lshlrev_b32_e32 v16, 16, v12
	v_fma_f32 v21, v148, v21, v149
	v_and_b32_e32 v12, 0xffff0000, v12
	v_fmac_f32_e32 v21, v45, v16
	v_fma_f32 v16, v148, v16, v149
	v_lshlrev_b32_e32 v17, 16, v13
	v_fmac_f32_e32 v16, v45, v12
	v_fma_f32 v28, v148, v12, v149
	v_and_b32_e32 v13, 0xffff0000, v13
	v_fmac_f32_e32 v16, v44, v17
	v_fmac_f32_e32 v28, v45, v17
	v_fma_f32 v17, v148, v17, v149
	v_lshlrev_b32_e32 v22, 16, v14
	v_fmac_f32_e32 v17, v45, v13
	v_fma_f32 v29, v148, v13, v149
	v_and_b32_e32 v14, 0xffff0000, v14
	v_fmac_f32_e32 v17, v44, v22
	v_fmac_f32_e32 v29, v45, v22
	v_fma_f32 v22, v148, v22, v149
	v_lshlrev_b32_e32 v23, 16, v15
	v_fmac_f32_e32 v22, v45, v14
	v_fma_f32 v30, v148, v14, v149
	v_and_b32_e32 v15, 0xffff0000, v15
	v_fmac_f32_e32 v22, v44, v23
	v_fmac_f32_e32 v30, v45, v23
	v_fma_f32 v23, v148, v23, v149
	v_lshlrev_b32_e32 v24, 16, v8
	v_fmac_f32_e32 v23, v45, v15
	v_fma_f32 v31, v148, v15, v149
	v_and_b32_e32 v8, 0xffff0000, v8
	v_fmac_f32_e32 v23, v44, v24
	v_fmac_f32_e32 v31, v45, v24
	v_fma_f32 v24, v148, v24, v149
	v_lshlrev_b32_e32 v25, 16, v9
	v_fmac_f32_e32 v24, v45, v8
	v_fma_f32 v41, v148, v8, v149
	v_and_b32_e32 v9, 0xffff0000, v9
	v_fmac_f32_e32 v24, v44, v25
	v_fmac_f32_e32 v41, v45, v25
	v_fma_f32 v25, v148, v25, v149
	v_lshlrev_b32_e32 v26, 16, v10
	v_fmac_f32_e32 v25, v45, v9
	v_fma_f32 v58, v148, v9, v149
	v_and_b32_e32 v10, 0xffff0000, v10
	v_lshlrev_b32_e32 v27, 16, v11
	v_fmac_f32_e32 v25, v44, v26
	v_fmac_f32_e32 v58, v45, v26
	v_fma_f32 v26, v148, v26, v149
	v_and_b32_e32 v11, 0xffff0000, v11
	v_fmac_f32_e32 v31, v44, v8
	v_fmac_f32_e32 v41, v44, v9
	v_fmac_f32_e32 v58, v44, v10
	v_fmac_f32_e32 v26, v45, v10
	v_fma_f32 v8, v148, v10, v149
	v_fma_f32 v9, v148, v27, v149
	s_waitcnt vmcnt(0)
	v_and_b32_e32 v10, 0xffff0000, v4
	v_fmac_f32_e32 v21, v44, v12
	v_fmac_f32_e32 v28, v44, v13
	v_fmac_f32_e32 v9, v45, v11
	v_lshlrev_b32_e32 v13, 16, v4
	v_mov_b32_e32 v12, v10
	v_fmac_f32_e32 v29, v44, v14
	v_fmac_f32_e32 v30, v44, v15
	v_fmac_f32_e32 v8, v45, v27
	v_fmac_f32_e32 v9, v44, v19
	v_fma_f32 v19, v148, v20, v149
	v_pk_mul_f32 v[14:15], v[44:45], v[12:13]
	v_fmac_f32_e32 v8, v44, v11
	v_and_b32_e32 v11, 16, v4
	v_add_f32_e32 v4, v15, v19
	v_and_b32_e32 v12, 0xffff0000, v5
	v_add_f32_e32 v14, v14, v4
	v_fma_f32 v15, v148, v13, v149
	v_and_b32_e32 v13, 16, v5
	v_lshlrev_b32_e32 v5, 16, v5
	v_mov_b32_e32 v4, v12
	v_fma_f32 v19, v148, v10, v149
	v_pk_mov_b32 v[10:11], v[4:5], v[10:11] op_sel:[1,0]
	v_fmac_f32_e32 v26, v44, v27
	v_pk_mul_f32 v[10:11], v[44:45], v[10:11]
	v_fma_f32 v27, v148, v12, v149
	v_add_f32_e32 v11, v11, v15
	v_add_f32_e32 v15, v10, v11
	v_pk_mul_f32 v[10:11], v[44:45], v[4:5]
	v_fma_f32 v20, v148, v5, v149
	v_add_f32_e32 v4, v11, v19
	v_add_f32_e32 v19, v10, v4
	v_and_b32_e32 v4, 0xffff0000, v6
	v_lshlrev_b32_e32 v11, 16, v6
	v_mov_b32_e32 v10, v4
	v_pk_mov_b32 v[12:13], v[10:11], v[12:13] op_sel:[1,0]
	v_and_b32_e32 v5, 16, v6
	v_pk_mul_f32 v[12:13], v[44:45], v[12:13]
	s_mov_b64 s[4:5], 0xc00000
	v_add_f32_e32 v6, v13, v20
	v_add_f32_e32 v20, v12, v6
	v_pk_mul_f32 v[12:13], v[44:45], v[10:11]
	v_and_b32_e32 v10, 0xffff0000, v7
	v_add_f32_e32 v6, v13, v27
	v_add_f32_e32 v12, v12, v6
	v_fma_f32 v13, v148, v11, v149
	v_and_b32_e32 v11, 16, v7
	v_lshlrev_b32_e32 v7, 16, v7
	v_mov_b32_e32 v6, v10
	v_fma_f32 v27, v148, v4, v149
	v_pk_mov_b32 v[4:5], v[6:7], v[4:5] op_sel:[1,0]
	v_fma_f32 v59, v148, v7, v149
	v_pk_mul_f32 v[4:5], v[44:45], v[4:5]
	v_fma_f32 v60, v148, v10, v149
	v_add_f32_e32 v5, v5, v13
	v_add_f32_e32 v13, v4, v5
	v_pk_mul_f32 v[4:5], v[44:45], v[6:7]
	v_lshlrev_b32_e32 v7, 16, v0
	v_add_f32_e32 v5, v5, v27
	v_add_f32_e32 v27, v4, v5
	v_and_b32_e32 v4, 0xffff0000, v0
	v_mov_b32_e32 v6, v4
	v_pk_mov_b32 v[10:11], v[6:7], v[10:11] op_sel:[1,0]
	v_and_b32_e32 v5, 16, v0
	v_pk_mul_f32 v[10:11], v[44:45], v[10:11]
	s_nop 0
	v_add_f32_e32 v0, v11, v59
	v_add_f32_e32 v59, v10, v0
	v_pk_mul_f32 v[10:11], v[44:45], v[6:7]
	v_and_b32_e32 v6, 0xffff0000, v1
	v_add_f32_e32 v0, v60, v11
	v_add_f32_e32 v10, v10, v0
	v_fma_f32 v11, v148, v7, v149
	v_and_b32_e32 v7, 16, v1
	v_lshlrev_b32_e32 v1, 16, v1
	v_mov_b32_e32 v0, v6
	v_fma_f32 v60, v148, v4, v149
	v_pk_mov_b32 v[4:5], v[0:1], v[4:5] op_sel:[1,0]
	v_fma_f32 v94, v148, v6, v149
	v_pk_mul_f32 v[4:5], v[44:45], v[4:5]
	v_fma_f32 v61, v148, v1, v149
	v_add_f32_e32 v5, v5, v11
	v_add_f32_e32 v11, v4, v5
	v_pk_mul_f32 v[4:5], v[44:45], v[0:1]
	v_and_b32_e32 v1, 16, v2
	v_add_f32_e32 v0, v5, v60
	v_add_f32_e32 v60, v4, v0
	v_and_b32_e32 v0, 0xffff0000, v2
	v_lshlrev_b32_e32 v5, 16, v2
	v_mov_b32_e32 v4, v0
	v_pk_mov_b32 v[6:7], v[4:5], v[6:7] op_sel:[1,0]
	s_nop 0
	v_pk_mul_f32 v[6:7], v[44:45], v[6:7]
	s_nop 0
	v_add_f32_e32 v2, v7, v61
	v_add_f32_e32 v61, v6, v2
	v_pk_mul_f32 v[6:7], v[44:45], v[4:5]
	v_fma_f32 v5, v148, v5, v149
	v_add_f32_e32 v2, v7, v94
	v_add_f32_e32 v4, v6, v2
	v_and_b32_e32 v2, 0xffff0000, v3
	v_lshlrev_b32_e32 v3, 16, v3
	v_fma_f32 v6, v148, v0, v149
	v_pk_mov_b32 v[0:1], v[2:3], v[0:1] op_sel:[1,0]
	v_fma_f32 v7, v148, v3, v149
	v_pk_mul_f32 v[0:1], v[44:45], v[0:1]
	s_nop 0
	v_add_f32_e32 v1, v1, v5
	v_add_f32_e32 v5, v0, v1
	v_pk_mul_f32 v[0:1], v[44:45], v[2:3]
	v_mov_b32_e32 v3, v18
	v_add_f32_e32 v1, v1, v6
	v_add_f32_e32 v6, v0, v1
	v_pk_mul_f32 v[0:1], v[50:51], v[2:3]
	s_nop 0
	v_add_f32_e32 v0, v0, v7
	v_add_f32_e32 v7, v0, v1
	ds_read2_b64 v[0:3], v152 offset1:1
	s_waitcnt lgkmcnt(0)
	v_fma_f32 v0, v150, v92, v0
	v_mul_f32_e32 v18, v21, v0
	v_fma_f32 v0, v150, v93, -v1
	v_mul_f32_e32 v14, v14, v0
	v_fma_f32 v0, v150, v86, v2
	v_mul_f32_e32 v16, v16, v0
	v_fma_f32 v0, v150, v87, -v3
	v_mul_f32_e32 v15, v15, v0
	ds_read2_b64 v[0:3], v152 offset0:2 offset1:3
	s_waitcnt lgkmcnt(0)
	v_fma_f32 v0, v150, v76, v0
	v_mul_f32_e32 v21, v28, v0
	v_fma_f32 v0, v150, v77, -v1
	v_mul_f32_e32 v19, v19, v0
	v_fma_f32 v0, v150, v70, v2
	v_mul_f32_e32 v17, v17, v0
	v_fma_f32 v0, v150, v71, -v3
	v_mul_f32_e32 v20, v20, v0
	ds_read2_b64 v[0:3], v152 offset0:4 offset1:5
	s_waitcnt lgkmcnt(0)
	v_fma_f32 v0, v150, v90, v0
	v_mul_f32_e32 v28, v29, v0
	v_fma_f32 v0, v150, v91, -v1
	v_mul_f32_e32 v12, v12, v0
	v_fma_f32 v0, v150, v82, v2
	v_mul_f32_e32 v22, v22, v0
	v_fma_f32 v0, v150, v83, -v3
	v_mul_f32_e32 v13, v13, v0
	ds_read2_b64 v[0:3], v152 offset0:6 offset1:7
	s_waitcnt lgkmcnt(0)
	v_fma_f32 v0, v150, v74, v0
	v_mul_f32_e32 v29, v30, v0
	v_fma_f32 v0, v150, v75, -v1
	v_mul_f32_e32 v27, v27, v0
	v_fma_f32 v0, v150, v66, v2
	v_mul_f32_e32 v23, v23, v0
	v_fma_f32 v0, v150, v67, -v3
	v_mul_f32_e32 v30, v59, v0
	ds_read2_b64 v[0:3], v152 offset0:8 offset1:9
	s_waitcnt lgkmcnt(0)
	v_fma_f32 v0, v150, v88, v0
	v_mul_f32_e32 v31, v31, v0
	v_fma_f32 v0, v150, v89, -v1
	v_mul_f32_e32 v59, v10, v0
	v_fma_f32 v0, v150, v80, v2
	v_mul_f32_e32 v10, v24, v0
	v_fma_f32 v0, v150, v81, -v3
	v_mul_f32_e32 v24, v11, v0
	ds_read2_b64 v[0:3], v152 offset0:10 offset1:11
	s_waitcnt lgkmcnt(0)
	v_fma_f32 v0, v150, v72, v0
	v_mul_f32_e32 v11, v41, v0
	v_fma_f32 v0, v150, v73, -v1
	v_mul_f32_e32 v41, v60, v0
	v_fma_f32 v0, v150, v64, v2
	v_mul_f32_e32 v25, v25, v0
	v_fma_f32 v0, v150, v65, -v3
	v_mul_f32_e32 v60, v61, v0
	ds_read2_b64 v[0:3], v152 offset0:12 offset1:13
	s_waitcnt lgkmcnt(0)
	v_fma_f32 v0, v150, v84, v0
	v_mul_f32_e32 v58, v58, v0
	v_fma_f32 v0, v150, v85, -v1
	v_mul_f32_e32 v61, v4, v0
	v_fma_f32 v0, v150, v78, v2
	v_mul_f32_e32 v26, v26, v0
	v_fma_f32 v0, v150, v79, -v3
	v_mul_f32_e32 v64, v5, v0
	ds_read2_b64 v[0:3], v152 offset0:14 offset1:15
	s_waitcnt lgkmcnt(0)
	v_fma_f32 v0, v150, v68, v0
	v_mul_f32_e32 v8, v8, v0
	v_fma_f32 v0, v150, v69, -v1
	v_mul_f32_e32 v65, v6, v0
	v_fma_f32 v0, v150, v62, v2
	v_mul_f32_e32 v9, v9, v0
	v_fma_f32 v0, v150, v63, -v3
	v_mul_f32_e32 v62, v7, v0
	v_cvt_pk_bf16_f32 v0, v18, v16
	v_cvt_pk_bf16_f32 v1, v21, v17
	v_cvt_pk_bf16_f32 v2, v28, v22
	v_cvt_pk_bf16_f32 v3, v29, v23
	v_cvt_pk_bf16_f32 v4, v31, v10
	v_cvt_pk_bf16_f32 v5, v11, v25
	v_cvt_pk_bf16_f32 v6, v58, v26
	v_cvt_pk_bf16_f32 v7, v8, v9
	v_cvt_pk_bf16_f32 v8, v14, v15
	v_cvt_pk_bf16_f32 v9, v19, v20
	v_cvt_pk_bf16_f32 v10, v12, v13
	v_cvt_pk_bf16_f32 v11, v27, v30
	v_cvt_pk_bf16_f32 v12, v59, v24
	v_cvt_pk_bf16_f32 v13, v41, v60
	v_cvt_pk_bf16_f32 v14, v61, v64
	v_cvt_pk_bf16_f32 v15, v65, v62
	global_store_dwordx4 v[56:57], v[0:3], off
	global_store_dwordx4 v[56:57], v[4:7], off offset:16
	s_nop 0
	v_add_co_u32_e32 v2, vcc, 0xc00000, v56
	v_lshl_add_u64 v[0:1], v[56:57], 0, s[4:5]
	s_nop 0
	v_addc_co_u32_e32 v3, vcc, 0, v57, vcc
	global_store_dwordx4 v[2:3], v[8:11], off
	global_store_dwordx4 v[0:1], v[12:15], off offset:16

.LBB0_603:
	s_or_b32 s4, s4, s57
	s_lshl_b32 s4, s4, 13
	s_add_u32 s38, s46, s4
	s_addc_u32 s39, s47, 0
	v_mov_b32_e32 v9, 0
	v_lshl_add_u64 v[56:57], v[48:49], 1, s[38:39]
	v_mov_b32_e32 v8, 0
	v_mov_b32_e32 v11, 0
	v_mov_b32_e32 v10, 0
	v_mov_b32_e32 v13, 0
	v_mov_b32_e32 v12, 0
	v_mov_b32_e32 v15, 0
	v_mov_b32_e32 v14, 0
	v_mov_b32_e32 v17, 0
	v_mov_b32_e32 v16, 0
	v_mov_b32_e32 v21, 0
	v_mov_b32_e32 v20, 0
	v_mov_b32_e32 v23, 0
	v_mov_b32_e32 v22, 0
	v_mov_b32_e32 v25, 0
	v_mov_b32_e32 v24, 0
	v_mov_b32_e32 v1, 0
	v_mov_b32_e32 v0, 0
	v_mov_b32_e32 v3, 0
	v_mov_b32_e32 v2, 0
	v_mov_b32_e32 v5, 0
	v_mov_b32_e32 v4, 0
	v_mov_b32_e32 v7, 0
	v_mov_b32_e32 v6, 0
	v_mov_b32_e32 v27, 0
	v_mov_b32_e32 v26, 0
	v_mov_b32_e32 v29, 0
	v_mov_b32_e32 v28, 0
	v_mov_b32_e32 v31, 0
	v_mov_b32_e32 v30, 0
	v_mov_b32_e32 v59, 0
	v_mov_b32_e32 v58, 0
	s_and_saveexec_b64 s[28:29], s[40:41]
	s_cbranch_execz .LBB0_613
	global_load_dwordx4 v[8:11], v[56:57], off offset:16
	global_load_dwordx4 v[12:15], v[56:57], off
	v_mov_b32_e32 v27, 0
	v_mov_b32_e32 v16, 0
	v_mov_b32_e32 v41, 0
	s_and_saveexec_b64 s[4:5], s[42:43]
	s_cbranch_execz .LBB0_606
	v_lshl_add_u64 v[0:1], v[172:173], 1, s[38:39]
	global_load_ushort v41, v[0:1], off offset:-2
.LBB0_606:
	s_or_b64 exec, exec, s[4:5]
	v_mov_b32_e32 v60, 0
	s_and_saveexec_b64 s[4:5], s[44:45]
	s_cbranch_execz .LBB0_608
	global_load_ushort v60, v[56:57], off offset:32
.LBB0_608:
	s_or_b64 exec, exec, s[4:5]
	s_add_u32 s4, s38, 0xc00000
	s_addc_u32 s5, s39, 0
	v_lshl_add_u64 v[20:21], v[48:49], 1, s[4:5]
	global_load_dwordx4 v[0:3], v[20:21], off offset:16
	global_load_dwordx4 v[4:7], v[20:21], off
	v_mov_b32_e32 v19, 0
	v_mov_b32_e32 v28, 0
	v_mov_b32_e32 v61, 0
	s_and_saveexec_b64 s[8:9], s[42:43]
	s_cbranch_execz .LBB0_610
	v_lshl_add_u64 v[22:23], v[172:173], 1, s[4:5]
	global_load_ushort v61, v[22:23], off offset:-2
.LBB0_610:
	s_or_b64 exec, exec, s[8:9]
	v_mov_b32_e32 v62, 0
	s_and_saveexec_b64 s[4:5], s[44:45]
	s_cbranch_execz .LBB0_612
	global_load_ushort v62, v[20:21], off offset:32
.LBB0_612:
	s_or_b64 exec, exec, s[4:5]
	s_waitcnt vmcnt(0)
	v_lshlrev_b32_e32 v16, 16, v41
	v_lshlrev_b32_e32 v27, 16, v60
	v_lshlrev_b32_e32 v28, 16, v61
	v_lshlrev_b32_e32 v19, 16, v62
	v_lshlrev_b32_e32 v25, 16, v13
	v_and_b32_e32 v31, 16, v14
	v_and_b32_e32 v30, 0xffff0000, v13
	v_lshlrev_b32_e32 v13, 16, v14
	v_and_b32_e32 v61, 16, v15
	v_and_b32_e32 v60, 0xffff0000, v14
	v_lshlrev_b32_e32 v63, 16, v15
	v_pk_mov_b32 v[14:15], v[14:15], v[8:9] op_sel:[1,0]
	v_lshlrev_b32_e32 v20, 16, v12
	v_and_b32_e32 v14, 0xffff0000, v14
	v_and_b32_e32 v70, 0xffff0000, v8
	v_and_b32_e32 v76, 0xffff0000, v9
	v_and_b32_e32 v24, 0xffff0000, v12
	v_mov_b32_e32 v17, v20
	v_mov_b32_e32 v12, v30
	v_mov_b32_e32 v62, v60
	v_and_b32_e32 v15, 16, v15
	v_lshlrev_b32_e32 v67, 16, v8
	v_mov_b32_e32 v66, v14
	v_and_b32_e32 v71, 16, v9
	v_lshlrev_b32_e32 v73, 16, v9
	v_mov_b32_e32 v72, v70
	v_and_b32_e32 v77, 16, v10
	v_lshlrev_b32_e32 v9, 16, v10
	v_mov_b32_e32 v8, v76
	v_and_b32_e32 v81, 16, v11
	v_and_b32_e32 v80, 0xffff0000, v10
	v_and_b32_e32 v23, 0xffff0000, v11
	v_mov_b32_e32 v21, v24
	v_pk_fma_f32 v[16:17], v[34:35], v[16:17], v[36:37]
	v_pk_fma_f32 v[58:59], v[34:35], v[24:25], v[36:37]
	v_pk_mov_b32 v[30:31], v[24:25], v[30:31] op_sel:[1,0]
	v_pk_fma_f32 v[64:65], v[34:35], v[12:13], v[36:37]
	v_pk_mov_b32 v[60:61], v[12:13], v[60:61] op_sel:[1,0]
	v_pk_fma_f32 v[68:69], v[34:35], v[62:63], v[36:37]
	v_pk_mov_b32 v[14:15], v[62:63], v[14:15] op_sel:[1,0]
	v_pk_fma_f32 v[74:75], v[34:35], v[66:67], v[36:37]
	v_pk_mov_b32 v[70:71], v[66:67], v[70:71] op_sel:[1,0]
	v_pk_fma_f32 v[78:79], v[34:35], v[72:73], v[36:37]
	v_pk_mov_b32 v[76:77], v[72:73], v[76:77] op_sel:[1,0]
	v_lshlrev_b32_e32 v11, 16, v11
	v_mov_b32_e32 v10, v80
	v_pk_fma_f32 v[82:83], v[34:35], v[8:9], v[36:37]
	v_pk_mov_b32 v[80:81], v[8:9], v[80:81] op_sel:[1,0]
	v_pk_fma_f32 v[84:85], v[34:35], v[10:11], v[36:37]
	v_mov_b32_e32 v22, v11
	v_pk_fma_f32 v[16:17], v[38:39], v[20:21], v[16:17]
	v_pk_fma_f32 v[20:21], v[38:39], v[30:31], v[58:59]
	v_pk_fma_f32 v[30:31], v[38:39], v[60:61], v[64:65]
	v_pk_fma_f32 v[14:15], v[38:39], v[14:15], v[68:69]
	v_pk_fma_f32 v[58:59], v[38:39], v[70:71], v[74:75]
	v_pk_fma_f32 v[60:61], v[38:39], v[76:77], v[78:79]
	v_pk_fma_f32 v[64:65], v[38:39], v[80:81], v[82:83]
	v_mov_b32_e32 v41, v40
	v_mov_b32_e32 v26, v23
	v_pk_fma_f32 v[68:69], v[38:39], v[22:23], v[84:85]
	v_pk_fma_f32 v[24:25], v[54:55], v[24:25], v[16:17]
	v_pk_fma_f32 v[22:23], v[40:41], v[12:13], v[20:21]
	v_pk_fma_f32 v[16:17], v[40:41], v[66:67], v[14:15]
	v_pk_fma_f32 v[14:15], v[40:41], v[72:73], v[58:59]
	v_pk_fma_f32 v[12:13], v[40:41], v[8:9], v[60:61]
	v_pk_fma_f32 v[10:11], v[40:41], v[10:11], v[64:65]
	s_waitcnt vmcnt(0)
	v_lshlrev_b32_e32 v59, 16, v5
	v_and_b32_e32 v61, 16, v6
	v_and_b32_e32 v60, 0xffff0000, v5
	v_lshlrev_b32_e32 v5, 16, v6
	v_and_b32_e32 v65, 16, v7
	v_and_b32_e32 v64, 0xffff0000, v6
	v_lshlrev_b32_e32 v67, 16, v7
	v_pk_mov_b32 v[6:7], v[6:7], v[0:1] op_sel:[1,0]
	v_pk_fma_f32 v[8:9], v[40:41], v[26:27], v[68:69]
	v_lshlrev_b32_e32 v26, 16, v4
	v_and_b32_e32 v6, 0xffff0000, v6
	v_and_b32_e32 v74, 0xffff0000, v0
	v_and_b32_e32 v80, 0xffff0000, v1
	v_and_b32_e32 v84, 0xffff0000, v2
	v_pk_fma_f32 v[20:21], v[40:41], v[62:63], v[30:31]
	v_and_b32_e32 v31, 0xffff0000, v3
	v_and_b32_e32 v58, 0xffff0000, v4
	v_mov_b32_e32 v29, v26
	v_mov_b32_e32 v4, v60
	v_mov_b32_e32 v66, v64
	v_and_b32_e32 v7, 16, v7
	v_lshlrev_b32_e32 v71, 16, v0
	v_mov_b32_e32 v70, v6
	v_and_b32_e32 v75, 16, v1
	v_lshlrev_b32_e32 v77, 16, v1
	v_mov_b32_e32 v76, v74
	v_and_b32_e32 v81, 16, v2
	v_lshlrev_b32_e32 v1, 16, v2
	v_mov_b32_e32 v0, v80
	v_and_b32_e32 v85, 16, v3
	v_lshlrev_b32_e32 v3, 16, v3
	v_mov_b32_e32 v2, v84
	v_mov_b32_e32 v27, v58
	v_pk_fma_f32 v[28:29], v[34:35], v[28:29], v[36:37]
	v_pk_fma_f32 v[62:63], v[34:35], v[58:59], v[36:37]
	v_pk_mov_b32 v[60:61], v[58:59], v[60:61] op_sel:[1,0]
	v_pk_fma_f32 v[68:69], v[34:35], v[4:5], v[36:37]
	v_pk_mov_b32 v[64:65], v[4:5], v[64:65] op_sel:[1,0]
	v_pk_fma_f32 v[72:73], v[34:35], v[66:67], v[36:37]
	v_pk_mov_b32 v[6:7], v[66:67], v[6:7] op_sel:[1,0]
	v_pk_fma_f32 v[78:79], v[34:35], v[70:71], v[36:37]
	v_pk_mov_b32 v[74:75], v[70:71], v[74:75] op_sel:[1,0]
	v_pk_fma_f32 v[82:83], v[34:35], v[76:77], v[36:37]
	v_pk_mov_b32 v[80:81], v[76:77], v[80:81] op_sel:[1,0]
	v_pk_fma_f32 v[86:87], v[34:35], v[0:1], v[36:37]
	v_pk_mov_b32 v[84:85], v[0:1], v[84:85] op_sel:[1,0]
	v_pk_fma_f32 v[88:89], v[34:35], v[2:3], v[36:37]
	v_mov_b32_e32 v30, v3
	v_mov_b32_e32 v18, v31
	v_pk_fma_f32 v[26:27], v[38:39], v[26:27], v[28:29]
	v_pk_fma_f32 v[28:29], v[38:39], v[60:61], v[62:63]
	v_pk_fma_f32 v[60:61], v[38:39], v[64:65], v[68:69]
	v_pk_fma_f32 v[6:7], v[38:39], v[6:7], v[72:73]
	v_pk_fma_f32 v[62:63], v[38:39], v[74:75], v[78:79]
	v_pk_fma_f32 v[64:65], v[38:39], v[80:81], v[82:83]
	v_pk_fma_f32 v[68:69], v[38:39], v[84:85], v[86:87]
	v_pk_fma_f32 v[72:73], v[38:39], v[30:31], v[88:89]
	v_pk_fma_f32 v[58:59], v[54:55], v[58:59], v[26:27]
	v_pk_fma_f32 v[30:31], v[40:41], v[4:5], v[28:29]
	v_pk_fma_f32 v[28:29], v[40:41], v[66:67], v[60:61]
	v_pk_fma_f32 v[26:27], v[40:41], v[70:71], v[6:7]
	v_pk_fma_f32 v[6:7], v[40:41], v[76:77], v[62:63]
	v_pk_fma_f32 v[4:5], v[40:41], v[0:1], v[64:65]
	v_pk_fma_f32 v[2:3], v[40:41], v[2:3], v[68:69]
	v_pk_fma_f32 v[0:1], v[40:41], v[18:19], v[72:73]

.LBB0_623:
	s_or_b64 exec, exec, s[4:5]
	v_mov_b32_e32 v41, v32
	s_waitcnt lgkmcnt(0)
	s_barrier
	s_mov_b32 s11, s14
	v_and_b32_e32 v98, 31, v41
	v_cvt_f32_ubyte0_e32 v24, v98
	v_mul_f32_e32 v92, 0x3b000000, v24
	v_sin_f32_e32 v24, v92
	v_ashrrev_i32_e32 v0, 4, v41
	v_lshlrev_b32_e32 v0, 3, v0
	v_lshlrev_b32_e32 v1, 3, v41
	v_cos_f32_e32 v92, v92
	v_add3_u32 v25, 0, v0, v1
	ds_read_b64 v[0:1], v25
	ds_read_b64 v[2:3], v25 offset:4352
	ds_read_b64 v[4:5], v25 offset:8704
	ds_read_b64 v[6:7], v25 offset:13056
	ds_read_b64 v[8:9], v25 offset:17408
	ds_read_b64 v[10:11], v25 offset:21760
	ds_read_b64 v[12:13], v25 offset:26112
	ds_read_b64 v[14:15], v25 offset:30464
	ds_read_b64 v[16:17], v25 offset:34816
	ds_read_b64 v[18:19], v25 offset:39168
	ds_read_b64 v[20:21], v25 offset:43520
	ds_read_b64 v[22:23], v25 offset:47872
	v_xor_b32_e32 v93, 0x80000000, v24
	s_waitcnt lgkmcnt(10)
	v_pk_mul_f32 v[94:95], v[2:3], v[24:25] op_sel:[1,0] op_sel_hi:[0,0] neg_hi:[0,1]
	v_pk_fma_f32 v[2:3], v[2:3], v[92:93], v[94:95] op_sel_hi:[1,0,1]
	v_pk_mul_f32 v[94:95], v[24:25], v[92:93] op_sel:[0,1] op_sel_hi:[0,0] neg_hi:[1,0]
	v_pk_fma_f32 v[94:95], v[92:93], v[92:93], v[94:95] op_sel_hi:[0,1,1]
	ds_read_b64 v[26:27], v25 offset:52224
	ds_read_b64 v[28:29], v25 offset:56576
	ds_read_b64 v[30:31], v25 offset:60928
	ds_read_b64 v[86:87], v25 offset:65280
	s_waitcnt lgkmcnt(13)
	v_pk_mul_f32 v[96:97], v[4:5], v[94:95] op_sel:[1,1] op_sel_hi:[0,1] neg_lo:[0,1]
	v_pk_fma_f32 v[4:5], v[4:5], v[94:95], v[96:97] op_sel_hi:[1,0,1]
	v_pk_mul_f32 v[96:97], v[24:25], v[94:95] op_sel:[0,1] op_sel_hi:[0,0] neg_hi:[1,0]
	v_pk_fma_f32 v[94:95], v[92:93], v[94:95], v[96:97] op_sel_hi:[0,1,1]
	s_mov_b32 s35, s30
	s_waitcnt lgkmcnt(12)
	v_pk_mul_f32 v[96:97], v[6:7], v[94:95] op_sel:[1,1] op_sel_hi:[0,1] neg_lo:[0,1]
	v_pk_fma_f32 v[6:7], v[6:7], v[94:95], v[96:97] op_sel_hi:[1,0,1]
	v_pk_mul_f32 v[96:97], v[24:25], v[94:95] op_sel:[0,1] op_sel_hi:[0,0] neg_hi:[1,0]
	v_pk_fma_f32 v[94:95], v[92:93], v[94:95], v[96:97] op_sel_hi:[0,1,1]
	s_mov_b32 s26, s19
	s_waitcnt lgkmcnt(11)
	v_pk_mul_f32 v[96:97], v[8:9], v[94:95] op_sel:[1,1] op_sel_hi:[0,1] neg_lo:[0,1]
	v_pk_fma_f32 v[8:9], v[8:9], v[94:95], v[96:97] op_sel_hi:[1,0,1]
	v_pk_mul_f32 v[96:97], v[24:25], v[94:95] op_sel:[0,1] op_sel_hi:[0,0] neg_hi:[1,0]
	v_pk_fma_f32 v[94:95], v[92:93], v[94:95], v[96:97] op_sel_hi:[0,1,1]
	s_waitcnt lgkmcnt(0)
	v_pk_mul_f32 v[96:97], v[10:11], v[94:95] op_sel:[1,1] op_sel_hi:[0,1] neg_lo:[0,1]
	v_pk_fma_f32 v[10:11], v[10:11], v[94:95], v[96:97] op_sel_hi:[1,0,1]
	v_pk_mul_f32 v[96:97], v[24:25], v[94:95] op_sel:[0,1] op_sel_hi:[0,0] neg_hi:[1,0]
	v_pk_fma_f32 v[94:95], v[92:93], v[94:95], v[96:97] op_sel_hi:[0,1,1]
	s_barrier
	v_pk_mul_f32 v[96:97], v[12:13], v[94:95] op_sel:[1,1] op_sel_hi:[0,1] neg_lo:[0,1]
	v_pk_fma_f32 v[12:13], v[12:13], v[94:95], v[96:97] op_sel_hi:[1,0,1]
	v_pk_mul_f32 v[96:97], v[24:25], v[94:95] op_sel:[0,1] op_sel_hi:[0,0] neg_hi:[1,0]
	v_pk_fma_f32 v[94:95], v[92:93], v[94:95], v[96:97] op_sel_hi:[0,1,1]
	s_nop 0
	v_pk_mul_f32 v[96:97], v[14:15], v[94:95] op_sel:[1,1] op_sel_hi:[0,1] neg_lo:[0,1]
	v_pk_fma_f32 v[14:15], v[14:15], v[94:95], v[96:97] op_sel_hi:[1,0,1]
	v_pk_mul_f32 v[96:97], v[24:25], v[94:95] op_sel:[0,1] op_sel_hi:[0,0] neg_hi:[1,0]
	v_pk_fma_f32 v[94:95], v[92:93], v[94:95], v[96:97] op_sel_hi:[0,1,1]
	s_nop 0
	v_pk_mul_f32 v[96:97], v[16:17], v[94:95] op_sel:[1,1] op_sel_hi:[0,1] neg_lo:[0,1]
	v_pk_fma_f32 v[16:17], v[16:17], v[94:95], v[96:97] op_sel_hi:[1,0,1]
	v_pk_mul_f32 v[96:97], v[24:25], v[94:95] op_sel:[0,1] op_sel_hi:[0,0] neg_hi:[1,0]
	v_pk_fma_f32 v[94:95], v[92:93], v[94:95], v[96:97] op_sel_hi:[0,1,1]
	s_nop 0
	v_pk_mul_f32 v[96:97], v[18:19], v[94:95] op_sel:[1,1] op_sel_hi:[0,1] neg_lo:[0,1]
	v_pk_fma_f32 v[18:19], v[18:19], v[94:95], v[96:97] op_sel_hi:[1,0,1]
	v_pk_mul_f32 v[96:97], v[24:25], v[94:95] op_sel:[0,1] op_sel_hi:[0,0] neg_hi:[1,0]
	v_pk_fma_f32 v[94:95], v[92:93], v[94:95], v[96:97] op_sel_hi:[0,1,1]
	s_nop 0
	v_pk_mul_f32 v[96:97], v[20:21], v[94:95] op_sel:[1,1] op_sel_hi:[0,1] neg_lo:[0,1]
	v_pk_fma_f32 v[20:21], v[20:21], v[94:95], v[96:97] op_sel_hi:[1,0,1]
	v_pk_mul_f32 v[96:97], v[24:25], v[94:95] op_sel:[0,1] op_sel_hi:[0,0] neg_hi:[1,0]
	v_pk_fma_f32 v[94:95], v[92:93], v[94:95], v[96:97] op_sel_hi:[0,1,1]
	s_nop 0
	v_pk_mul_f32 v[96:97], v[22:23], v[94:95] op_sel:[1,1] op_sel_hi:[0,1] neg_lo:[0,1]
	v_pk_fma_f32 v[22:23], v[22:23], v[94:95], v[96:97] op_sel_hi:[1,0,1]
	v_pk_mul_f32 v[96:97], v[24:25], v[94:95] op_sel:[0,1] op_sel_hi:[0,0] neg_hi:[1,0]
	v_pk_fma_f32 v[94:95], v[92:93], v[94:95], v[96:97] op_sel_hi:[0,1,1]
	s_nop 0
	v_pk_mul_f32 v[96:97], v[26:27], v[94:95] op_sel:[1,1] op_sel_hi:[0,1] neg_lo:[0,1]
	v_pk_fma_f32 v[26:27], v[26:27], v[94:95], v[96:97] op_sel_hi:[1,0,1]
	v_pk_mul_f32 v[96:97], v[24:25], v[94:95] op_sel:[0,1] op_sel_hi:[0,0] neg_hi:[1,0]
	v_pk_fma_f32 v[94:95], v[92:93], v[94:95], v[96:97] op_sel_hi:[0,1,1]
	s_nop 0
	v_pk_mul_f32 v[96:97], v[28:29], v[94:95] op_sel:[1,1] op_sel_hi:[0,1] neg_lo:[0,1]
	v_pk_fma_f32 v[28:29], v[28:29], v[94:95], v[96:97] op_sel_hi:[1,0,1]
	v_pk_mul_f32 v[96:97], v[24:25], v[94:95] op_sel:[0,1] op_sel_hi:[0,0] neg_hi:[1,0]
	v_pk_fma_f32 v[94:95], v[92:93], v[94:95], v[96:97] op_sel_hi:[0,1,1]
	v_pk_mul_f32 v[24:25], v[24:25], v[94:95] op_sel:[0,1] op_sel_hi:[0,0] neg_hi:[1,0]
	v_pk_fma_f32 v[24:25], v[92:93], v[94:95], v[24:25] op_sel_hi:[0,1,1]
	v_pk_mul_f32 v[92:93], v[86:87], v[24:25] op_sel:[1,1] op_sel_hi:[0,1] neg_lo:[0,1]
	v_pk_fma_f32 v[24:25], v[86:87], v[24:25], v[92:93] op_sel_hi:[1,0,1]
	v_pk_add_f32 v[86:87], v[0:1], v[16:17]
	v_pk_add_f32 v[0:1], v[0:1], v[16:17] neg_lo:[0,1] neg_hi:[0,1]
	v_pk_add_f32 v[16:17], v[2:3], v[18:19]
	v_pk_add_f32 v[2:3], v[2:3], v[18:19] neg_lo:[0,1] neg_hi:[0,1]
	v_pk_mul_f32 v[96:97], v[30:31], v[94:95] op_sel:[1,1] op_sel_hi:[0,1] neg_lo:[0,1]
	v_pk_mul_f32 v[18:19], v[2:3], s[18:19]
	v_pk_fma_f32 v[30:31], v[30:31], v[94:95], v[96:97] op_sel_hi:[1,0,1]
	v_pk_fma_f32 v[2:3], v[2:3], s[30:31], v[18:19] op_sel:[0,0,1] op_sel_hi:[1,0,0]
	v_pk_add_f32 v[18:19], v[4:5], v[20:21]
	v_pk_add_f32 v[4:5], v[4:5], v[20:21] neg_lo:[0,1] neg_hi:[0,1]
	s_nop 0
	v_pk_mul_f32 v[20:21], v[4:5], s[10:11]
	s_nop 0
	v_pk_fma_f32 v[4:5], v[4:5], s[14:15], v[20:21] op_sel:[0,0,1] op_sel_hi:[1,0,0]
	v_pk_add_f32 v[20:21], v[6:7], v[22:23]
	v_pk_add_f32 v[6:7], v[6:7], v[22:23] neg_lo:[0,1] neg_hi:[0,1]
	s_nop 0
	v_pk_mul_f32 v[22:23], v[6:7], s[34:35]
	s_nop 0
	v_pk_fma_f32 v[6:7], v[6:7], s[26:27], v[22:23] op_sel:[0,0,1] op_sel_hi:[1,0,0]
	v_pk_add_f32 v[22:23], v[8:9], v[26:27]
	v_pk_add_f32 v[8:9], v[8:9], v[26:27] neg_lo:[0,1] neg_hi:[0,1]
	v_pk_add_f32 v[26:27], v[10:11], v[28:29]
	v_pk_add_f32 v[10:11], v[10:11], v[28:29] neg_lo:[0,1] neg_hi:[0,1]
	s_nop 0
	v_pk_mul_f32 v[28:29], v[10:11], s[34:35]
	s_nop 0
	v_pk_fma_f32 v[10:11], v[10:11], s[26:27], v[28:29] op_sel:[0,0,1] op_sel_hi:[1,0,0] neg_lo:[1,0,0] neg_hi:[1,0,0]
	v_pk_add_f32 v[28:29], v[12:13], v[30:31]
	v_pk_add_f32 v[12:13], v[12:13], v[30:31] neg_lo:[0,1] neg_hi:[0,1]
	s_nop 0
	v_pk_mul_f32 v[30:31], v[12:13], s[10:11]
	s_nop 0
	v_pk_fma_f32 v[12:13], v[12:13], s[14:15], v[30:31] op_sel:[0,0,1] op_sel_hi:[1,0,0] neg_lo:[1,0,0] neg_hi:[1,0,0]
	v_pk_add_f32 v[30:31], v[14:15], v[24:25]
	v_pk_add_f32 v[14:15], v[14:15], v[24:25] neg_lo:[0,1] neg_hi:[0,1]
	s_nop 0
	v_pk_mul_f32 v[24:25], v[14:15], s[18:19]
	s_nop 0
	v_pk_fma_f32 v[14:15], v[14:15], s[30:31], v[24:25] op_sel:[0,0,1] op_sel_hi:[1,0,0] neg_lo:[1,0,0] neg_hi:[1,0,0]
	v_pk_add_f32 v[24:25], v[86:87], v[22:23]
	v_pk_add_f32 v[22:23], v[86:87], v[22:23] neg_lo:[0,1] neg_hi:[0,1]
	v_pk_add_f32 v[86:87], v[16:17], v[26:27]
	v_pk_add_f32 v[16:17], v[16:17], v[26:27] neg_lo:[0,1] neg_hi:[0,1]
	s_nop 0
	v_pk_mul_f32 v[26:27], v[16:17], s[10:11]
	s_nop 0
	v_pk_fma_f32 v[16:17], v[16:17], s[14:15], v[26:27] op_sel:[0,0,1] op_sel_hi:[1,0,0]
	v_pk_add_f32 v[26:27], v[18:19], v[28:29]
	v_pk_add_f32 v[18:19], v[18:19], v[28:29] neg_lo:[0,1] neg_hi:[0,1]
	v_pk_add_f32 v[28:29], v[20:21], v[30:31]
	v_pk_add_f32 v[20:21], v[20:21], v[30:31] neg_lo:[0,1] neg_hi:[0,1]
	s_nop 0
	v_pk_mul_f32 v[30:31], v[20:21], s[10:11]
	s_nop 0
	v_pk_fma_f32 v[20:21], v[20:21], s[14:15], v[30:31] op_sel:[0,0,1] op_sel_hi:[1,0,0] neg_lo:[1,0,0] neg_hi:[1,0,0]
	v_pk_add_f32 v[30:31], v[0:1], v[8:9] op_sel:[0,1] op_sel_hi:[1,0] neg_hi:[0,1]
	v_pk_add_f32 v[0:1], v[0:1], v[8:9] op_sel:[0,1] op_sel_hi:[1,0] neg_lo:[0,1]
	v_pk_add_f32 v[8:9], v[2:3], v[10:11]
	v_pk_add_f32 v[2:3], v[2:3], v[10:11] neg_lo:[0,1] neg_hi:[0,1]
	s_nop 0
	v_pk_mul_f32 v[10:11], v[2:3], s[10:11]
	s_nop 0
	v_pk_fma_f32 v[2:3], v[2:3], s[14:15], v[10:11] op_sel:[0,0,1] op_sel_hi:[1,0,0]
	v_pk_add_f32 v[10:11], v[4:5], v[12:13]
	v_pk_add_f32 v[4:5], v[4:5], v[12:13] neg_lo:[0,1] neg_hi:[0,1]
	v_pk_add_f32 v[12:13], v[6:7], v[14:15]
	v_pk_add_f32 v[6:7], v[6:7], v[14:15] neg_lo:[0,1] neg_hi:[0,1]
	s_nop 0
	v_pk_mul_f32 v[14:15], v[6:7], s[10:11]
	s_nop 0
	v_pk_fma_f32 v[6:7], v[6:7], s[14:15], v[14:15] op_sel:[0,0,1] op_sel_hi:[1,0,0] neg_lo:[1,0,0] neg_hi:[1,0,0]
	v_pk_add_f32 v[14:15], v[24:25], v[26:27]
	v_pk_add_f32 v[24:25], v[24:25], v[26:27] neg_lo:[0,1] neg_hi:[0,1]
	v_pk_add_f32 v[26:27], v[86:87], v[28:29]
	v_pk_add_f32 v[28:29], v[86:87], v[28:29] neg_lo:[0,1] neg_hi:[0,1]
	v_pk_add_f32 v[86:87], v[22:23], v[18:19] op_sel:[0,1] op_sel_hi:[1,0] neg_hi:[0,1]
	v_pk_add_f32 v[18:19], v[22:23], v[18:19] op_sel:[0,1] op_sel_hi:[1,0] neg_lo:[0,1]
	v_pk_add_f32 v[22:23], v[16:17], v[20:21]
	v_pk_add_f32 v[16:17], v[16:17], v[20:21] neg_lo:[0,1] neg_hi:[0,1]
	v_pk_add_f32 v[20:21], v[30:31], v[10:11]
	v_pk_add_f32 v[10:11], v[30:31], v[10:11] neg_lo:[0,1] neg_hi:[0,1]
	v_pk_add_f32 v[30:31], v[8:9], v[12:13]
	v_pk_add_f32 v[8:9], v[8:9], v[12:13] neg_lo:[0,1] neg_hi:[0,1]
	v_pk_add_f32 v[12:13], v[0:1], v[4:5] op_sel:[0,1] op_sel_hi:[1,0] neg_hi:[0,1]
	v_pk_add_f32 v[0:1], v[0:1], v[4:5] op_sel:[0,1] op_sel_hi:[1,0] neg_lo:[0,1]
	v_pk_add_f32 v[4:5], v[2:3], v[6:7]
	v_pk_add_f32 v[2:3], v[2:3], v[6:7] neg_lo:[0,1] neg_hi:[0,1]
	s_nop 0
	v_pk_mul_f32 v[2:3], v[2:3], s[22:23]
	v_pk_add_f32 v[6:7], v[14:15], v[26:27]
	v_pk_add_f32 v[14:15], v[14:15], v[26:27] neg_lo:[0,1] neg_hi:[0,1]
	v_pk_add_f32 v[26:27], v[24:25], v[28:29] op_sel:[0,1] op_sel_hi:[1,0] neg_hi:[0,1]
	v_pk_add_f32 v[24:25], v[24:25], v[28:29] op_sel:[0,1] op_sel_hi:[1,0] neg_lo:[0,1]
	v_pk_add_f32 v[28:29], v[86:87], v[22:23]
	v_pk_add_f32 v[22:23], v[86:87], v[22:23] neg_lo:[0,1] neg_hi:[0,1]
	v_pk_add_f32 v[86:87], v[18:19], v[16:17] op_sel:[0,1] op_sel_hi:[1,0] neg_hi:[0,1]
	v_pk_add_f32 v[16:17], v[18:19], v[16:17] op_sel:[0,1] op_sel_hi:[1,0] neg_lo:[0,1]
	v_pk_add_f32 v[18:19], v[20:21], v[30:31]
	v_pk_add_f32 v[20:21], v[20:21], v[30:31] neg_lo:[0,1] neg_hi:[0,1]
	v_pk_add_f32 v[30:31], v[10:11], v[8:9] op_sel:[0,1] op_sel_hi:[1,0] neg_hi:[0,1]
	v_pk_add_f32 v[8:9], v[10:11], v[8:9] op_sel:[0,1] op_sel_hi:[1,0] neg_lo:[0,1]
	v_pk_add_f32 v[10:11], v[12:13], v[4:5]
	v_pk_add_f32 v[4:5], v[12:13], v[4:5] neg_lo:[0,1] neg_hi:[0,1]
	v_pk_add_f32 v[12:13], v[0:1], v[2:3] op_sel:[0,1] op_sel_hi:[1,0]
	v_pk_add_f32 v[0:1], v[0:1], v[2:3] op_sel:[0,1] op_sel_hi:[1,0] neg_lo:[0,1] neg_hi:[0,1]
	v_lshlrev_b32_e32 v2, 4, v41
	v_and_or_b32 v2, v2, s7, v98
	v_ashrrev_i32_e32 v3, 4, v2
	v_lshlrev_b32_e32 v3, 3, v3
	v_lshlrev_b32_e32 v2, 3, v2
	v_add3_u32 v2, 0, v3, v2
	v_add_u32_e32 v3, 0x800, v2
	v_mov_b32_e32 v41, v32
	ds_write2_b64 v2, v[6:7], v[18:19] offset1:34
	ds_write2_b64 v3, v[14:15], v[20:21] offset0:16 offset1:50
	ds_write2_b64 v2, v[26:27], v[30:31] offset0:136 offset1:170
	ds_write2_b64 v3, v[24:25], v[8:9] offset0:152 offset1:186
	ds_write2_b64 v2, v[28:29], v[10:11] offset0:68 offset1:102
	ds_write2_b64 v3, v[22:23], v[4:5] offset0:84 offset1:118
	ds_write2_b64 v2, v[86:87], v[12:13] offset0:204 offset1:238
	ds_write2_b64 v3, v[16:17], v[0:1] offset0:220 offset1:254
	s_waitcnt lgkmcnt(0)
	s_barrier
	s_nop 0
	v_and_b32_e32 v98, 0x1ff, v41
	v_cvt_f32_u32_e32 v24, v98
	v_ashrrev_i32_e32 v0, 4, v41
	v_lshlrev_b32_e32 v0, 3, v0
	v_lshlrev_b32_e32 v1, 3, v41
	v_mul_f32_e32 v92, 0x39000000, v24
	v_sin_f32_e32 v24, v92
	v_cos_f32_e32 v92, v92
	v_add3_u32 v25, 0, v0, v1
	ds_read_b64 v[0:1], v25
	ds_read_b64 v[2:3], v25 offset:4352
	ds_read_b64 v[4:5], v25 offset:8704
	ds_read_b64 v[6:7], v25 offset:13056
	ds_read_b64 v[8:9], v25 offset:17408
	ds_read_b64 v[10:11], v25 offset:21760
	ds_read_b64 v[12:13], v25 offset:26112
	ds_read_b64 v[14:15], v25 offset:30464
	v_xor_b32_e32 v93, 0x80000000, v24
	s_waitcnt lgkmcnt(6)
	v_pk_mul_f32 v[94:95], v[2:3], v[24:25] op_sel:[1,0] op_sel_hi:[0,0] neg_hi:[0,1]
	v_pk_fma_f32 v[2:3], v[2:3], v[92:93], v[94:95] op_sel_hi:[1,0,1]
	v_pk_mul_f32 v[94:95], v[24:25], v[92:93] op_sel:[0,1] op_sel_hi:[0,0] neg_hi:[1,0]
	v_pk_fma_f32 v[94:95], v[92:93], v[92:93], v[94:95] op_sel_hi:[0,1,1]
	ds_read_b64 v[16:17], v25 offset:34816
	ds_read_b64 v[18:19], v25 offset:39168
	ds_read_b64 v[20:21], v25 offset:43520
	ds_read_b64 v[22:23], v25 offset:47872
	s_waitcnt lgkmcnt(9)
	v_pk_mul_f32 v[96:97], v[4:5], v[94:95] op_sel:[1,1] op_sel_hi:[0,1] neg_lo:[0,1]
	v_pk_fma_f32 v[4:5], v[4:5], v[94:95], v[96:97] op_sel_hi:[1,0,1]
	v_pk_mul_f32 v[96:97], v[24:25], v[94:95] op_sel:[0,1] op_sel_hi:[0,0] neg_hi:[1,0]
	v_pk_fma_f32 v[94:95], v[92:93], v[94:95], v[96:97] op_sel_hi:[0,1,1]
	ds_read_b64 v[26:27], v25 offset:52224
	ds_read_b64 v[28:29], v25 offset:56576
	ds_read_b64 v[30:31], v25 offset:60928
	ds_read_b64 v[86:87], v25 offset:65280
	s_waitcnt lgkmcnt(12)
	v_pk_mul_f32 v[96:97], v[6:7], v[94:95] op_sel:[1,1] op_sel_hi:[0,1] neg_lo:[0,1]
	v_pk_fma_f32 v[6:7], v[6:7], v[94:95], v[96:97] op_sel_hi:[1,0,1]
	v_pk_mul_f32 v[96:97], v[24:25], v[94:95] op_sel:[0,1] op_sel_hi:[0,0] neg_hi:[1,0]
	v_pk_fma_f32 v[94:95], v[92:93], v[94:95], v[96:97] op_sel_hi:[0,1,1]
	s_waitcnt lgkmcnt(0)
	v_pk_mul_f32 v[96:97], v[8:9], v[94:95] op_sel:[1,1] op_sel_hi:[0,1] neg_lo:[0,1]
	v_pk_fma_f32 v[8:9], v[8:9], v[94:95], v[96:97] op_sel_hi:[1,0,1]
	v_pk_mul_f32 v[96:97], v[24:25], v[94:95] op_sel:[0,1] op_sel_hi:[0,0] neg_hi:[1,0]
	v_pk_fma_f32 v[94:95], v[92:93], v[94:95], v[96:97] op_sel_hi:[0,1,1]
	s_barrier
	v_pk_mul_f32 v[96:97], v[10:11], v[94:95] op_sel:[1,1] op_sel_hi:[0,1] neg_lo:[0,1]
	v_pk_fma_f32 v[10:11], v[10:11], v[94:95], v[96:97] op_sel_hi:[1,0,1]
	v_pk_mul_f32 v[96:97], v[24:25], v[94:95] op_sel:[0,1] op_sel_hi:[0,0] neg_hi:[1,0]
	v_pk_fma_f32 v[94:95], v[92:93], v[94:95], v[96:97] op_sel_hi:[0,1,1]
	s_nop 0
	v_pk_mul_f32 v[96:97], v[12:13], v[94:95] op_sel:[1,1] op_sel_hi:[0,1] neg_lo:[0,1]
	v_pk_fma_f32 v[12:13], v[12:13], v[94:95], v[96:97] op_sel_hi:[1,0,1]
	v_pk_mul_f32 v[96:97], v[24:25], v[94:95] op_sel:[0,1] op_sel_hi:[0,0] neg_hi:[1,0]
	v_pk_fma_f32 v[94:95], v[92:93], v[94:95], v[96:97] op_sel_hi:[0,1,1]
	s_nop 0
	v_pk_mul_f32 v[96:97], v[14:15], v[94:95] op_sel:[1,1] op_sel_hi:[0,1] neg_lo:[0,1]
	v_pk_fma_f32 v[14:15], v[14:15], v[94:95], v[96:97] op_sel_hi:[1,0,1]
	v_pk_mul_f32 v[96:97], v[24:25], v[94:95] op_sel:[0,1] op_sel_hi:[0,0] neg_hi:[1,0]
	v_pk_fma_f32 v[94:95], v[92:93], v[94:95], v[96:97] op_sel_hi:[0,1,1]
	s_nop 0
	v_pk_mul_f32 v[96:97], v[16:17], v[94:95] op_sel:[1,1] op_sel_hi:[0,1] neg_lo:[0,1]
	v_pk_fma_f32 v[16:17], v[16:17], v[94:95], v[96:97] op_sel_hi:[1,0,1]
	v_pk_mul_f32 v[96:97], v[24:25], v[94:95] op_sel:[0,1] op_sel_hi:[0,0] neg_hi:[1,0]
	v_pk_fma_f32 v[94:95], v[92:93], v[94:95], v[96:97] op_sel_hi:[0,1,1]
	s_nop 0
	v_pk_mul_f32 v[96:97], v[18:19], v[94:95] op_sel:[1,1] op_sel_hi:[0,1] neg_lo:[0,1]
	v_pk_fma_f32 v[18:19], v[18:19], v[94:95], v[96:97] op_sel_hi:[1,0,1]
	v_pk_mul_f32 v[96:97], v[24:25], v[94:95] op_sel:[0,1] op_sel_hi:[0,0] neg_hi:[1,0]
	v_pk_fma_f32 v[94:95], v[92:93], v[94:95], v[96:97] op_sel_hi:[0,1,1]
	s_nop 0
	v_pk_mul_f32 v[96:97], v[20:21], v[94:95] op_sel:[1,1] op_sel_hi:[0,1] neg_lo:[0,1]
	v_pk_fma_f32 v[20:21], v[20:21], v[94:95], v[96:97] op_sel_hi:[1,0,1]
	v_pk_mul_f32 v[96:97], v[24:25], v[94:95] op_sel:[0,1] op_sel_hi:[0,0] neg_hi:[1,0]
	v_pk_fma_f32 v[94:95], v[92:93], v[94:95], v[96:97] op_sel_hi:[0,1,1]
	s_nop 0
	v_pk_mul_f32 v[96:97], v[22:23], v[94:95] op_sel:[1,1] op_sel_hi:[0,1] neg_lo:[0,1]
	v_pk_fma_f32 v[22:23], v[22:23], v[94:95], v[96:97] op_sel_hi:[1,0,1]
	v_pk_mul_f32 v[96:97], v[24:25], v[94:95] op_sel:[0,1] op_sel_hi:[0,0] neg_hi:[1,0]
	v_pk_fma_f32 v[94:95], v[92:93], v[94:95], v[96:97] op_sel_hi:[0,1,1]
	s_nop 0
	v_pk_mul_f32 v[96:97], v[26:27], v[94:95] op_sel:[1,1] op_sel_hi:[0,1] neg_lo:[0,1]
	v_pk_fma_f32 v[26:27], v[26:27], v[94:95], v[96:97] op_sel_hi:[1,0,1]
	v_pk_mul_f32 v[96:97], v[24:25], v[94:95] op_sel:[0,1] op_sel_hi:[0,0] neg_hi:[1,0]
	v_pk_fma_f32 v[94:95], v[92:93], v[94:95], v[96:97] op_sel_hi:[0,1,1]
	s_nop 0
	v_pk_mul_f32 v[96:97], v[28:29], v[94:95] op_sel:[1,1] op_sel_hi:[0,1] neg_lo:[0,1]
	v_pk_fma_f32 v[28:29], v[28:29], v[94:95], v[96:97] op_sel_hi:[1,0,1]
	v_pk_mul_f32 v[96:97], v[24:25], v[94:95] op_sel:[0,1] op_sel_hi:[0,0] neg_hi:[1,0]
	v_pk_fma_f32 v[94:95], v[92:93], v[94:95], v[96:97] op_sel_hi:[0,1,1]
	v_pk_mul_f32 v[24:25], v[24:25], v[94:95] op_sel:[0,1] op_sel_hi:[0,0] neg_hi:[1,0]
	v_pk_fma_f32 v[24:25], v[92:93], v[94:95], v[24:25] op_sel_hi:[0,1,1]
	v_pk_mul_f32 v[92:93], v[86:87], v[24:25] op_sel:[1,1] op_sel_hi:[0,1] neg_lo:[0,1]
	v_pk_fma_f32 v[24:25], v[86:87], v[24:25], v[92:93] op_sel_hi:[1,0,1]
	v_pk_add_f32 v[86:87], v[0:1], v[16:17]
	v_pk_add_f32 v[0:1], v[0:1], v[16:17] neg_lo:[0,1] neg_hi:[0,1]
	v_pk_add_f32 v[16:17], v[2:3], v[18:19]
	v_pk_add_f32 v[2:3], v[2:3], v[18:19] neg_lo:[0,1] neg_hi:[0,1]
	v_pk_mul_f32 v[96:97], v[30:31], v[94:95] op_sel:[1,1] op_sel_hi:[0,1] neg_lo:[0,1]
	v_pk_mul_f32 v[18:19], v[2:3], s[18:19]
	v_pk_fma_f32 v[30:31], v[30:31], v[94:95], v[96:97] op_sel_hi:[1,0,1]
	v_pk_fma_f32 v[2:3], v[2:3], s[30:31], v[18:19] op_sel:[0,0,1] op_sel_hi:[1,0,0]
	v_pk_add_f32 v[18:19], v[4:5], v[20:21]
	v_pk_add_f32 v[4:5], v[4:5], v[20:21] neg_lo:[0,1] neg_hi:[0,1]
	s_nop 0
	v_pk_mul_f32 v[20:21], v[4:5], s[10:11]
	s_nop 0
	v_pk_fma_f32 v[4:5], v[4:5], s[14:15], v[20:21] op_sel:[0,0,1] op_sel_hi:[1,0,0]
	v_pk_add_f32 v[20:21], v[6:7], v[22:23]
	v_pk_add_f32 v[6:7], v[6:7], v[22:23] neg_lo:[0,1] neg_hi:[0,1]
	s_nop 0
	v_pk_mul_f32 v[22:23], v[6:7], s[34:35]
	s_nop 0
	v_pk_fma_f32 v[6:7], v[6:7], s[26:27], v[22:23] op_sel:[0,0,1] op_sel_hi:[1,0,0]
	v_pk_add_f32 v[22:23], v[8:9], v[26:27]
	v_pk_add_f32 v[8:9], v[8:9], v[26:27] neg_lo:[0,1] neg_hi:[0,1]
	v_pk_add_f32 v[26:27], v[10:11], v[28:29]
	v_pk_add_f32 v[10:11], v[10:11], v[28:29] neg_lo:[0,1] neg_hi:[0,1]
	s_nop 0
	v_pk_mul_f32 v[28:29], v[10:11], s[34:35]
	s_nop 0
	v_pk_fma_f32 v[10:11], v[10:11], s[26:27], v[28:29] op_sel:[0,0,1] op_sel_hi:[1,0,0] neg_lo:[1,0,0] neg_hi:[1,0,0]
	v_pk_add_f32 v[28:29], v[12:13], v[30:31]
	v_pk_add_f32 v[12:13], v[12:13], v[30:31] neg_lo:[0,1] neg_hi:[0,1]
	s_nop 0
	v_pk_mul_f32 v[30:31], v[12:13], s[10:11]
	s_nop 0
	v_pk_fma_f32 v[12:13], v[12:13], s[14:15], v[30:31] op_sel:[0,0,1] op_sel_hi:[1,0,0] neg_lo:[1,0,0] neg_hi:[1,0,0]
	v_pk_add_f32 v[30:31], v[14:15], v[24:25]
	v_pk_add_f32 v[14:15], v[14:15], v[24:25] neg_lo:[0,1] neg_hi:[0,1]
	s_nop 0
	v_pk_mul_f32 v[24:25], v[14:15], s[18:19]
	s_nop 0
	v_pk_fma_f32 v[14:15], v[14:15], s[30:31], v[24:25] op_sel:[0,0,1] op_sel_hi:[1,0,0] neg_lo:[1,0,0] neg_hi:[1,0,0]
	v_pk_add_f32 v[24:25], v[86:87], v[22:23]
	v_pk_add_f32 v[22:23], v[86:87], v[22:23] neg_lo:[0,1] neg_hi:[0,1]
	v_pk_add_f32 v[86:87], v[16:17], v[26:27]
	v_pk_add_f32 v[16:17], v[16:17], v[26:27] neg_lo:[0,1] neg_hi:[0,1]
	s_nop 0
	v_pk_mul_f32 v[26:27], v[16:17], s[10:11]
	s_nop 0
	v_pk_fma_f32 v[16:17], v[16:17], s[14:15], v[26:27] op_sel:[0,0,1] op_sel_hi:[1,0,0]
	v_pk_add_f32 v[26:27], v[18:19], v[28:29]
	v_pk_add_f32 v[18:19], v[18:19], v[28:29] neg_lo:[0,1] neg_hi:[0,1]
	v_pk_add_f32 v[28:29], v[20:21], v[30:31]
	v_pk_add_f32 v[20:21], v[20:21], v[30:31] neg_lo:[0,1] neg_hi:[0,1]
	s_nop 0
	v_pk_mul_f32 v[30:31], v[20:21], s[10:11]
	s_nop 0
	v_pk_fma_f32 v[20:21], v[20:21], s[14:15], v[30:31] op_sel:[0,0,1] op_sel_hi:[1,0,0] neg_lo:[1,0,0] neg_hi:[1,0,0]
	v_pk_add_f32 v[30:31], v[0:1], v[8:9] op_sel:[0,1] op_sel_hi:[1,0] neg_hi:[0,1]
	v_pk_add_f32 v[0:1], v[0:1], v[8:9] op_sel:[0,1] op_sel_hi:[1,0] neg_lo:[0,1]
	v_pk_add_f32 v[8:9], v[2:3], v[10:11]
	v_pk_add_f32 v[2:3], v[2:3], v[10:11] neg_lo:[0,1] neg_hi:[0,1]
	s_nop 0
	v_pk_mul_f32 v[10:11], v[2:3], s[10:11]
	s_nop 0
	v_pk_fma_f32 v[2:3], v[2:3], s[14:15], v[10:11] op_sel:[0,0,1] op_sel_hi:[1,0,0]
	v_pk_add_f32 v[10:11], v[4:5], v[12:13]
	v_pk_add_f32 v[4:5], v[4:5], v[12:13] neg_lo:[0,1] neg_hi:[0,1]
	v_pk_add_f32 v[12:13], v[6:7], v[14:15]
	v_pk_add_f32 v[6:7], v[6:7], v[14:15] neg_lo:[0,1] neg_hi:[0,1]
	s_nop 0
	v_pk_mul_f32 v[14:15], v[6:7], s[10:11]
	s_nop 0
	v_pk_fma_f32 v[6:7], v[6:7], s[14:15], v[14:15] op_sel:[0,0,1] op_sel_hi:[1,0,0] neg_lo:[1,0,0] neg_hi:[1,0,0]
	v_pk_add_f32 v[14:15], v[24:25], v[26:27]
	v_pk_add_f32 v[24:25], v[24:25], v[26:27] neg_lo:[0,1] neg_hi:[0,1]
	v_pk_add_f32 v[26:27], v[86:87], v[28:29]
	v_pk_add_f32 v[28:29], v[86:87], v[28:29] neg_lo:[0,1] neg_hi:[0,1]
	v_pk_add_f32 v[86:87], v[22:23], v[18:19] op_sel:[0,1] op_sel_hi:[1,0] neg_hi:[0,1]
	v_pk_add_f32 v[18:19], v[22:23], v[18:19] op_sel:[0,1] op_sel_hi:[1,0] neg_lo:[0,1]
	v_pk_add_f32 v[22:23], v[16:17], v[20:21]
	v_pk_add_f32 v[16:17], v[16:17], v[20:21] neg_lo:[0,1] neg_hi:[0,1]
	v_pk_add_f32 v[20:21], v[30:31], v[10:11]
	v_pk_add_f32 v[10:11], v[30:31], v[10:11] neg_lo:[0,1] neg_hi:[0,1]
	v_pk_add_f32 v[30:31], v[8:9], v[12:13]
	v_pk_add_f32 v[8:9], v[8:9], v[12:13] neg_lo:[0,1] neg_hi:[0,1]
	v_pk_add_f32 v[12:13], v[0:1], v[4:5] op_sel:[0,1] op_sel_hi:[1,0] neg_hi:[0,1]
	v_pk_add_f32 v[0:1], v[0:1], v[4:5] op_sel:[0,1] op_sel_hi:[1,0] neg_lo:[0,1]
	v_pk_add_f32 v[4:5], v[2:3], v[6:7]
	v_pk_add_f32 v[2:3], v[2:3], v[6:7] neg_lo:[0,1] neg_hi:[0,1]
	s_nop 0
	v_pk_mul_f32 v[2:3], v[2:3], s[22:23]
	v_pk_add_f32 v[6:7], v[14:15], v[26:27]
	v_pk_add_f32 v[14:15], v[14:15], v[26:27] neg_lo:[0,1] neg_hi:[0,1]
	v_pk_add_f32 v[26:27], v[24:25], v[28:29] op_sel:[0,1] op_sel_hi:[1,0] neg_hi:[0,1]
	v_pk_add_f32 v[24:25], v[24:25], v[28:29] op_sel:[0,1] op_sel_hi:[1,0] neg_lo:[0,1]
	v_pk_add_f32 v[28:29], v[86:87], v[22:23]
	v_pk_add_f32 v[22:23], v[86:87], v[22:23] neg_lo:[0,1] neg_hi:[0,1]
	v_pk_add_f32 v[86:87], v[18:19], v[16:17] op_sel:[0,1] op_sel_hi:[1,0] neg_hi:[0,1]
	v_pk_add_f32 v[16:17], v[18:19], v[16:17] op_sel:[0,1] op_sel_hi:[1,0] neg_lo:[0,1]
	v_pk_add_f32 v[18:19], v[20:21], v[30:31]
	v_pk_add_f32 v[20:21], v[20:21], v[30:31] neg_lo:[0,1] neg_hi:[0,1]
	v_pk_add_f32 v[30:31], v[10:11], v[8:9] op_sel:[0,1] op_sel_hi:[1,0] neg_hi:[0,1]
	v_pk_add_f32 v[8:9], v[10:11], v[8:9] op_sel:[0,1] op_sel_hi:[1,0] neg_lo:[0,1]
	v_pk_add_f32 v[10:11], v[12:13], v[4:5]
	v_pk_add_f32 v[4:5], v[12:13], v[4:5] neg_lo:[0,1] neg_hi:[0,1]
	v_pk_add_f32 v[12:13], v[0:1], v[2:3] op_sel:[0,1] op_sel_hi:[1,0]
	v_pk_add_f32 v[0:1], v[0:1], v[2:3] op_sel:[0,1] op_sel_hi:[1,0] neg_lo:[0,1] neg_hi:[0,1]
	v_lshlrev_b32_e32 v2, 4, v41
	v_and_or_b32 v2, v2, s15, v98
	v_ashrrev_i32_e32 v3, 4, v2
	v_lshlrev_b32_e32 v3, 3, v3
	v_lshlrev_b32_e32 v2, 3, v2
	v_add3_u32 v2, 0, v3, v2
	ds_write_b64 v2, v[6:7]
	ds_write_b64 v2, v[14:15] offset:34816
	ds_write_b64 v2, v[26:27] offset:17408
	ds_write_b64 v2, v[24:25] offset:52224
	ds_write_b64 v2, v[28:29] offset:8704
	ds_write_b64 v2, v[22:23] offset:43520
	ds_write_b64 v2, v[86:87] offset:26112
	ds_write_b64 v2, v[16:17] offset:60928
	ds_write_b64 v2, v[18:19] offset:4352
	ds_write_b64 v2, v[20:21] offset:39168
	ds_write_b64 v2, v[30:31] offset:21760
	ds_write_b64 v2, v[8:9] offset:56576
	ds_write_b64 v2, v[10:11] offset:13056
	ds_write_b64 v2, v[4:5] offset:47872
	ds_write_b64 v2, v[12:13] offset:30464
	ds_write_b64 v2, v[0:1] offset:65280
	s_waitcnt lgkmcnt(0)
	s_barrier
	s_and_saveexec_b64 s[28:29], s[40:41]
	s_cbranch_execz .LBB0_633
	s_add_u32 s4, s38, 0x400000
	s_addc_u32 s5, s39, 0
	v_lshl_add_u64 v[0:1], v[48:49], 1, s[4:5]
	global_load_dwordx4 v[8:11], v[0:1], off offset:16
	global_load_dwordx4 v[12:15], v[0:1], off
	v_mov_b32_e32 v19, 0
	v_mov_b32_e32 v18, 0
	v_mov_b32_e32 v86, 0
	s_and_saveexec_b64 s[8:9], s[42:43]
	s_cbranch_execz .LBB0_626
	v_lshl_add_u64 v[2:3], v[172:173], 1, s[4:5]
	global_load_ushort v86, v[2:3], off offset:-2
.LBB0_626:
	s_or_b64 exec, exec, s[8:9]
	v_mov_b32_e32 v87, 0
	s_and_saveexec_b64 s[4:5], s[44:45]
	s_cbranch_execz .LBB0_628
	global_load_ushort v87, v[0:1], off offset:32
.LBB0_628:
	s_or_b64 exec, exec, s[4:5]
	s_add_u32 s4, s38, 0x1000000
	s_addc_u32 s5, s39, 0
	v_lshl_add_u64 v[16:17], v[48:49], 1, s[4:5]
	global_load_dwordx4 v[0:3], v[16:17], off offset:16
	global_load_dwordx4 v[4:7], v[16:17], off
	v_mov_b32_e32 v41, 0
	v_mov_b32_e32 v21, 0
	v_mov_b32_e32 v92, 0
	s_and_saveexec_b64 s[8:9], s[42:43]
	s_cbranch_execz .LBB0_630
	v_lshl_add_u64 v[20:21], v[172:173], 1, s[4:5]
	global_load_ushort v92, v[20:21], off offset:-2
.LBB0_630:
	s_or_b64 exec, exec, s[8:9]
	v_mov_b32_e32 v93, 0
	s_and_saveexec_b64 s[4:5], s[44:45]
	s_cbranch_execz .LBB0_632
	global_load_ushort v93, v[16:17], off offset:32
.LBB0_632:
	s_or_b64 exec, exec, s[4:5]
	s_waitcnt vmcnt(0)
	v_lshlrev_b32_e32 v18, 16, v86
	v_lshlrev_b32_e32 v19, 16, v87
	v_lshlrev_b32_e32 v21, 16, v92
	v_lshlrev_b32_e32 v41, 16, v93
	v_lshlrev_b32_e32 v17, 16, v13
	v_and_b32_e32 v13, 0xffff0000, v13
	v_lshlrev_b32_e32 v20, 16, v14
	v_lshlrev_b32_e32 v23, 16, v8
	v_and_b32_e32 v8, 0xffff0000, v8
	v_fma_f32 v30, v147, v13, v146
	v_lshlrev_b32_e32 v16, 16, v12
	v_and_b32_e32 v14, 0xffff0000, v14
	v_lshlrev_b32_e32 v25, 16, v9
	v_and_b32_e32 v9, 0xffff0000, v9
	v_fma_f32 v100, v147, v18, v146
	v_fmac_f32_e32 v30, v42, v20
	v_fma_f32 v28, v147, v20, v146
	v_fma_f32 v18, v147, v8, v146
	s_waitcnt vmcnt(0)
	v_and_b32_e32 v86, 0xffff0000, v4
	v_and_b32_e32 v12, 0xffff0000, v12
	v_lshlrev_b32_e32 v22, 16, v15
	v_and_b32_e32 v15, 0xffff0000, v15
	v_lshlrev_b32_e32 v27, 16, v10
	v_fmac_f32_e32 v100, v42, v16
	v_fma_f32 v98, v147, v16, v146
	v_fma_f32 v94, v147, v17, v146
	v_fmac_f32_e32 v30, v43, v14
	v_fmac_f32_e32 v28, v42, v14
	v_fma_f32 v26, v147, v14, v146
	v_fmac_f32_e32 v18, v42, v25
	v_fma_f32 v16, v147, v25, v146
	v_fma_f32 v14, v147, v9, v146
	v_lshlrev_b32_e32 v93, 16, v4
	v_mov_b32_e32 v92, v86
	v_and_b32_e32 v10, 0xffff0000, v10
	v_fmac_f32_e32 v100, v43, v12
	v_fmac_f32_e32 v98, v42, v12
	v_fma_f32 v96, v147, v12, v146
	v_fmac_f32_e32 v94, v42, v13
	v_fmac_f32_e32 v28, v43, v22
	v_fmac_f32_e32 v26, v42, v22
	v_fma_f32 v24, v147, v22, v146
	v_fma_f32 v22, v147, v15, v146
	v_fmac_f32_e32 v18, v43, v9
	v_fmac_f32_e32 v16, v42, v9
	v_fmac_f32_e32 v14, v42, v27
	v_fma_f32 v12, v147, v27, v146
	v_fma_f32 v9, v147, v21, v146
	v_pk_mul_f32 v[102:103], v[52:53], v[92:93]
	v_lshlrev_b32_e32 v29, 16, v11
	v_fmac_f32_e32 v94, v43, v20
	v_fmac_f32_e32 v22, v42, v23
	v_fma_f32 v20, v147, v23, v146
	v_fmac_f32_e32 v14, v43, v10
	v_fmac_f32_e32 v12, v42, v10
	v_fma_f32 v10, v147, v10, v146
	v_and_b32_e32 v87, 16, v4
	v_add_f32_e32 v4, v103, v9
	v_and_b32_e32 v92, 0xffff0000, v5
	v_and_b32_e32 v11, 0xffff0000, v11
	v_fmac_f32_e32 v22, v43, v8
	v_fmac_f32_e32 v20, v42, v8
	v_fmac_f32_e32 v10, v42, v29
	v_fma_f32 v8, v147, v29, v146
	v_add_f32_e32 v101, v102, v4
	v_fma_f32 v9, v147, v93, v146
	v_and_b32_e32 v93, 16, v5
	v_lshlrev_b32_e32 v5, 16, v5
	v_mov_b32_e32 v4, v92
	v_fmac_f32_e32 v10, v43, v11
	v_fmac_f32_e32 v8, v42, v11
	v_fma_f32 v11, v147, v86, v146
	v_pk_mov_b32 v[86:87], v[4:5], v[86:87] op_sel:[1,0]
	v_fmac_f32_e32 v12, v43, v29
	v_pk_mul_f32 v[86:87], v[52:53], v[86:87]
	v_fmac_f32_e32 v16, v43, v27
	v_add_f32_e32 v9, v87, v9
	v_add_f32_e32 v99, v86, v9
	v_pk_mul_f32 v[86:87], v[52:53], v[4:5]
	v_fma_f32 v9, v147, v5, v146
	v_add_f32_e32 v4, v87, v11
	v_add_f32_e32 v97, v86, v4
	v_and_b32_e32 v4, 0xffff0000, v6
	v_lshlrev_b32_e32 v87, 16, v6
	v_mov_b32_e32 v86, v4
	v_fma_f32 v11, v147, v92, v146
	v_pk_mov_b32 v[92:93], v[86:87], v[92:93] op_sel:[1,0]
	v_and_b32_e32 v5, 16, v6
	v_pk_mul_f32 v[92:93], v[52:53], v[92:93]
	v_fmac_f32_e32 v20, v43, v25
	v_add_f32_e32 v6, v93, v9
	v_add_f32_e32 v95, v92, v6
	v_pk_mul_f32 v[92:93], v[52:53], v[86:87]
	v_and_b32_e32 v86, 0xffff0000, v7
	v_add_f32_e32 v6, v93, v11
	v_add_f32_e32 v31, v92, v6
	v_fma_f32 v9, v147, v87, v146
	v_and_b32_e32 v87, 16, v7
	v_lshlrev_b32_e32 v7, 16, v7
	v_mov_b32_e32 v6, v86
	v_fma_f32 v11, v147, v4, v146
	v_pk_mov_b32 v[4:5], v[6:7], v[4:5] op_sel:[1,0]
	v_fmac_f32_e32 v24, v42, v15
	v_pk_mul_f32 v[4:5], v[52:53], v[4:5]
	v_fmac_f32_e32 v24, v43, v23
	v_add_f32_e32 v5, v5, v9
	v_add_f32_e32 v29, v4, v5
	v_pk_mul_f32 v[4:5], v[52:53], v[6:7]
	v_fma_f32 v9, v147, v7, v146
	v_add_f32_e32 v5, v5, v11
	v_add_f32_e32 v27, v4, v5
	v_and_b32_e32 v4, 0xffff0000, v0
	v_lshlrev_b32_e32 v7, 16, v0
	v_mov_b32_e32 v6, v4
	v_fma_f32 v11, v147, v86, v146
	v_pk_mov_b32 v[86:87], v[6:7], v[86:87] op_sel:[1,0]
	v_and_b32_e32 v5, 16, v0
	v_pk_mul_f32 v[86:87], v[52:53], v[86:87]
	v_fmac_f32_e32 v8, v43, v19
	v_add_f32_e32 v0, v87, v9
	v_add_f32_e32 v25, v86, v0
	v_pk_mul_f32 v[86:87], v[52:53], v[6:7]
	v_and_b32_e32 v6, 0xffff0000, v1
	v_add_f32_e32 v0, v11, v87
	v_add_f32_e32 v23, v86, v0
	v_fma_f32 v9, v147, v7, v146
	v_and_b32_e32 v7, 16, v1
	v_lshlrev_b32_e32 v1, 16, v1
	v_mov_b32_e32 v0, v6
	v_fma_f32 v11, v147, v4, v146
	v_pk_mov_b32 v[4:5], v[0:1], v[4:5] op_sel:[1,0]
	v_fmac_f32_e32 v98, v43, v17
	v_pk_mul_f32 v[4:5], v[52:53], v[4:5]
	v_fmac_f32_e32 v96, v42, v17
	v_add_f32_e32 v5, v5, v9
	v_add_f32_e32 v21, v4, v5
	v_pk_mul_f32 v[4:5], v[52:53], v[0:1]
	v_fma_f32 v9, v147, v1, v146
	v_add_f32_e32 v0, v5, v11
	v_add_f32_e32 v19, v4, v0
	v_and_b32_e32 v0, 0xffff0000, v2
	v_lshlrev_b32_e32 v5, 16, v2
	v_mov_b32_e32 v4, v0
	v_fma_f32 v11, v147, v6, v146
	v_pk_mov_b32 v[6:7], v[4:5], v[6:7] op_sel:[1,0]
	v_and_b32_e32 v1, 16, v2
	v_pk_mul_f32 v[6:7], v[52:53], v[6:7]
	v_fmac_f32_e32 v26, v43, v15
	v_add_f32_e32 v2, v7, v9
	v_add_f32_e32 v17, v6, v2
	v_pk_mul_f32 v[6:7], v[52:53], v[4:5]
	v_fma_f32 v4, v147, v5, v146
	v_add_f32_e32 v2, v7, v11
	v_add_f32_e32 v15, v6, v2
	v_and_b32_e32 v2, 0xffff0000, v3
	v_lshlrev_b32_e32 v3, 16, v3
	v_fma_f32 v5, v147, v0, v146
	v_pk_mov_b32 v[0:1], v[2:3], v[0:1] op_sel:[1,0]
	v_fmac_f32_e32 v96, v43, v13
	v_pk_mul_f32 v[0:1], v[52:53], v[0:1]
	s_nop 0
	v_add_f32_e32 v1, v1, v4
	v_add_f32_e32 v13, v0, v1
	v_pk_mul_f32 v[0:1], v[52:53], v[2:3]
	v_fma_f32 v4, v147, v3, v146
	v_add_f32_e32 v1, v1, v5
	v_mov_b32_e32 v3, v41
	v_add_f32_e32 v11, v0, v1
	v_pk_mul_f32 v[0:1], v[42:43], v[2:3]
	s_nop 0
	v_add_f32_e32 v0, v0, v4
	v_add_f32_e32 v9, v0, v1

.LBB0_675:
	s_or_b64 exec, exec, s[4:5]
	v_mov_b32_e32 v41, v32
	s_waitcnt lgkmcnt(0)
	s_barrier
	s_mov_b32 s11, s14
	v_and_b32_e32 v98, 31, v41
	v_cvt_f32_ubyte0_e32 v24, v98
	v_mul_f32_e32 v60, 0x3b000000, v24
	v_sin_f32_e32 v24, v60
	v_ashrrev_i32_e32 v0, 4, v41
	v_lshlrev_b32_e32 v0, 3, v0
	v_lshlrev_b32_e32 v1, 3, v41
	v_cos_f32_e32 v60, v60
	v_add3_u32 v25, 0, v0, v1
	ds_read_b64 v[0:1], v25
	ds_read_b64 v[2:3], v25 offset:4352
	ds_read_b64 v[4:5], v25 offset:8704
	ds_read_b64 v[6:7], v25 offset:13056
	ds_read_b64 v[8:9], v25 offset:17408
	ds_read_b64 v[10:11], v25 offset:21760
	ds_read_b64 v[12:13], v25 offset:26112
	ds_read_b64 v[14:15], v25 offset:30464
	ds_read_b64 v[16:17], v25 offset:34816
	ds_read_b64 v[18:19], v25 offset:39168
	ds_read_b64 v[20:21], v25 offset:43520
	ds_read_b64 v[22:23], v25 offset:47872
	v_xor_b32_e32 v61, 0x80000000, v24
	s_waitcnt lgkmcnt(10)
	v_pk_mul_f32 v[94:95], v[2:3], v[24:25] op_sel:[1,0] op_sel_hi:[0,0] neg_hi:[0,1]
	v_pk_fma_f32 v[2:3], v[2:3], v[60:61], v[94:95] op_sel_hi:[1,0,1]
	v_pk_mul_f32 v[94:95], v[24:25], v[60:61] op_sel:[0,1] op_sel_hi:[0,0] neg_hi:[1,0]
	v_pk_fma_f32 v[94:95], v[60:61], v[60:61], v[94:95] op_sel_hi:[0,1,1]
	ds_read_b64 v[26:27], v25 offset:52224
	ds_read_b64 v[28:29], v25 offset:56576
	ds_read_b64 v[30:31], v25 offset:60928
	ds_read_b64 v[58:59], v25 offset:65280
	s_waitcnt lgkmcnt(13)
	v_pk_mul_f32 v[96:97], v[4:5], v[94:95] op_sel:[1,1] op_sel_hi:[0,1] neg_lo:[0,1]
	v_pk_fma_f32 v[4:5], v[4:5], v[94:95], v[96:97] op_sel_hi:[1,0,1]
	v_pk_mul_f32 v[96:97], v[24:25], v[94:95] op_sel:[0,1] op_sel_hi:[0,0] neg_hi:[1,0]
	v_pk_fma_f32 v[94:95], v[60:61], v[94:95], v[96:97] op_sel_hi:[0,1,1]
	s_mov_b32 s35, s30
	s_waitcnt lgkmcnt(12)
	v_pk_mul_f32 v[96:97], v[6:7], v[94:95] op_sel:[1,1] op_sel_hi:[0,1] neg_lo:[0,1]
	v_pk_fma_f32 v[6:7], v[6:7], v[94:95], v[96:97] op_sel_hi:[1,0,1]
	v_pk_mul_f32 v[96:97], v[24:25], v[94:95] op_sel:[0,1] op_sel_hi:[0,0] neg_hi:[1,0]
	v_pk_fma_f32 v[94:95], v[60:61], v[94:95], v[96:97] op_sel_hi:[0,1,1]
	s_mov_b32 s26, s19
	s_waitcnt lgkmcnt(11)
	v_pk_mul_f32 v[96:97], v[8:9], v[94:95] op_sel:[1,1] op_sel_hi:[0,1] neg_lo:[0,1]
	v_pk_fma_f32 v[8:9], v[8:9], v[94:95], v[96:97] op_sel_hi:[1,0,1]
	v_pk_mul_f32 v[96:97], v[24:25], v[94:95] op_sel:[0,1] op_sel_hi:[0,0] neg_hi:[1,0]
	v_pk_fma_f32 v[94:95], v[60:61], v[94:95], v[96:97] op_sel_hi:[0,1,1]
	s_waitcnt lgkmcnt(0)
	v_pk_mul_f32 v[96:97], v[10:11], v[94:95] op_sel:[1,1] op_sel_hi:[0,1] neg_lo:[0,1]
	v_pk_fma_f32 v[10:11], v[10:11], v[94:95], v[96:97] op_sel_hi:[1,0,1]
	v_pk_mul_f32 v[96:97], v[24:25], v[94:95] op_sel:[0,1] op_sel_hi:[0,0] neg_hi:[1,0]
	v_pk_fma_f32 v[94:95], v[60:61], v[94:95], v[96:97] op_sel_hi:[0,1,1]
	s_barrier
	v_pk_mul_f32 v[96:97], v[12:13], v[94:95] op_sel:[1,1] op_sel_hi:[0,1] neg_lo:[0,1]
	v_pk_fma_f32 v[12:13], v[12:13], v[94:95], v[96:97] op_sel_hi:[1,0,1]
	v_pk_mul_f32 v[96:97], v[24:25], v[94:95] op_sel:[0,1] op_sel_hi:[0,0] neg_hi:[1,0]
	v_pk_fma_f32 v[94:95], v[60:61], v[94:95], v[96:97] op_sel_hi:[0,1,1]
	s_nop 0
	v_pk_mul_f32 v[96:97], v[14:15], v[94:95] op_sel:[1,1] op_sel_hi:[0,1] neg_lo:[0,1]
	v_pk_fma_f32 v[14:15], v[14:15], v[94:95], v[96:97] op_sel_hi:[1,0,1]
	v_pk_mul_f32 v[96:97], v[24:25], v[94:95] op_sel:[0,1] op_sel_hi:[0,0] neg_hi:[1,0]
	v_pk_fma_f32 v[94:95], v[60:61], v[94:95], v[96:97] op_sel_hi:[0,1,1]
	s_nop 0
	v_pk_mul_f32 v[96:97], v[16:17], v[94:95] op_sel:[1,1] op_sel_hi:[0,1] neg_lo:[0,1]
	v_pk_fma_f32 v[16:17], v[16:17], v[94:95], v[96:97] op_sel_hi:[1,0,1]
	v_pk_mul_f32 v[96:97], v[24:25], v[94:95] op_sel:[0,1] op_sel_hi:[0,0] neg_hi:[1,0]
	v_pk_fma_f32 v[94:95], v[60:61], v[94:95], v[96:97] op_sel_hi:[0,1,1]
	s_nop 0
	v_pk_mul_f32 v[96:97], v[18:19], v[94:95] op_sel:[1,1] op_sel_hi:[0,1] neg_lo:[0,1]
	v_pk_fma_f32 v[18:19], v[18:19], v[94:95], v[96:97] op_sel_hi:[1,0,1]
	v_pk_mul_f32 v[96:97], v[24:25], v[94:95] op_sel:[0,1] op_sel_hi:[0,0] neg_hi:[1,0]
	v_pk_fma_f32 v[94:95], v[60:61], v[94:95], v[96:97] op_sel_hi:[0,1,1]
	s_nop 0
	v_pk_mul_f32 v[96:97], v[20:21], v[94:95] op_sel:[1,1] op_sel_hi:[0,1] neg_lo:[0,1]
	v_pk_fma_f32 v[20:21], v[20:21], v[94:95], v[96:97] op_sel_hi:[1,0,1]
	v_pk_mul_f32 v[96:97], v[24:25], v[94:95] op_sel:[0,1] op_sel_hi:[0,0] neg_hi:[1,0]
	v_pk_fma_f32 v[94:95], v[60:61], v[94:95], v[96:97] op_sel_hi:[0,1,1]
	s_nop 0
	v_pk_mul_f32 v[96:97], v[22:23], v[94:95] op_sel:[1,1] op_sel_hi:[0,1] neg_lo:[0,1]
	v_pk_fma_f32 v[22:23], v[22:23], v[94:95], v[96:97] op_sel_hi:[1,0,1]
	v_pk_mul_f32 v[96:97], v[24:25], v[94:95] op_sel:[0,1] op_sel_hi:[0,0] neg_hi:[1,0]
	v_pk_fma_f32 v[94:95], v[60:61], v[94:95], v[96:97] op_sel_hi:[0,1,1]
	s_nop 0
	v_pk_mul_f32 v[96:97], v[26:27], v[94:95] op_sel:[1,1] op_sel_hi:[0,1] neg_lo:[0,1]
	v_pk_fma_f32 v[26:27], v[26:27], v[94:95], v[96:97] op_sel_hi:[1,0,1]
	v_pk_mul_f32 v[96:97], v[24:25], v[94:95] op_sel:[0,1] op_sel_hi:[0,0] neg_hi:[1,0]
	v_pk_fma_f32 v[94:95], v[60:61], v[94:95], v[96:97] op_sel_hi:[0,1,1]
	s_nop 0
	v_pk_mul_f32 v[96:97], v[28:29], v[94:95] op_sel:[1,1] op_sel_hi:[0,1] neg_lo:[0,1]
	v_pk_fma_f32 v[28:29], v[28:29], v[94:95], v[96:97] op_sel_hi:[1,0,1]
	v_pk_mul_f32 v[96:97], v[24:25], v[94:95] op_sel:[0,1] op_sel_hi:[0,0] neg_hi:[1,0]
	v_pk_fma_f32 v[94:95], v[60:61], v[94:95], v[96:97] op_sel_hi:[0,1,1]
	v_pk_mul_f32 v[24:25], v[24:25], v[94:95] op_sel:[0,1] op_sel_hi:[0,0] neg_hi:[1,0]
	v_pk_fma_f32 v[24:25], v[60:61], v[94:95], v[24:25] op_sel_hi:[0,1,1]
	v_pk_mul_f32 v[60:61], v[58:59], v[24:25] op_sel:[1,1] op_sel_hi:[0,1] neg_lo:[0,1]
	v_pk_fma_f32 v[24:25], v[58:59], v[24:25], v[60:61] op_sel_hi:[1,0,1]
	v_pk_add_f32 v[58:59], v[0:1], v[16:17]
	v_pk_add_f32 v[0:1], v[0:1], v[16:17] neg_lo:[0,1] neg_hi:[0,1]
	v_pk_add_f32 v[16:17], v[2:3], v[18:19]
	v_pk_add_f32 v[2:3], v[2:3], v[18:19] neg_lo:[0,1] neg_hi:[0,1]
	v_pk_mul_f32 v[96:97], v[30:31], v[94:95] op_sel:[1,1] op_sel_hi:[0,1] neg_lo:[0,1]
	v_pk_mul_f32 v[18:19], v[2:3], s[18:19]
	v_pk_fma_f32 v[30:31], v[30:31], v[94:95], v[96:97] op_sel_hi:[1,0,1]
	v_pk_fma_f32 v[2:3], v[2:3], s[30:31], v[18:19] op_sel:[0,0,1] op_sel_hi:[1,0,0]
	v_pk_add_f32 v[18:19], v[4:5], v[20:21]
	v_pk_add_f32 v[4:5], v[4:5], v[20:21] neg_lo:[0,1] neg_hi:[0,1]
	s_nop 0
	v_pk_mul_f32 v[20:21], v[4:5], s[10:11]
	s_nop 0
	v_pk_fma_f32 v[4:5], v[4:5], s[14:15], v[20:21] op_sel:[0,0,1] op_sel_hi:[1,0,0]
	v_pk_add_f32 v[20:21], v[6:7], v[22:23]
	v_pk_add_f32 v[6:7], v[6:7], v[22:23] neg_lo:[0,1] neg_hi:[0,1]
	s_nop 0
	v_pk_mul_f32 v[22:23], v[6:7], s[34:35]
	s_nop 0
	v_pk_fma_f32 v[6:7], v[6:7], s[26:27], v[22:23] op_sel:[0,0,1] op_sel_hi:[1,0,0]
	v_pk_add_f32 v[22:23], v[8:9], v[26:27]
	v_pk_add_f32 v[8:9], v[8:9], v[26:27] neg_lo:[0,1] neg_hi:[0,1]
	v_pk_add_f32 v[26:27], v[10:11], v[28:29]
	v_pk_add_f32 v[10:11], v[10:11], v[28:29] neg_lo:[0,1] neg_hi:[0,1]
	s_nop 0
	v_pk_mul_f32 v[28:29], v[10:11], s[34:35]
	s_nop 0
	v_pk_fma_f32 v[10:11], v[10:11], s[26:27], v[28:29] op_sel:[0,0,1] op_sel_hi:[1,0,0] neg_lo:[1,0,0] neg_hi:[1,0,0]
	v_pk_add_f32 v[28:29], v[12:13], v[30:31]
	v_pk_add_f32 v[12:13], v[12:13], v[30:31] neg_lo:[0,1] neg_hi:[0,1]
	s_nop 0
	v_pk_mul_f32 v[30:31], v[12:13], s[10:11]
	s_nop 0
	v_pk_fma_f32 v[12:13], v[12:13], s[14:15], v[30:31] op_sel:[0,0,1] op_sel_hi:[1,0,0] neg_lo:[1,0,0] neg_hi:[1,0,0]
	v_pk_add_f32 v[30:31], v[14:15], v[24:25]
	v_pk_add_f32 v[14:15], v[14:15], v[24:25] neg_lo:[0,1] neg_hi:[0,1]
	s_nop 0
	v_pk_mul_f32 v[24:25], v[14:15], s[18:19]
	s_nop 0
	v_pk_fma_f32 v[14:15], v[14:15], s[30:31], v[24:25] op_sel:[0,0,1] op_sel_hi:[1,0,0] neg_lo:[1,0,0] neg_hi:[1,0,0]
	v_pk_add_f32 v[24:25], v[58:59], v[22:23]
	v_pk_add_f32 v[22:23], v[58:59], v[22:23] neg_lo:[0,1] neg_hi:[0,1]
	v_pk_add_f32 v[58:59], v[16:17], v[26:27]
	v_pk_add_f32 v[16:17], v[16:17], v[26:27] neg_lo:[0,1] neg_hi:[0,1]
	s_nop 0
	v_pk_mul_f32 v[26:27], v[16:17], s[10:11]
	s_nop 0
	v_pk_fma_f32 v[16:17], v[16:17], s[14:15], v[26:27] op_sel:[0,0,1] op_sel_hi:[1,0,0]
	v_pk_add_f32 v[26:27], v[18:19], v[28:29]
	v_pk_add_f32 v[18:19], v[18:19], v[28:29] neg_lo:[0,1] neg_hi:[0,1]
	v_pk_add_f32 v[28:29], v[20:21], v[30:31]
	v_pk_add_f32 v[20:21], v[20:21], v[30:31] neg_lo:[0,1] neg_hi:[0,1]
	s_nop 0
	v_pk_mul_f32 v[30:31], v[20:21], s[10:11]
	s_nop 0
	v_pk_fma_f32 v[20:21], v[20:21], s[14:15], v[30:31] op_sel:[0,0,1] op_sel_hi:[1,0,0] neg_lo:[1,0,0] neg_hi:[1,0,0]
	v_pk_add_f32 v[30:31], v[0:1], v[8:9] op_sel:[0,1] op_sel_hi:[1,0] neg_hi:[0,1]
	v_pk_add_f32 v[0:1], v[0:1], v[8:9] op_sel:[0,1] op_sel_hi:[1,0] neg_lo:[0,1]
	v_pk_add_f32 v[8:9], v[2:3], v[10:11]
	v_pk_add_f32 v[2:3], v[2:3], v[10:11] neg_lo:[0,1] neg_hi:[0,1]
	s_nop 0
	v_pk_mul_f32 v[10:11], v[2:3], s[10:11]
	s_nop 0
	v_pk_fma_f32 v[2:3], v[2:3], s[14:15], v[10:11] op_sel:[0,0,1] op_sel_hi:[1,0,0]
	v_pk_add_f32 v[10:11], v[4:5], v[12:13]
	v_pk_add_f32 v[4:5], v[4:5], v[12:13] neg_lo:[0,1] neg_hi:[0,1]
	v_pk_add_f32 v[12:13], v[6:7], v[14:15]
	v_pk_add_f32 v[6:7], v[6:7], v[14:15] neg_lo:[0,1] neg_hi:[0,1]
	s_nop 0
	v_pk_mul_f32 v[14:15], v[6:7], s[10:11]
	s_nop 0
	v_pk_fma_f32 v[6:7], v[6:7], s[14:15], v[14:15] op_sel:[0,0,1] op_sel_hi:[1,0,0] neg_lo:[1,0,0] neg_hi:[1,0,0]
	v_pk_add_f32 v[14:15], v[24:25], v[26:27]
	v_pk_add_f32 v[24:25], v[24:25], v[26:27] neg_lo:[0,1] neg_hi:[0,1]
	v_pk_add_f32 v[26:27], v[58:59], v[28:29]
	v_pk_add_f32 v[28:29], v[58:59], v[28:29] neg_lo:[0,1] neg_hi:[0,1]
	v_pk_add_f32 v[58:59], v[22:23], v[18:19] op_sel:[0,1] op_sel_hi:[1,0] neg_hi:[0,1]
	v_pk_add_f32 v[18:19], v[22:23], v[18:19] op_sel:[0,1] op_sel_hi:[1,0] neg_lo:[0,1]
	v_pk_add_f32 v[22:23], v[16:17], v[20:21]
	v_pk_add_f32 v[16:17], v[16:17], v[20:21] neg_lo:[0,1] neg_hi:[0,1]
	v_pk_add_f32 v[20:21], v[30:31], v[10:11]
	v_pk_add_f32 v[10:11], v[30:31], v[10:11] neg_lo:[0,1] neg_hi:[0,1]
	v_pk_add_f32 v[30:31], v[8:9], v[12:13]
	v_pk_add_f32 v[8:9], v[8:9], v[12:13] neg_lo:[0,1] neg_hi:[0,1]
	v_pk_add_f32 v[12:13], v[0:1], v[4:5] op_sel:[0,1] op_sel_hi:[1,0] neg_hi:[0,1]
	v_pk_add_f32 v[0:1], v[0:1], v[4:5] op_sel:[0,1] op_sel_hi:[1,0] neg_lo:[0,1]
	v_pk_add_f32 v[4:5], v[2:3], v[6:7]
	v_pk_add_f32 v[2:3], v[2:3], v[6:7] neg_lo:[0,1] neg_hi:[0,1]
	s_nop 0
	v_pk_mul_f32 v[2:3], v[2:3], s[22:23]
	v_pk_add_f32 v[6:7], v[14:15], v[26:27]
	v_pk_add_f32 v[14:15], v[14:15], v[26:27] neg_lo:[0,1] neg_hi:[0,1]
	v_pk_add_f32 v[26:27], v[24:25], v[28:29] op_sel:[0,1] op_sel_hi:[1,0] neg_hi:[0,1]
	v_pk_add_f32 v[24:25], v[24:25], v[28:29] op_sel:[0,1] op_sel_hi:[1,0] neg_lo:[0,1]
	v_pk_add_f32 v[28:29], v[58:59], v[22:23]
	v_pk_add_f32 v[22:23], v[58:59], v[22:23] neg_lo:[0,1] neg_hi:[0,1]
	v_pk_add_f32 v[58:59], v[18:19], v[16:17] op_sel:[0,1] op_sel_hi:[1,0] neg_hi:[0,1]
	v_pk_add_f32 v[16:17], v[18:19], v[16:17] op_sel:[0,1] op_sel_hi:[1,0] neg_lo:[0,1]
	v_pk_add_f32 v[18:19], v[20:21], v[30:31]
	v_pk_add_f32 v[20:21], v[20:21], v[30:31] neg_lo:[0,1] neg_hi:[0,1]
	v_pk_add_f32 v[30:31], v[10:11], v[8:9] op_sel:[0,1] op_sel_hi:[1,0] neg_hi:[0,1]
	v_pk_add_f32 v[8:9], v[10:11], v[8:9] op_sel:[0,1] op_sel_hi:[1,0] neg_lo:[0,1]
	v_pk_add_f32 v[10:11], v[12:13], v[4:5]
	v_pk_add_f32 v[4:5], v[12:13], v[4:5] neg_lo:[0,1] neg_hi:[0,1]
	v_pk_add_f32 v[12:13], v[0:1], v[2:3] op_sel:[0,1] op_sel_hi:[1,0]
	v_pk_add_f32 v[0:1], v[0:1], v[2:3] op_sel:[0,1] op_sel_hi:[1,0] neg_lo:[0,1] neg_hi:[0,1]
	v_lshlrev_b32_e32 v2, 4, v41
	v_and_or_b32 v2, v2, s7, v98
	v_ashrrev_i32_e32 v3, 4, v2
	v_lshlrev_b32_e32 v3, 3, v3
	v_lshlrev_b32_e32 v2, 3, v2
	v_add3_u32 v2, 0, v3, v2
	v_add_u32_e32 v3, 0x800, v2
	v_mov_b32_e32 v41, v32
	ds_write2_b64 v2, v[6:7], v[18:19] offset1:34
	ds_write2_b64 v3, v[14:15], v[20:21] offset0:16 offset1:50
	ds_write2_b64 v2, v[26:27], v[30:31] offset0:136 offset1:170
	ds_write2_b64 v3, v[24:25], v[8:9] offset0:152 offset1:186
	ds_write2_b64 v2, v[28:29], v[10:11] offset0:68 offset1:102
	ds_write2_b64 v3, v[22:23], v[4:5] offset0:84 offset1:118
	ds_write2_b64 v2, v[58:59], v[12:13] offset0:204 offset1:238
	ds_write2_b64 v3, v[16:17], v[0:1] offset0:220 offset1:254
	s_waitcnt lgkmcnt(0)
	s_barrier
	s_nop 0
	v_and_b32_e32 v98, 0x1ff, v41
	v_cvt_f32_u32_e32 v24, v98
	v_ashrrev_i32_e32 v0, 4, v41
	v_lshlrev_b32_e32 v0, 3, v0
	v_lshlrev_b32_e32 v1, 3, v41
	v_mul_f32_e32 v60, 0x39000000, v24
	v_sin_f32_e32 v24, v60
	v_cos_f32_e32 v60, v60
	v_add3_u32 v25, 0, v0, v1
	ds_read_b64 v[0:1], v25
	ds_read_b64 v[2:3], v25 offset:4352
	ds_read_b64 v[4:5], v25 offset:8704
	ds_read_b64 v[6:7], v25 offset:13056
	ds_read_b64 v[8:9], v25 offset:17408
	ds_read_b64 v[10:11], v25 offset:21760
	ds_read_b64 v[12:13], v25 offset:26112
	ds_read_b64 v[14:15], v25 offset:30464
	v_xor_b32_e32 v61, 0x80000000, v24
	s_waitcnt lgkmcnt(6)
	v_pk_mul_f32 v[94:95], v[2:3], v[24:25] op_sel:[1,0] op_sel_hi:[0,0] neg_hi:[0,1]
	v_pk_fma_f32 v[2:3], v[2:3], v[60:61], v[94:95] op_sel_hi:[1,0,1]
	v_pk_mul_f32 v[94:95], v[24:25], v[60:61] op_sel:[0,1] op_sel_hi:[0,0] neg_hi:[1,0]
	v_pk_fma_f32 v[94:95], v[60:61], v[60:61], v[94:95] op_sel_hi:[0,1,1]
	ds_read_b64 v[16:17], v25 offset:34816
	ds_read_b64 v[18:19], v25 offset:39168
	ds_read_b64 v[20:21], v25 offset:43520
	ds_read_b64 v[22:23], v25 offset:47872
	s_waitcnt lgkmcnt(9)
	v_pk_mul_f32 v[96:97], v[4:5], v[94:95] op_sel:[1,1] op_sel_hi:[0,1] neg_lo:[0,1]
	v_pk_fma_f32 v[4:5], v[4:5], v[94:95], v[96:97] op_sel_hi:[1,0,1]
	v_pk_mul_f32 v[96:97], v[24:25], v[94:95] op_sel:[0,1] op_sel_hi:[0,0] neg_hi:[1,0]
	v_pk_fma_f32 v[94:95], v[60:61], v[94:95], v[96:97] op_sel_hi:[0,1,1]
	ds_read_b64 v[26:27], v25 offset:52224
	ds_read_b64 v[28:29], v25 offset:56576
	ds_read_b64 v[30:31], v25 offset:60928
	ds_read_b64 v[58:59], v25 offset:65280
	s_waitcnt lgkmcnt(12)
	v_pk_mul_f32 v[96:97], v[6:7], v[94:95] op_sel:[1,1] op_sel_hi:[0,1] neg_lo:[0,1]
	v_pk_fma_f32 v[6:7], v[6:7], v[94:95], v[96:97] op_sel_hi:[1,0,1]
	v_pk_mul_f32 v[96:97], v[24:25], v[94:95] op_sel:[0,1] op_sel_hi:[0,0] neg_hi:[1,0]
	v_pk_fma_f32 v[94:95], v[60:61], v[94:95], v[96:97] op_sel_hi:[0,1,1]
	s_waitcnt lgkmcnt(0)
	v_pk_mul_f32 v[96:97], v[8:9], v[94:95] op_sel:[1,1] op_sel_hi:[0,1] neg_lo:[0,1]
	v_pk_fma_f32 v[8:9], v[8:9], v[94:95], v[96:97] op_sel_hi:[1,0,1]
	v_pk_mul_f32 v[96:97], v[24:25], v[94:95] op_sel:[0,1] op_sel_hi:[0,0] neg_hi:[1,0]
	v_pk_fma_f32 v[94:95], v[60:61], v[94:95], v[96:97] op_sel_hi:[0,1,1]
	s_barrier
	v_pk_mul_f32 v[96:97], v[10:11], v[94:95] op_sel:[1,1] op_sel_hi:[0,1] neg_lo:[0,1]
	v_pk_fma_f32 v[10:11], v[10:11], v[94:95], v[96:97] op_sel_hi:[1,0,1]
	v_pk_mul_f32 v[96:97], v[24:25], v[94:95] op_sel:[0,1] op_sel_hi:[0,0] neg_hi:[1,0]
	v_pk_fma_f32 v[94:95], v[60:61], v[94:95], v[96:97] op_sel_hi:[0,1,1]
	s_nop 0
	v_pk_mul_f32 v[96:97], v[12:13], v[94:95] op_sel:[1,1] op_sel_hi:[0,1] neg_lo:[0,1]
	v_pk_fma_f32 v[12:13], v[12:13], v[94:95], v[96:97] op_sel_hi:[1,0,1]
	v_pk_mul_f32 v[96:97], v[24:25], v[94:95] op_sel:[0,1] op_sel_hi:[0,0] neg_hi:[1,0]
	v_pk_fma_f32 v[94:95], v[60:61], v[94:95], v[96:97] op_sel_hi:[0,1,1]
	s_nop 0
	v_pk_mul_f32 v[96:97], v[14:15], v[94:95] op_sel:[1,1] op_sel_hi:[0,1] neg_lo:[0,1]
	v_pk_fma_f32 v[14:15], v[14:15], v[94:95], v[96:97] op_sel_hi:[1,0,1]
	v_pk_mul_f32 v[96:97], v[24:25], v[94:95] op_sel:[0,1] op_sel_hi:[0,0] neg_hi:[1,0]
	v_pk_fma_f32 v[94:95], v[60:61], v[94:95], v[96:97] op_sel_hi:[0,1,1]
	s_nop 0
	v_pk_mul_f32 v[96:97], v[16:17], v[94:95] op_sel:[1,1] op_sel_hi:[0,1] neg_lo:[0,1]
	v_pk_fma_f32 v[16:17], v[16:17], v[94:95], v[96:97] op_sel_hi:[1,0,1]
	v_pk_mul_f32 v[96:97], v[24:25], v[94:95] op_sel:[0,1] op_sel_hi:[0,0] neg_hi:[1,0]
	v_pk_fma_f32 v[94:95], v[60:61], v[94:95], v[96:97] op_sel_hi:[0,1,1]
	s_nop 0
	v_pk_mul_f32 v[96:97], v[18:19], v[94:95] op_sel:[1,1] op_sel_hi:[0,1] neg_lo:[0,1]
	v_pk_fma_f32 v[18:19], v[18:19], v[94:95], v[96:97] op_sel_hi:[1,0,1]
	v_pk_mul_f32 v[96:97], v[24:25], v[94:95] op_sel:[0,1] op_sel_hi:[0,0] neg_hi:[1,0]
	v_pk_fma_f32 v[94:95], v[60:61], v[94:95], v[96:97] op_sel_hi:[0,1,1]
	s_nop 0
	v_pk_mul_f32 v[96:97], v[20:21], v[94:95] op_sel:[1,1] op_sel_hi:[0,1] neg_lo:[0,1]
	v_pk_fma_f32 v[20:21], v[20:21], v[94:95], v[96:97] op_sel_hi:[1,0,1]
	v_pk_mul_f32 v[96:97], v[24:25], v[94:95] op_sel:[0,1] op_sel_hi:[0,0] neg_hi:[1,0]
	v_pk_fma_f32 v[94:95], v[60:61], v[94:95], v[96:97] op_sel_hi:[0,1,1]
	s_nop 0
	v_pk_mul_f32 v[96:97], v[22:23], v[94:95] op_sel:[1,1] op_sel_hi:[0,1] neg_lo:[0,1]
	v_pk_fma_f32 v[22:23], v[22:23], v[94:95], v[96:97] op_sel_hi:[1,0,1]
	v_pk_mul_f32 v[96:97], v[24:25], v[94:95] op_sel:[0,1] op_sel_hi:[0,0] neg_hi:[1,0]
	v_pk_fma_f32 v[94:95], v[60:61], v[94:95], v[96:97] op_sel_hi:[0,1,1]
	s_nop 0
	v_pk_mul_f32 v[96:97], v[26:27], v[94:95] op_sel:[1,1] op_sel_hi:[0,1] neg_lo:[0,1]
	v_pk_fma_f32 v[26:27], v[26:27], v[94:95], v[96:97] op_sel_hi:[1,0,1]
	v_pk_mul_f32 v[96:97], v[24:25], v[94:95] op_sel:[0,1] op_sel_hi:[0,0] neg_hi:[1,0]
	v_pk_fma_f32 v[94:95], v[60:61], v[94:95], v[96:97] op_sel_hi:[0,1,1]
	s_nop 0
	v_pk_mul_f32 v[96:97], v[28:29], v[94:95] op_sel:[1,1] op_sel_hi:[0,1] neg_lo:[0,1]
	v_pk_fma_f32 v[28:29], v[28:29], v[94:95], v[96:97] op_sel_hi:[1,0,1]
	v_pk_mul_f32 v[96:97], v[24:25], v[94:95] op_sel:[0,1] op_sel_hi:[0,0] neg_hi:[1,0]
	v_pk_fma_f32 v[94:95], v[60:61], v[94:95], v[96:97] op_sel_hi:[0,1,1]
	v_pk_mul_f32 v[24:25], v[24:25], v[94:95] op_sel:[0,1] op_sel_hi:[0,0] neg_hi:[1,0]
	v_pk_fma_f32 v[24:25], v[60:61], v[94:95], v[24:25] op_sel_hi:[0,1,1]
	v_pk_mul_f32 v[60:61], v[58:59], v[24:25] op_sel:[1,1] op_sel_hi:[0,1] neg_lo:[0,1]
	v_pk_fma_f32 v[24:25], v[58:59], v[24:25], v[60:61] op_sel_hi:[1,0,1]
	v_pk_add_f32 v[58:59], v[0:1], v[16:17]
	v_pk_add_f32 v[0:1], v[0:1], v[16:17] neg_lo:[0,1] neg_hi:[0,1]
	v_pk_add_f32 v[16:17], v[2:3], v[18:19]
	v_pk_add_f32 v[2:3], v[2:3], v[18:19] neg_lo:[0,1] neg_hi:[0,1]
	v_pk_mul_f32 v[96:97], v[30:31], v[94:95] op_sel:[1,1] op_sel_hi:[0,1] neg_lo:[0,1]
	v_pk_mul_f32 v[18:19], v[2:3], s[18:19]
	v_pk_fma_f32 v[30:31], v[30:31], v[94:95], v[96:97] op_sel_hi:[1,0,1]
	v_pk_fma_f32 v[2:3], v[2:3], s[30:31], v[18:19] op_sel:[0,0,1] op_sel_hi:[1,0,0]
	v_pk_add_f32 v[18:19], v[4:5], v[20:21]
	v_pk_add_f32 v[4:5], v[4:5], v[20:21] neg_lo:[0,1] neg_hi:[0,1]
	s_nop 0
	v_pk_mul_f32 v[20:21], v[4:5], s[10:11]
	s_nop 0
	v_pk_fma_f32 v[4:5], v[4:5], s[14:15], v[20:21] op_sel:[0,0,1] op_sel_hi:[1,0,0]
	v_pk_add_f32 v[20:21], v[6:7], v[22:23]
	v_pk_add_f32 v[6:7], v[6:7], v[22:23] neg_lo:[0,1] neg_hi:[0,1]
	s_nop 0
	v_pk_mul_f32 v[22:23], v[6:7], s[34:35]
	s_nop 0
	v_pk_fma_f32 v[6:7], v[6:7], s[26:27], v[22:23] op_sel:[0,0,1] op_sel_hi:[1,0,0]
	v_pk_add_f32 v[22:23], v[8:9], v[26:27]
	v_pk_add_f32 v[8:9], v[8:9], v[26:27] neg_lo:[0,1] neg_hi:[0,1]
	v_pk_add_f32 v[26:27], v[10:11], v[28:29]
	v_pk_add_f32 v[10:11], v[10:11], v[28:29] neg_lo:[0,1] neg_hi:[0,1]
	s_nop 0
	v_pk_mul_f32 v[28:29], v[10:11], s[34:35]
	s_nop 0
	v_pk_fma_f32 v[10:11], v[10:11], s[26:27], v[28:29] op_sel:[0,0,1] op_sel_hi:[1,0,0] neg_lo:[1,0,0] neg_hi:[1,0,0]
	v_pk_add_f32 v[28:29], v[12:13], v[30:31]
	v_pk_add_f32 v[12:13], v[12:13], v[30:31] neg_lo:[0,1] neg_hi:[0,1]
	s_nop 0
	v_pk_mul_f32 v[30:31], v[12:13], s[10:11]
	s_nop 0
	v_pk_fma_f32 v[12:13], v[12:13], s[14:15], v[30:31] op_sel:[0,0,1] op_sel_hi:[1,0,0] neg_lo:[1,0,0] neg_hi:[1,0,0]
	v_pk_add_f32 v[30:31], v[14:15], v[24:25]
	v_pk_add_f32 v[14:15], v[14:15], v[24:25] neg_lo:[0,1] neg_hi:[0,1]
	s_nop 0
	v_pk_mul_f32 v[24:25], v[14:15], s[18:19]
	s_nop 0
	v_pk_fma_f32 v[14:15], v[14:15], s[30:31], v[24:25] op_sel:[0,0,1] op_sel_hi:[1,0,0] neg_lo:[1,0,0] neg_hi:[1,0,0]
	v_pk_add_f32 v[24:25], v[58:59], v[22:23]
	v_pk_add_f32 v[22:23], v[58:59], v[22:23] neg_lo:[0,1] neg_hi:[0,1]
	v_pk_add_f32 v[58:59], v[16:17], v[26:27]
	v_pk_add_f32 v[16:17], v[16:17], v[26:27] neg_lo:[0,1] neg_hi:[0,1]
	s_nop 0
	v_pk_mul_f32 v[26:27], v[16:17], s[10:11]
	s_nop 0
	v_pk_fma_f32 v[16:17], v[16:17], s[14:15], v[26:27] op_sel:[0,0,1] op_sel_hi:[1,0,0]
	v_pk_add_f32 v[26:27], v[18:19], v[28:29]
	v_pk_add_f32 v[18:19], v[18:19], v[28:29] neg_lo:[0,1] neg_hi:[0,1]
	v_pk_add_f32 v[28:29], v[20:21], v[30:31]
	v_pk_add_f32 v[20:21], v[20:21], v[30:31] neg_lo:[0,1] neg_hi:[0,1]
	s_nop 0
	v_pk_mul_f32 v[30:31], v[20:21], s[10:11]
	s_nop 0
	v_pk_fma_f32 v[20:21], v[20:21], s[14:15], v[30:31] op_sel:[0,0,1] op_sel_hi:[1,0,0] neg_lo:[1,0,0] neg_hi:[1,0,0]
	v_pk_add_f32 v[30:31], v[0:1], v[8:9] op_sel:[0,1] op_sel_hi:[1,0] neg_hi:[0,1]
	v_pk_add_f32 v[0:1], v[0:1], v[8:9] op_sel:[0,1] op_sel_hi:[1,0] neg_lo:[0,1]
	v_pk_add_f32 v[8:9], v[2:3], v[10:11]
	v_pk_add_f32 v[2:3], v[2:3], v[10:11] neg_lo:[0,1] neg_hi:[0,1]
	s_nop 0
	v_pk_mul_f32 v[10:11], v[2:3], s[10:11]
	s_nop 0
	v_pk_fma_f32 v[2:3], v[2:3], s[14:15], v[10:11] op_sel:[0,0,1] op_sel_hi:[1,0,0]
	v_pk_add_f32 v[10:11], v[4:5], v[12:13]
	v_pk_add_f32 v[4:5], v[4:5], v[12:13] neg_lo:[0,1] neg_hi:[0,1]
	v_pk_add_f32 v[12:13], v[6:7], v[14:15]
	v_pk_add_f32 v[6:7], v[6:7], v[14:15] neg_lo:[0,1] neg_hi:[0,1]
	s_nop 0
	v_pk_mul_f32 v[14:15], v[6:7], s[10:11]
	s_nop 0
	v_pk_fma_f32 v[6:7], v[6:7], s[14:15], v[14:15] op_sel:[0,0,1] op_sel_hi:[1,0,0] neg_lo:[1,0,0] neg_hi:[1,0,0]
	v_pk_add_f32 v[14:15], v[24:25], v[26:27]
	v_pk_add_f32 v[24:25], v[24:25], v[26:27] neg_lo:[0,1] neg_hi:[0,1]
	v_pk_add_f32 v[26:27], v[58:59], v[28:29]
	v_pk_add_f32 v[28:29], v[58:59], v[28:29] neg_lo:[0,1] neg_hi:[0,1]
	v_pk_add_f32 v[58:59], v[22:23], v[18:19] op_sel:[0,1] op_sel_hi:[1,0] neg_hi:[0,1]
	v_pk_add_f32 v[18:19], v[22:23], v[18:19] op_sel:[0,1] op_sel_hi:[1,0] neg_lo:[0,1]
	v_pk_add_f32 v[22:23], v[16:17], v[20:21]
	v_pk_add_f32 v[16:17], v[16:17], v[20:21] neg_lo:[0,1] neg_hi:[0,1]
	v_pk_add_f32 v[20:21], v[30:31], v[10:11]
	v_pk_add_f32 v[10:11], v[30:31], v[10:11] neg_lo:[0,1] neg_hi:[0,1]
	v_pk_add_f32 v[30:31], v[8:9], v[12:13]
	v_pk_add_f32 v[8:9], v[8:9], v[12:13] neg_lo:[0,1] neg_hi:[0,1]
	v_pk_add_f32 v[12:13], v[0:1], v[4:5] op_sel:[0,1] op_sel_hi:[1,0] neg_hi:[0,1]
	v_pk_add_f32 v[0:1], v[0:1], v[4:5] op_sel:[0,1] op_sel_hi:[1,0] neg_lo:[0,1]
	v_pk_add_f32 v[4:5], v[2:3], v[6:7]
	v_pk_add_f32 v[2:3], v[2:3], v[6:7] neg_lo:[0,1] neg_hi:[0,1]
	s_nop 0
	v_pk_mul_f32 v[2:3], v[2:3], s[22:23]
	v_pk_add_f32 v[6:7], v[14:15], v[26:27]
	v_pk_add_f32 v[14:15], v[14:15], v[26:27] neg_lo:[0,1] neg_hi:[0,1]
	v_pk_add_f32 v[26:27], v[24:25], v[28:29] op_sel:[0,1] op_sel_hi:[1,0] neg_hi:[0,1]
	v_pk_add_f32 v[24:25], v[24:25], v[28:29] op_sel:[0,1] op_sel_hi:[1,0] neg_lo:[0,1]
	v_pk_add_f32 v[28:29], v[58:59], v[22:23]
	v_pk_add_f32 v[22:23], v[58:59], v[22:23] neg_lo:[0,1] neg_hi:[0,1]
	v_pk_add_f32 v[58:59], v[18:19], v[16:17] op_sel:[0,1] op_sel_hi:[1,0] neg_hi:[0,1]
	v_pk_add_f32 v[16:17], v[18:19], v[16:17] op_sel:[0,1] op_sel_hi:[1,0] neg_lo:[0,1]
	v_pk_add_f32 v[18:19], v[20:21], v[30:31]
	v_pk_add_f32 v[20:21], v[20:21], v[30:31] neg_lo:[0,1] neg_hi:[0,1]
	v_pk_add_f32 v[30:31], v[10:11], v[8:9] op_sel:[0,1] op_sel_hi:[1,0] neg_hi:[0,1]
	v_pk_add_f32 v[8:9], v[10:11], v[8:9] op_sel:[0,1] op_sel_hi:[1,0] neg_lo:[0,1]
	v_pk_add_f32 v[10:11], v[12:13], v[4:5]
	v_pk_add_f32 v[4:5], v[12:13], v[4:5] neg_lo:[0,1] neg_hi:[0,1]
	v_pk_add_f32 v[12:13], v[0:1], v[2:3] op_sel:[0,1] op_sel_hi:[1,0]
	v_pk_add_f32 v[0:1], v[0:1], v[2:3] op_sel:[0,1] op_sel_hi:[1,0] neg_lo:[0,1] neg_hi:[0,1]
	v_lshlrev_b32_e32 v2, 4, v41
	v_and_or_b32 v2, v2, s15, v98
	v_ashrrev_i32_e32 v3, 4, v2
	v_lshlrev_b32_e32 v3, 3, v3
	v_lshlrev_b32_e32 v2, 3, v2
	v_add3_u32 v2, 0, v3, v2
	ds_write_b64 v2, v[6:7]
	ds_write_b64 v2, v[14:15] offset:34816
	ds_write_b64 v2, v[26:27] offset:17408
	ds_write_b64 v2, v[24:25] offset:52224
	ds_write_b64 v2, v[28:29] offset:8704
	ds_write_b64 v2, v[22:23] offset:43520
	ds_write_b64 v2, v[58:59] offset:26112
	ds_write_b64 v2, v[16:17] offset:60928
	ds_write_b64 v2, v[18:19] offset:4352
	ds_write_b64 v2, v[20:21] offset:39168
	ds_write_b64 v2, v[30:31] offset:21760
	ds_write_b64 v2, v[8:9] offset:56576
	ds_write_b64 v2, v[10:11] offset:13056
	ds_write_b64 v2, v[4:5] offset:47872
	ds_write_b64 v2, v[12:13] offset:30464
	ds_write_b64 v2, v[0:1] offset:65280
	s_waitcnt lgkmcnt(0)
	s_barrier
	s_and_saveexec_b64 s[28:29], s[40:41]
	s_cbranch_execz .LBB0_602
	s_add_u32 s4, s38, 0x800000
	s_addc_u32 s5, s39, 0
	v_lshl_add_u64 v[0:1], v[48:49], 1, s[4:5]
	global_load_dwordx4 v[8:11], v[0:1], off offset:16
	global_load_dwordx4 v[12:15], v[0:1], off
	v_mov_b32_e32 v19, 0
	v_mov_b32_e32 v21, 0
	v_mov_b32_e32 v157, 0
	s_and_saveexec_b64 s[8:9], s[42:43]
	s_cbranch_execz .LBB0_678
	v_lshl_add_u64 v[2:3], v[172:173], 1, s[4:5]
	global_load_ushort v157, v[2:3], off offset:-2
.LBB0_678:
	s_or_b64 exec, exec, s[8:9]
	v_mov_b32_e32 v158, 0
	s_and_saveexec_b64 s[4:5], s[44:45]
	s_cbranch_execz .LBB0_680
	global_load_ushort v158, v[0:1], off offset:32
.LBB0_680:
	s_or_b64 exec, exec, s[4:5]
	s_add_u32 s4, s38, 0x1400000
	s_addc_u32 s5, s39, 0
	v_lshl_add_u64 v[16:17], v[48:49], 1, s[4:5]
	global_load_dwordx4 v[0:3], v[16:17], off offset:16
	global_load_dwordx4 v[4:7], v[16:17], off
	v_mov_b32_e32 v18, 0
	v_mov_b32_e32 v20, 0
	v_mov_b32_e32 v159, 0
	s_and_saveexec_b64 s[8:9], s[42:43]
	s_cbranch_execz .LBB0_682
	v_lshl_add_u64 v[22:23], v[172:173], 1, s[4:5]
	global_load_ushort v159, v[22:23], off offset:-2
.LBB0_682:
	s_or_b64 exec, exec, s[8:9]
	v_mov_b32_e32 v160, 0
	s_and_saveexec_b64 s[4:5], s[44:45]
	s_cbranch_execz .LBB0_601
	global_load_ushort v160, v[16:17], off offset:32
	s_branch .LBB0_601
